# attention K rows in LDS: 16-byte piece index XORed with ((row+4)>>3)&1 so the K-fragment ds_read_b128 groups are bank-conflict free
# baseline (speedup 1.0000x reference)
.LBB0_387:
	s_or_b64 exec, exec, s[2:3]
	s_abs_i32 s0, s84
	v_cvt_f32_u32_e32 v0, s0
	s_sub_i32 s3, 0, s0
	s_add_i32 s1, s84, 0x4ff
	s_xor_b32 s2, s1, s84
	v_rcp_iflag_f32_e32 v0, v0
	s_abs_i32 s1, s1
	s_ashr_i32 s2, s2, 31
	v_and_b32_e32 v146, 15, v164
	v_mul_f32_e32 v0, 0x4f7ffffe, v0
	v_cvt_u32_f32_e32 v0, v0
	s_mov_b32 s61, 0
	s_waitcnt lgkmcnt(0)
	s_barrier
	v_readfirstlane_b32 s4, v0
	s_mul_i32 s3, s3, s4
	s_mul_hi_u32 s3, s4, s3
	s_add_i32 s4, s4, s3
	s_mul_hi_u32 s3, s1, s4
	s_mul_i32 s4, s3, s0
	s_sub_i32 s1, s1, s4
	s_add_i32 s4, s3, 1
	s_sub_i32 s5, s1, s0
	s_cmp_ge_u32 s1, s0
	s_cselect_b32 s3, s4, s3
	s_cselect_b32 s1, s5, s1
	s_add_i32 s4, s3, 1
	s_cmp_ge_u32 s1, s0
	s_cselect_b32 s0, s4, s3
	s_xor_b32 s0, s0, s2
	s_sub_i32 s0, s0, s2
	s_mul_i32 s51, s0, s33
	s_min_i32 s0, s0, 3
	s_add_i32 s0, s51, s0
	s_min_i32 s53, s0, 0x500
	s_cmp_lt_i32 s51, s53
	s_cbranch_scc0 .LBB0_424
	v_lshrrev_b32_e32 v1, 2, v180
	v_and_b32_e32 v2, 12, v1
	v_add_u32_e32 v13, 26, v2
	v_add_u32_e32 v14, 24, v146
	v_sub_u32_e32 v15, v13, v14
	v_mov_b32_e32 v16, 0x400
	v_cmp_gt_u32_e32 vcc, 16, v15
	v_mov_b32_e32 v18, 0x800
	v_mov_b32_e32 v19, 0x200
	v_cndmask_b32_e32 v15, 0, v16, vcc
	v_add_u32_e32 v16, 27, v2
	v_sub_u32_e32 v17, v16, v14
	v_cmp_gt_u32_e64 s[0:1], 16, v17
	v_sub_u32_e64 v0, v146, 8 clamp
	v_or_b32_e32 v4, 1, v2
	v_cndmask_b32_e64 v17, 0, v18, s[0:1]
	v_add_u32_e32 v18, 25, v2
	v_sub_u32_e32 v14, v18, v14
	v_cmp_gt_u32_e64 s[4:5], 16, v14
	v_or_b32_e32 v6, 2, v2
	v_or_b32_e32 v8, 3, v1
	v_add_u32_e32 v9, 8, v146
	v_add_u32_e32 v11, 9, v2
	v_cndmask_b32_e64 v14, 0, v19, s[4:5]
	v_add_u32_e32 v19, 10, v2
	v_add_u32_e32 v21, 11, v2
	v_sub_u32_e32 v3, v2, v0
	v_sub_u32_e32 v5, v4, v0
	v_sub_u32_e32 v7, v6, v0
	v_sub_u32_e32 v0, v8, v0
	v_sub_u32_e32 v10, v2, v146
	v_sub_u32_e32 v12, v11, v9
	v_sub_u32_e32 v20, v19, v9
	v_sub_u32_e32 v9, v21, v9
	v_mov_b32_e32 v22, 0x80
	v_cmp_lt_u32_e64 s[8:9], 15, v9
	v_cmp_lt_u32_e64 s[14:15], 15, v0
	v_cmp_lt_u32_e64 s[16:17], 15, v10
	v_cmp_gt_u32_e64 s[2:3], 16, v10
	v_cmp_lt_u32_e64 s[6:7], 15, v20
	v_cndmask_b32_e64 v9, v22, 0, s[8:9]
	v_cmp_lt_u32_e64 s[10:11], 15, v5
	v_cndmask_b32_e64 v0, 8, 0, s[14:15]
	v_cndmask_b32_e64 v10, 16, 0, s[16:17]
	v_cndmask_b32_e64 v20, 64, 0, s[6:7]
	v_cndmask_b32_e64 v5, 2, 0, s[10:11]
	v_cmp_lt_u32_e64 s[12:13], 15, v7
	v_cmp_lt_u32_e64 s[18:19], 15, v12
	v_or3_b32 v0, v0, v10, v9
	v_or_b32_e32 v15, v15, v17
	v_mov_b32_e32 v17, 0x100
	v_cndmask_b32_e64 v7, 4, 0, s[12:13]
	v_cndmask_b32_e64 v12, 32, 0, s[18:19]
	v_or3_b32 v0, v5, v20, v0
	v_cndmask_b32_e64 v17, 0, v17, s[2:3]
	v_or3_b32 v0, v7, v12, v0
	v_or3_b32 v5, v17, v0, v14
	v_add_u32_e32 v0, 42, v2
	v_add_u32_e32 v12, 43, v2
	v_add_u32_e32 v17, 41, v2
	v_cndmask_b32_e32 v0, v0, v13, vcc
	v_or_b32_e32 v9, 32, v146
	v_cndmask_b32_e64 v12, v12, v16, s[0:1]
	v_cndmask_b32_e64 v17, v17, v18, s[4:5]
	v_sub_u32_e32 v0, v0, v9
	v_sub_u32_e32 v12, v12, v9
	v_sub_u32_e32 v17, v17, v9
	v_cndmask_b32_e64 v22, 40, 24, s[2:3]
	v_sub_u32_e32 v9, v2, v9
	v_mov_b32_e32 v20, 0x3c00
	v_add_u32_e32 v9, v9, v22
	v_mov_b32_e32 v10, 0x3c0000
	v_bfrev_b32_e32 v14, 60
	v_lshl_add_u32 v17, v17, 10, v20
	v_lshl_add_u32 v9, v9, 2, 60
	v_lshl_add_u32 v0, v0, 18, v10
	v_lshl_add_u32 v12, v12, 26, v14
	v_or_b32_e32 v139, v17, v9
	v_or3_b32 v140, v0, v12, v139
	v_cndmask_b32_e64 v0, v19, v13, s[6:7]
	v_or_b32_e32 v9, 16, v146
	v_cndmask_b32_e64 v12, v21, v16, s[8:9]
	v_cndmask_b32_e64 v11, v11, v18, s[18:19]
	v_sub_u32_e32 v0, v0, v9
	v_sub_u32_e32 v12, v12, v9
	v_sub_u32_e32 v11, v11, v9
	v_cndmask_b32_e64 v13, 8, 24, s[16:17]
	v_sub_u32_e32 v9, v2, v9
	v_add_u32_e32 v9, v9, v13
	v_lshl_add_u32 v11, v11, 10, v20
	v_lshl_add_u32 v9, v9, 2, 60
	v_lshl_add_u32 v0, v0, 18, v10
	v_lshl_add_u32 v12, v12, 26, v14
	v_or_b32_e32 v141, v11, v9
	v_or3_b32 v142, v0, v12, v141
	v_or_b32_e32 v0, 18, v2
	v_cndmask_b32_e64 v0, v6, v0, s[12:13]
	v_or_b32_e32 v6, 19, v1
	v_cndmask_b32_e64 v6, v8, v6, s[14:15]
	v_or_b32_e32 v8, 17, v2
	v_cndmask_b32_e64 v4, v4, v8, s[10:11]
	v_or_b32_e32 v8, 16, v2
	v_cmp_gt_u32_e64 s[20:21], 16, v3
	v_sub_u32_e32 v4, v4, v146
	v_sub_u32_e32 v0, v0, v146
	v_cndmask_b32_e64 v3, v8, v2, s[20:21]
	v_sub_u32_e32 v3, v3, v146
	v_sub_u32_e32 v6, v6, v146
	v_lshl_add_u32 v4, v4, 10, v20
	v_lshl_add_u32 v3, v3, 2, 60
	v_lshl_add_u32 v0, v0, 18, v10
	v_lshl_add_u32 v6, v6, 26, v14
	v_or_b32_e32 v4, v4, v3
	v_or3_b32 v143, v0, v6, v4
	v_or_b32_e32 v6, 48, v180
	v_add_u32_e32 v8, -8, v6
	v_or_b32_e32 v0, 35, v1
	v_min_u32_e32 v8, 48, v8
	v_sub_u32_e32 v9, v0, v8
	v_mov_b32_e32 v11, 0x8000
	v_cmp_gt_u32_e32 vcc, 16, v9
	v_mov_b32_e32 v16, 0x4000
	v_or_b32_e32 v1, 51, v1
	v_cndmask_b32_e32 v9, 0, v11, vcc
	v_or_b32_e32 v11, 34, v2
	v_sub_u32_e32 v12, v11, v8
	v_cmp_gt_u32_e64 s[0:1], 16, v12
	v_mov_b32_e32 v18, 0x2000
	v_cndmask_b32_e32 v0, v1, v0, vcc
	v_cndmask_b32_e64 v12, 0, v16, s[0:1]
	v_or_b32_e32 v16, 33, v2
	v_sub_u32_e32 v17, v16, v8
	v_cmp_gt_u32_e64 s[22:23], 16, v17
	v_or_b32_e32 v1, 50, v2
	v_cndmask_b32_e64 v1, v1, v11, s[0:1]
	v_cndmask_b32_e64 v17, 0, v18, s[22:23]
	v_or_b32_e32 v18, 32, v2
	v_sub_u32_e32 v8, v18, v8
	v_sub_u32_e32 v1, v1, v6
	v_cmp_gt_u32_e64 s[24:25], 16, v8
	v_lshl_add_u32 v1, v1, 18, v10
	v_or_b32_e32 v10, 49, v2
	v_or_b32_e32 v2, 48, v2
	v_cndmask_b32_e64 v10, v10, v16, s[22:23]
	v_cndmask_b32_e64 v2, v2, v18, s[24:25]
	v_sub_u32_e32 v10, v10, v6
	v_sub_u32_e32 v2, v2, v6
	v_sub_u32_e32 v0, v0, v6
	v_lshl_add_u32 v10, v10, 10, v20
	v_lshl_add_u32 v2, v2, 2, 60
	v_lshl_add_u32 v0, v0, 26, v14
	v_or_b32_e32 v144, v10, v2
	v_or3_b32 v145, v1, v0, v144
	v_and_b32_e32 v1, 7, v164
	v_mov_b32_e32 v19, 0x1000
	v_lshrrev_b32_e32 v147, 3, v164
	v_lshlrev_b32_e32 v114, 4, v1
	s_movk_i32 s0, 0x90
	s_movk_i32 s26, 0x400
	s_movk_i32 s27, 0x800
	v_cndmask_b32_e64 v8, 0, v19, s[24:25]
	v_lshlrev_b32_e32 v0, 3, v1
	v_lshrrev_b32_e32 v1, 4, v180
	v_mad_u32_u24 v10, v147, s0, v114
	s_add_u32 s0, s80, 0x11000000
	v_and_b32_e32 v112, 48, v180
	v_or_b32_e32 v7, v15, v5
	s_movk_i32 s29, 0x1000
	v_or_b32_e32 v8, v8, v17
	v_lshl_add_u32 v150, v1, 3, 0
	v_mul_u32_u24_e32 v151, 0x90, v6
	v_bitop3_b32 v6, v15, s26, v5 bitop3:0xc8
	v_bitop3_b32 v5, v15, s27, v5 bitop3:0xc8
	v_and_b32_e32 v152, 0xfc, v3
	v_and_b32_e32 v154, 0xfc, v2
	v_lshlrev_b32_e32 v2, 2, v1
	s_addc_u32 s1, s81, 0
	v_lshl_add_u32 v1, v13, 2, v112
	v_lshlrev_b32_e32 v3, 2, v146
	s_movk_i32 s28, 0x2000
	v_cmp_eq_u32_e64 s[24:25], 0, v5
	v_bitop3_b32 v5, v8, s29, v7 bitop3:0xc8
	s_add_u32 s62, s80, 0x50000
	v_sub_u32_e32 v1, v1, v3
	s_movk_i32 s30, 0x4000
	v_or_b32_e32 v17, v8, v7
	v_or_b32_e32 v9, v12, v9
	v_cmp_eq_u32_e64 s[26:27], 0, v5
	v_bitop3_b32 v5, v8, s28, v7 bitop3:0xc8
	s_addc_u32 s63, s81, 0
	v_add_u32_e32 v1, -4, v1
	s_mov_b32 s34, 0x8000
	v_cmp_eq_u32_e64 s[28:29], 0, v5
	v_bitop3_b32 v5, v9, s30, v17 bitop3:0xc8
	s_add_u32 s75, s80, 0x17000000
	v_and_b32_e32 v155, 0xfc, v1
	v_lshl_add_u32 v1, v22, 2, v112
	v_mov_b32_e32 v113, 0
	v_cmp_eq_u32_e64 s[30:31], 0, v5
	v_bitop3_b32 v5, v9, s34, v17 bitop3:0xc8
	s_addc_u32 s76, s81, 0
	v_sub_u32_e32 v1, v1, v3
	v_and_b32_e32 v11, 48, v164
	v_cmp_eq_u32_e64 s[34:35], 0, v5
	v_lshrrev_b32_e32 v153, 8, v4
	v_lshl_add_u64 v[4:5], s[80:81], 0, v[112:113]
	s_mov_b64 s[38:39], 0xc000000
	s_add_u32 s77, s80, 0x16000000
	v_add_u32_e32 v1, 0xffffffbc, v1
	v_add_u32_e32 v148, 0, v11
	v_mul_u32_u24_e32 v149, 0x90, v146
	v_cmp_eq_u32_e64 s[22:23], 0, v6
	v_cmp_gt_u32_e64 s[36:37], 16, v180
	v_lshl_add_u64 v[116:117], v[4:5], 0, s[38:39]
	s_addc_u32 s93, s81, 0
	v_mov_b32_e32 v115, v113
	v_and_b32_e32 v156, 0xfc, v1
	v_lshlrev_b32_e32 v112, 1, v0
	s_mov_b64 s[64:65], 0x100
	v_lshlrev_b32_e32 v118, 1, v2
	s_mov_b64 s[66:67], 0x39000000
	s_mov_b32 s94, 0x500000
	v_add_u32_e32 v157, 0, v10
	v_add_u32_e32 v226, 4, v147
	v_bfe_u32 v226, v226, 3, 1
	v_and_b32_e32 v227, 1, v164
	v_lshlrev_b32_e32 v227, 5, v227
	v_sub_u32_e32 v227, 16, v227
	v_mad_i32_i24 v225, v226, v227, v157
	v_add_u32_e32 v226, 4, v146
	v_bfe_u32 v226, v226, 3, 1
	v_lshlrev_b32_e32 v226, 4, v226
	v_xor_b32_e32 v148, v148, v226
	v_xor_b32_e32 v228, 16, v148
	s_branch .LBB0_390

.LBB0_399:
	s_add_i32 s97, s38, s92
	s_lshl_b32 s38, s97, 6
	s_add_i32 s38, s38, s39
	v_add_u32_e32 v128, s38, v146
	s_lshl_b32 s38, s71, 1
	s_mov_b32 s39, s61
	v_ashrrev_i32_e32 v129, 31, v128
	v_lshl_add_u64 v[0:1], v[116:117], 0, s[38:39]
	v_lshlrev_b64 v[2:3], 10, v[128:129]
	v_add_u32_e32 v126, 16, v128
	v_lshl_add_u64 v[2:3], v[0:1], 0, v[2:3]
	v_ashrrev_i32_e32 v127, 31, v126
	global_load_dwordx4 v[80:83], v[2:3], off
	global_load_dwordx4 v[84:87], v[2:3], off offset:64
	v_lshlrev_b64 v[2:3], 10, v[126:127]
	v_add_u32_e32 v122, 32, v128
	v_lshl_add_u64 v[2:3], v[0:1], 0, v[2:3]
	v_ashrrev_i32_e32 v123, 31, v122
	global_load_dwordx4 v[88:91], v[2:3], off
	global_load_dwordx4 v[92:95], v[2:3], off offset:64
	v_lshlrev_b64 v[2:3], 10, v[122:123]
	v_add_u32_e32 v120, 48, v128
	v_lshl_add_u64 v[2:3], v[0:1], 0, v[2:3]
	v_ashrrev_i32_e32 v121, 31, v120
	global_load_dwordx4 v[96:99], v[2:3], off
	global_load_dwordx4 v[100:103], v[2:3], off offset:64
	v_lshlrev_b64 v[2:3], 10, v[120:121]
	v_lshl_add_u64 v[0:1], v[0:1], 0, v[2:3]
	global_load_dwordx4 v[104:107], v[0:1], off
	global_load_dwordx4 v[108:111], v[0:1], off offset:64
	v_mov_b32_e32 v131, 0
	s_andn2_b64 vcc, exec, s[72:73]
	v_mov_b32_e32 v130, 0
	v_mov_b32_e32 v125, 0
	v_mov_b32_e32 v124, 0
	v_mov_b32_e32 v63, 0
	v_mov_b32_e32 v62, 0
	v_mov_b32_e32 v61, 0
	v_mov_b32_e32 v60, 0
	v_mov_b32_e32 v59, 0
	v_mov_b32_e32 v58, 0
	v_mov_b32_e32 v57, 0
	v_mov_b32_e32 v56, 0
	v_mov_b32_e32 v55, 0
	v_mov_b32_e32 v54, 0
	v_mov_b32_e32 v53, 0
	v_mov_b32_e32 v52, 0
	v_mov_b32_e32 v51, 0
	v_mov_b32_e32 v50, 0
	v_mov_b32_e32 v49, 0
	v_mov_b32_e32 v48, 0
	v_mov_b32_e32 v47, 0
	v_mov_b32_e32 v46, 0
	v_mov_b32_e32 v45, 0
	v_mov_b32_e32 v44, 0
	v_mov_b32_e32 v43, 0
	v_mov_b32_e32 v42, 0
	v_mov_b32_e32 v41, 0
	v_mov_b32_e32 v40, 0
	v_mov_b32_e32 v39, 0
	v_mov_b32_e32 v38, 0
	v_mov_b32_e32 v37, 0
	v_mov_b32_e32 v36, 0
	v_mov_b32_e32 v35, 0
	v_mov_b32_e32 v34, 0
	v_mov_b32_e32 v33, 0
	v_mov_b32_e32 v32, 0
	v_mov_b32_e32 v31, 0
	v_mov_b32_e32 v30, 0
	v_mov_b32_e32 v29, 0
	v_mov_b32_e32 v28, 0
	v_mov_b32_e32 v27, 0
	v_mov_b32_e32 v26, 0
	v_mov_b32_e32 v25, 0
	v_mov_b32_e32 v24, 0
	v_mov_b32_e32 v23, 0
	v_mov_b32_e32 v22, 0
	v_mov_b32_e32 v21, 0
	v_mov_b32_e32 v20, 0
	v_mov_b32_e32 v19, 0
	v_mov_b32_e32 v18, 0
	v_mov_b32_e32 v17, 0
	v_mov_b32_e32 v16, 0
	v_mov_b32_e32 v15, 0
	v_mov_b32_e32 v14, 0
	v_mov_b32_e32 v13, 0
	v_mov_b32_e32 v12, 0
	v_mov_b32_e32 v11, 0
	v_mov_b32_e32 v10, 0
	v_mov_b32_e32 v9, 0
	v_mov_b32_e32 v8, 0
	v_mov_b32_e32 v7, 0
	v_mov_b32_e32 v6, 0
	v_mov_b32_e32 v5, 0
	v_mov_b32_e32 v4, 0
	v_mov_b32_e32 v3, 0
	v_mov_b32_e32 v2, 0
	v_mov_b32_e32 v1, 0
	v_mov_b32_e32 v0, 0
	s_waitcnt vmcnt(9)
	ds_write_b128 v225, v[64:67]
	s_waitcnt vmcnt(8)
	ds_write_b128 v157, v[68:71] offset:9216
	s_waitcnt lgkmcnt(0)
	s_barrier
	s_cbranch_vccnz .LBB0_416
	s_max_i32 s38, s97, 4
	s_add_i32 s38, s38, -4
	s_min_u32 s38, s38, s70
	s_mov_b32 s71, s61
	v_mov_b32_e32 v133, v113
	s_add_i32 s39, s38, 8
	v_mov_b32_e32 v0, s70
	v_cmp_lt_u64_e32 vcc, s[70:71], v[132:133]
	s_add_u32 s70, s80, s60
	v_mov_b32_e32 v1, v113
	v_cndmask_b32_e32 v2, v132, v0, vcc
	v_lshlrev_b32_e32 v0, 16, v2
	s_addc_u32 s71, s81, 0
	v_lshl_add_u64 v[0:1], s[70:71], 0, v[0:1]
	v_lshl_add_u64 v[132:133], v[0:1], 0, v[134:135]
	v_lshlrev_b32_e32 v0, 7, v2
	v_mov_b32_e32 v1, v113
	s_mul_i32 s72, s95, 0x780
	v_lshlrev_b32_e32 v2, 1, v136
	v_mov_b32_e32 v3, v113
	v_lshl_add_u64 v[0:1], s[68:69], 0, v[0:1]
	s_lshl_b32 s68, s89, 7
	v_lshl_add_u64 v[134:135], v[0:1], 0, v[2:3]
	s_add_i32 s72, s72, s68
	s_lshl_b32 s68, s97, 7
	v_mov_b32_e32 v2, v113
	s_sub_i32 s68, s72, s68
	v_mov_b32_e32 v124, v113
	v_mov_b32_e32 v125, v113
	v_mov_b32_e32 v0, v113
	v_mov_b32_e32 v1, v113
	v_mov_b64_e32 v[6:7], v[2:3]
	v_mov_b64_e32 v[10:11], v[2:3]
	v_mov_b64_e32 v[14:15], v[2:3]
	v_mov_b64_e32 v[18:19], v[2:3]
	v_mov_b64_e32 v[22:23], v[2:3]
	v_mov_b64_e32 v[26:27], v[2:3]
	v_mov_b64_e32 v[30:31], v[2:3]
	v_mov_b64_e32 v[34:35], v[2:3]
	v_mov_b64_e32 v[38:39], v[2:3]
	v_mov_b64_e32 v[42:43], v[2:3]
	v_mov_b64_e32 v[46:47], v[2:3]
	v_mov_b64_e32 v[50:51], v[2:3]
	v_mov_b64_e32 v[54:55], v[2:3]
	v_mov_b64_e32 v[58:59], v[2:3]
	v_mov_b64_e32 v[62:63], v[2:3]
	s_add_i32 s60, s89, 3
	s_add_i32 s70, s68, 0
	v_mov_b64_e32 v[4:5], v[0:1]
	v_mov_b64_e32 v[8:9], v[0:1]
	v_mov_b64_e32 v[12:13], v[0:1]
	v_mov_b64_e32 v[16:17], v[0:1]
	v_mov_b64_e32 v[20:21], v[0:1]
	v_mov_b64_e32 v[24:25], v[0:1]
	v_mov_b64_e32 v[28:29], v[0:1]
	v_mov_b64_e32 v[32:33], v[0:1]
	v_mov_b64_e32 v[36:37], v[0:1]
	v_mov_b64_e32 v[40:41], v[0:1]
	v_mov_b64_e32 v[44:45], v[0:1]
	v_mov_b64_e32 v[48:49], v[0:1]
	v_mov_b64_e32 v[52:53], v[0:1]
	v_mov_b64_e32 v[56:57], v[0:1]
	v_mov_b64_e32 v[60:61], v[0:1]
	v_mov_b64_e32 v[130:131], v[124:125]
	s_branch .LBB0_403

.LBB0_405:
	s_add_i32 s72, s60, -3
	s_cmp_ge_u32 s72, s38
	s_cselect_b64 s[68:69], -1, 0
	s_cmp_lt_u32 s72, s39
	s_cselect_b64 vcc, -1, 0
	s_and_b64 s[68:69], s[68:69], vcc
	s_andn2_b64 vcc, exec, s[68:69]
	s_cbranch_vccnz .LBB0_407
	v_add_u32_e32 v178, v150, v149
	v_add_u32_e32 v181, 0x2000, v178
	v_add_u32_e32 v218, 0x2800, v178
	v_add_u32_e32 v219, 0x3000, v178
	v_add_u32_e32 v178, v150, v151
	v_add_u32_e32 v119, v148, v149
	v_add_u32_e32 v229, v228, v149
	v_add_u32_e32 v136, s70, v152
	v_add_u32_sdwa v163, s70, v143 dst_sel:DWORD dst_unused:UNUSED_PAD src0_sel:DWORD src1_sel:BYTE_2
	v_add_u32_sdwa v165, s70, v143 dst_sel:DWORD dst_unused:UNUSED_PAD src0_sel:DWORD src1_sel:BYTE_3
	v_add_u32_e32 v220, 0x2000, v178
	v_add_u32_sdwa v179, s70, v141 dst_sel:DWORD dst_unused:UNUSED_PAD src0_sel:DWORD src1_sel:BYTE_1
	ds_read_b128 v[158:161], v119
	ds_read_b128 v[166:169], v119 offset:64
	ds_read_b128 v[170:173], v119 offset:2304
	ds_read_b128 v[174:177], v119 offset:2368
	v_add_u32_e32 v162, s70, v153
	ds_read_b64 v[182:183], v181 offset:1024
	ds_read_b64 v[184:185], v181 offset:1056
	ds_read_b64 v[186:187], v218 offset:1280
	ds_read_b64 v[188:189], v218 offset:1312
	ds_read_b64 v[190:191], v219 offset:1536
	ds_read_b64 v[192:193], v219 offset:1568
	ds_read_b64 v[194:195], v220 offset:1024
	ds_read_b64 v[196:197], v220 offset:1056
	ds_read_b128 v[198:201], v229 offset:1152
	ds_read_b128 v[202:205], v229 offset:1216
	ds_read_b128 v[206:209], v229 offset:3456
	ds_read_b128 v[210:213], v229 offset:3520
	v_add_u32_e32 v178, s70, v155
	v_add_u32_sdwa v214, s70, v142 dst_sel:DWORD dst_unused:UNUSED_PAD src0_sel:DWORD src1_sel:BYTE_2
	v_add_u32_sdwa v215, s70, v142 dst_sel:DWORD dst_unused:UNUSED_PAD src0_sel:DWORD src1_sel:BYTE_3
	ds_read_b32 v136, v136 offset:41856
	ds_read_b32 v216, v162 offset:41856
	ds_read_b32 v163, v163 offset:41856
	ds_read_b32 v165, v165 offset:41856
	ds_read_b32 v217, v178 offset:41856
	ds_read_b32 v179, v179 offset:41856
	ds_read_b32 v221, v214 offset:41856
	ds_read_b32 v222, v215 offset:41856
	s_setprio 1
	s_waitcnt vmcnt(7) lgkmcnt(15)
	v_mfma_f32_16x16x32_bf16 v[158:161], v[158:161], v[80:83], 0
	s_waitcnt vmcnt(6)
	v_mfma_f32_16x16x32_bf16 v[158:161], v[166:169], v[84:87], v[158:161]
	v_mfma_f32_16x16x32_bf16 v[166:169], v[170:173], v[80:83], 0
	v_mfma_f32_16x16x32_bf16 v[166:169], v[174:177], v[84:87], v[166:169]
	s_setprio 0
	s_nop 6
	v_cndmask_b32_e64 v158, v166, v158, s[20:21]
	s_waitcnt lgkmcnt(7)
	v_add_f32_e32 v136, v136, v158
	v_exp_f32_e32 v162, v136
	v_cndmask_b32_e64 v136, v159, v167, s[10:11]
	v_cndmask_b32_e64 v159, v160, v168, s[12:13]
	s_waitcnt lgkmcnt(5)
	v_add_f32_e32 v159, v163, v159
	v_add_f32_e32 v136, v216, v136
	v_exp_f32_e32 v214, v159
	v_cndmask_b32_e64 v159, v161, v169, s[14:15]
	v_exp_f32_e32 v178, v136
	s_waitcnt lgkmcnt(4)
	v_add_f32_e32 v159, v165, v159
	v_exp_f32_e32 v216, v159
	v_cndmask_b32_e64 v159, v214, 0, s[12:13]
	v_cndmask_b32_e64 v158, v178, 0, s[10:11]
	v_cndmask_b32_e64 v160, 0, v178, s[10:11]
	v_cndmask_b32_e64 v161, 0, v214, s[12:13]
	v_cndmask_b32_e64 v136, 0, v162, s[20:21]
	v_cndmask_b32_e64 v166, v162, 0, s[20:21]
	v_cndmask_b32_e64 v163, v216, 0, s[14:15]
	v_cndmask_b32_e64 v165, 0, v216, s[14:15]
	v_cvt_pk_bf16_f32 v158, v136, v158
	v_cvt_pk_bf16_f32 v159, v159, v163
	v_cvt_pk_bf16_f32 v160, v166, v160
	v_cvt_pk_bf16_f32 v161, v161, v165
	s_setprio 1
	v_mfma_f32_16x16x32_bf16 v[60:63], v[182:185], v[158:161], v[60:63]
	v_mfma_f32_16x16x32_bf16 v[56:59], v[186:189], v[158:161], v[56:59]
	v_mfma_f32_16x16x32_bf16 v[52:55], v[190:193], v[158:161], v[52:55]
	v_mfma_f32_16x16x32_bf16 v[48:51], v[194:197], v[158:161], v[48:51]
	s_setprio 0
	ds_read_b64 v[158:159], v181 offset:1040
	ds_read_b64 v[160:161], v181 offset:1072
	ds_read_b64 v[166:167], v218 offset:1296
	ds_read_b64 v[168:169], v218 offset:1328
	ds_read_b64 v[170:171], v219 offset:1552
	ds_read_b64 v[172:173], v219 offset:1584
	ds_read_b64 v[174:175], v220 offset:1040
	ds_read_b64 v[176:177], v220 offset:1072
	ds_read_b128 v[182:185], v229 offset:3456
	ds_read_b128 v[186:189], v229 offset:3520
	ds_read_b128 v[190:193], v229 offset:5760
	ds_read_b128 v[194:197], v229 offset:5824
	v_add_u32_e32 v136, s70, v156
	v_add_u32_sdwa v165, s70, v140 dst_sel:DWORD dst_unused:UNUSED_PAD src0_sel:DWORD src1_sel:BYTE_2
	v_add_u32_sdwa v163, s70, v139 dst_sel:DWORD dst_unused:UNUSED_PAD src0_sel:DWORD src1_sel:BYTE_1
	v_add_u32_sdwa v215, s70, v140 dst_sel:DWORD dst_unused:UNUSED_PAD src0_sel:DWORD src1_sel:BYTE_3
	ds_read_b32 v136, v136 offset:41856
	ds_read_b32 v223, v163 offset:41856
	ds_read_b32 v165, v165 offset:41856
	ds_read_b32 v224, v215 offset:41856
	s_setprio 1
	s_waitcnt vmcnt(5)
	v_mfma_f32_16x16x32_bf16 v[198:201], v[198:201], v[88:91], 0
	s_waitcnt vmcnt(4)
	v_mfma_f32_16x16x32_bf16 v[198:201], v[202:205], v[92:95], v[198:201]
	v_mfma_f32_16x16x32_bf16 v[202:205], v[206:209], v[88:91], 0
	v_mfma_f32_16x16x32_bf16 v[202:205], v[210:213], v[92:95], v[202:205]
	s_setprio 0
	s_nop 6
	v_cndmask_b32_e64 v163, v198, v202, s[16:17]
	s_waitcnt lgkmcnt(15)
	v_add_f32_e32 v163, v217, v163
	v_cndmask_b32_e64 v198, v199, v203, s[18:19]
	v_cndmask_b32_e64 v200, v200, v204, s[6:7]
	v_exp_f32_e32 v163, v163
	v_add_f32_e32 v179, v179, v198
	s_waitcnt lgkmcnt(15)
	v_add_f32_e32 v200, v221, v200
	v_exp_f32_e32 v179, v179
	v_exp_f32_e32 v215, v200
	v_cndmask_b32_e64 v200, v201, v205, s[8:9]
	s_waitcnt lgkmcnt(15)
	v_add_f32_e32 v200, v222, v200
	v_exp_f32_e32 v217, v200
	v_cndmask_b32_e64 v198, v163, 0, s[16:17]
	v_cndmask_b32_e64 v202, 0, v163, s[16:17]
	v_pk_add_f32 v[162:163], v[162:163], 0 op_sel_hi:[1,0]
	v_cndmask_b32_e64 v199, v179, 0, s[18:19]
	v_pk_add_f32 v[162:163], v[178:179], v[162:163]
	v_cndmask_b32_e64 v200, 0, v179, s[18:19]
	v_pk_add_f32 v[162:163], v[214:215], v[162:163]
	v_cndmask_b32_e64 v201, v215, 0, s[6:7]
	v_pk_add_f32 v[162:163], v[216:217], v[162:163]
	v_cndmask_b32_e64 v203, 0, v215, s[6:7]
	v_pk_add_f32 v[130:131], v[130:131], v[162:163]
	v_cndmask_b32_e64 v204, v217, 0, s[8:9]
	v_cndmask_b32_e64 v205, 0, v217, s[8:9]
	v_cvt_pk_bf16_f32 v198, v198, v199
	v_cvt_pk_bf16_f32 v199, v201, v204
	v_cvt_pk_bf16_f32 v200, v202, v200
	v_cvt_pk_bf16_f32 v201, v203, v205
	s_setprio 1
	s_waitcnt lgkmcnt(14)
	v_mfma_f32_16x16x32_bf16 v[44:47], v[158:161], v[198:201], v[44:47]
	s_waitcnt lgkmcnt(12)
	v_mfma_f32_16x16x32_bf16 v[40:43], v[166:169], v[198:201], v[40:43]
	s_waitcnt lgkmcnt(10)
	v_mfma_f32_16x16x32_bf16 v[36:39], v[170:173], v[198:201], v[36:39]
	s_waitcnt lgkmcnt(8)
	v_mfma_f32_16x16x32_bf16 v[32:35], v[174:177], v[198:201], v[32:35]
	s_setprio 0
	ds_read_b64 v[158:159], v181 offset:1072
	ds_read_b64 v[160:161], v181 offset:1104
	ds_read_b64 v[166:167], v218 offset:1328
	ds_read_b64 v[168:169], v218 offset:1360
	ds_read_b64 v[170:171], v219 offset:1584
	ds_read_b64 v[172:173], v219 offset:1616
	ds_read_b64 v[174:175], v220 offset:1072
	ds_read_b64 v[176:177], v220 offset:1104
	ds_read_b128 v[198:201], v119 offset:4608
	ds_read_b128 v[202:205], v119 offset:4672
	v_add_u32_e32 v119, v148, v151
	ds_read_b128 v[206:209], v119
	ds_read_b128 v[210:213], v119 offset:64
	v_add_u32_e32 v119, s70, v154
	v_add_u32_sdwa v162, s70, v144 dst_sel:DWORD dst_unused:UNUSED_PAD src0_sel:DWORD src1_sel:BYTE_1
	v_add_u32_sdwa v163, s70, v145 dst_sel:DWORD dst_unused:UNUSED_PAD src0_sel:DWORD src1_sel:BYTE_2
	v_add_u32_sdwa v178, s70, v145 dst_sel:DWORD dst_unused:UNUSED_PAD src0_sel:DWORD src1_sel:BYTE_3
	ds_read_b32 v119, v119 offset:41856
	ds_read_b32 v179, v162 offset:41856
	ds_read_b32 v214, v163 offset:41856
	ds_read_b32 v215, v178 offset:41856
	s_setprio 1
	s_waitcnt vmcnt(3) lgkmcnt(15)
	v_mfma_f32_16x16x32_bf16 v[182:185], v[182:185], v[96:99], 0
	s_waitcnt vmcnt(2)
	v_mfma_f32_16x16x32_bf16 v[182:185], v[186:189], v[100:103], v[182:185]
	v_mfma_f32_16x16x32_bf16 v[186:189], v[190:193], v[96:99], 0
	v_mfma_f32_16x16x32_bf16 v[186:189], v[194:197], v[100:103], v[186:189]
	s_setprio 0
	s_nop 6
	v_cndmask_b32_e64 v162, v186, v182, s[2:3]
	v_add_f32_e32 v136, v136, v162
	v_exp_f32_e32 v162, v136
	v_cndmask_b32_e64 v136, v187, v183, s[4:5]
	v_cndmask_b32_e64 v183, v184, v188, s[22:23]
	s_waitcnt lgkmcnt(15)
	v_add_f32_e32 v165, v165, v183
	v_exp_f32_e32 v190, v165
	v_cndmask_b32_e64 v165, v185, v189, s[24:25]
	v_add_f32_e32 v136, v223, v136
	s_waitcnt lgkmcnt(15)
	v_add_f32_e32 v165, v224, v165
	v_exp_f32_e32 v178, v136
	v_exp_f32_e32 v192, v165
	v_cndmask_b32_e64 v183, v190, 0, s[22:23]
	v_cndmask_b32_e64 v185, 0, v190, s[22:23]
	v_cndmask_b32_e64 v182, 0, v178, s[4:5]
	v_cndmask_b32_e64 v184, v192, 0, s[24:25]
	v_cndmask_b32_e64 v136, 0, v162, s[2:3]
	v_cndmask_b32_e64 v163, v162, 0, s[2:3]
	v_cndmask_b32_e64 v165, v178, 0, s[4:5]
	v_cndmask_b32_e64 v186, 0, v192, s[24:25]
	v_cvt_pk_bf16_f32 v182, v136, v182
	v_cvt_pk_bf16_f32 v183, v183, v184
	v_cvt_pk_bf16_f32 v184, v163, v165
	v_cvt_pk_bf16_f32 v185, v185, v186
	s_setprio 1
	s_waitcnt lgkmcnt(14)
	v_mfma_f32_16x16x32_bf16 v[28:31], v[158:161], v[182:185], v[28:31]
	s_waitcnt lgkmcnt(12)
	v_mfma_f32_16x16x32_bf16 v[24:27], v[166:169], v[182:185], v[24:27]
	s_waitcnt lgkmcnt(10)
	v_mfma_f32_16x16x32_bf16 v[20:23], v[170:173], v[182:185], v[20:23]
	s_waitcnt lgkmcnt(8)
	v_mfma_f32_16x16x32_bf16 v[16:19], v[174:177], v[182:185], v[16:19]
	s_setprio 0
	ds_read_b64 v[158:159], v220 offset:1088
	ds_read_b64 v[160:161], v220 offset:1120
	ds_read_b64 v[166:167], v219 offset:1600
	ds_read_b64 v[168:169], v219 offset:1632
	ds_read_b64 v[170:171], v218 offset:1344
	ds_read_b64 v[172:173], v218 offset:1376
	ds_read_b64 v[174:175], v181 offset:1088
	ds_read_b64 v[176:177], v181 offset:1120
	s_setprio 1
	s_waitcnt vmcnt(1) lgkmcnt(15)
	v_mfma_f32_16x16x32_bf16 v[182:185], v[198:201], v[104:107], 0
	s_waitcnt lgkmcnt(13)
	v_mfma_f32_16x16x32_bf16 v[186:189], v[206:209], v[104:107], 0
	s_waitcnt vmcnt(0)
	v_mfma_f32_16x16x32_bf16 v[182:185], v[202:205], v[108:111], v[182:185]
	s_waitcnt lgkmcnt(12)
	v_mfma_f32_16x16x32_bf16 v[186:189], v[210:213], v[108:111], v[186:189]
	s_setprio 0
	s_nop 6
	v_cndmask_b32_e64 v136, v182, v186, s[26:27]
	s_waitcnt lgkmcnt(11)
	v_add_f32_e32 v119, v119, v136
	v_exp_f32_e32 v163, v119
	v_cndmask_b32_e64 v119, v183, v187, s[28:29]
	v_cndmask_b32_e64 v181, v184, v188, s[30:31]
	s_waitcnt lgkmcnt(10)
	v_add_f32_e32 v119, v179, v119
	s_waitcnt lgkmcnt(9)
	v_add_f32_e32 v181, v214, v181
	v_exp_f32_e32 v179, v119
	v_exp_f32_e32 v191, v181
	v_cndmask_b32_e64 v181, v185, v189, s[34:35]
	s_waitcnt lgkmcnt(8)
	v_add_f32_e32 v181, v215, v181
	v_exp_f32_e32 v193, v181
	v_cndmask_b32_e64 v119, v163, 0, s[26:27]
	v_cndmask_b32_e64 v136, 0, v163, s[26:27]
	v_pk_add_f32 v[162:163], v[162:163], 0 op_sel_hi:[1,0]
	v_cndmask_b32_e64 v183, v191, 0, s[30:31]
	v_pk_add_f32 v[162:163], v[178:179], v[162:163]
	v_cndmask_b32_e64 v185, 0, v191, s[30:31]
	v_pk_add_f32 v[162:163], v[190:191], v[162:163]
	v_cndmask_b32_e64 v184, v193, 0, s[34:35]
	v_pk_add_f32 v[162:163], v[192:193], v[162:163]
	v_cndmask_b32_e64 v165, v179, 0, s[28:29]
	v_pk_add_f32 v[124:125], v[124:125], v[162:163]
	v_cndmask_b32_e64 v181, 0, v179, s[28:29]
	v_cndmask_b32_e64 v186, 0, v193, s[34:35]
	v_cvt_pk_bf16_f32 v182, v119, v165
	v_cvt_pk_bf16_f32 v183, v183, v184
	v_cvt_pk_bf16_f32 v184, v136, v181
	v_cvt_pk_bf16_f32 v185, v185, v186
	s_setprio 1
	s_waitcnt lgkmcnt(0)
	v_mfma_f32_16x16x32_bf16 v[12:15], v[174:177], v[182:185], v[12:15]
	v_mfma_f32_16x16x32_bf16 v[8:11], v[170:173], v[182:185], v[8:11]
	v_mfma_f32_16x16x32_bf16 v[4:7], v[166:169], v[182:185], v[4:7]
	v_mfma_f32_16x16x32_bf16 v[0:3], v[158:161], v[182:185], v[0:3]
	s_setprio 0
.LBB0_407:
	s_cmp_lt_u32 s72, s96
	s_cselect_b64 s[68:69], -1, 0
	s_cmp_ge_u32 s72, s96
	s_cbranch_scc1 .LBB0_409
	s_waitcnt vmcnt(1)
	ds_write_b128 v225, v[72:75] offset:18432
	s_waitcnt vmcnt(0)
	ds_write_b128 v157, v[76:79] offset:27648

.LBB0_412:
	s_add_i32 s68, s60, -2
	s_cmp_ge_u32 s68, s38
	s_cselect_b64 s[72:73], -1, 0
	s_cmp_lt_u32 s68, s39
	s_cselect_b64 vcc, -1, 0
	s_and_b64 s[72:73], s[72:73], vcc
	s_andn2_b64 vcc, exec, s[72:73]
	s_cbranch_vccnz .LBB0_414
	v_add_u32_e32 v178, v150, v149
	v_add_u32_e32 v181, 0x6800, v178
	v_add_u32_e32 v218, 0x7000, v178
	v_add_u32_e32 v219, 0x7800, v178
	v_add_u32_e32 v178, v150, v151
	v_add_u32_e32 v119, v148, v149
	v_add_u32_e32 v229, v228, v149
	v_add_u32_e32 v136, s70, v152
	v_add_u32_sdwa v163, s70, v143 dst_sel:DWORD dst_unused:UNUSED_PAD src0_sel:DWORD src1_sel:BYTE_2
	v_add_u32_sdwa v165, s70, v143 dst_sel:DWORD dst_unused:UNUSED_PAD src0_sel:DWORD src1_sel:BYTE_3
	v_add_u32_e32 v220, 0x6800, v178
	v_add_u32_sdwa v179, s70, v141 dst_sel:DWORD dst_unused:UNUSED_PAD src0_sel:DWORD src1_sel:BYTE_1
	ds_read_b128 v[158:161], v119 offset:18432
	ds_read_b128 v[166:169], v119 offset:18496
	ds_read_b128 v[170:173], v119 offset:20736
	ds_read_b128 v[174:177], v119 offset:20800
	v_add_u32_e32 v162, s70, v153
	ds_read_b64 v[182:183], v181 offset:1024
	ds_read_b64 v[184:185], v181 offset:1056
	ds_read_b64 v[186:187], v218 offset:1280
	ds_read_b64 v[188:189], v218 offset:1312
	ds_read_b64 v[190:191], v219 offset:1536
	ds_read_b64 v[192:193], v219 offset:1568
	ds_read_b64 v[194:195], v220 offset:1024
	ds_read_b64 v[196:197], v220 offset:1056
	ds_read_b128 v[198:201], v229 offset:19584
	ds_read_b128 v[202:205], v229 offset:19648
	ds_read_b128 v[206:209], v229 offset:21888
	ds_read_b128 v[210:213], v229 offset:21952
	v_add_u32_e32 v178, s70, v155
	v_add_u32_sdwa v214, s70, v142 dst_sel:DWORD dst_unused:UNUSED_PAD src0_sel:DWORD src1_sel:BYTE_2
	v_add_u32_sdwa v215, s70, v142 dst_sel:DWORD dst_unused:UNUSED_PAD src0_sel:DWORD src1_sel:BYTE_3
	ds_read_b32 v136, v136 offset:41984
	ds_read_b32 v216, v162 offset:41984
	ds_read_b32 v163, v163 offset:41984
	ds_read_b32 v165, v165 offset:41984
	ds_read_b32 v217, v178 offset:41984
	ds_read_b32 v179, v179 offset:41984
	ds_read_b32 v221, v214 offset:41984
	ds_read_b32 v222, v215 offset:41984
	s_setprio 1
	s_waitcnt vmcnt(7) lgkmcnt(15)
	v_mfma_f32_16x16x32_bf16 v[158:161], v[158:161], v[80:83], 0
	s_waitcnt vmcnt(6)
	v_mfma_f32_16x16x32_bf16 v[158:161], v[166:169], v[84:87], v[158:161]
	v_mfma_f32_16x16x32_bf16 v[166:169], v[170:173], v[80:83], 0
	v_mfma_f32_16x16x32_bf16 v[166:169], v[174:177], v[84:87], v[166:169]
	s_setprio 0
	s_nop 6
	v_cndmask_b32_e64 v158, v166, v158, s[20:21]
	s_waitcnt lgkmcnt(7)
	v_add_f32_e32 v136, v136, v158
	v_exp_f32_e32 v162, v136
	v_cndmask_b32_e64 v136, v159, v167, s[10:11]
	v_cndmask_b32_e64 v159, v160, v168, s[12:13]
	s_waitcnt lgkmcnt(5)
	v_add_f32_e32 v159, v163, v159
	v_add_f32_e32 v136, v216, v136
	v_exp_f32_e32 v214, v159
	v_cndmask_b32_e64 v159, v161, v169, s[14:15]
	v_exp_f32_e32 v178, v136
	s_waitcnt lgkmcnt(4)
	v_add_f32_e32 v159, v165, v159
	v_exp_f32_e32 v216, v159
	v_cndmask_b32_e64 v159, v214, 0, s[12:13]
	v_cndmask_b32_e64 v158, v178, 0, s[10:11]
	v_cndmask_b32_e64 v160, 0, v178, s[10:11]
	v_cndmask_b32_e64 v161, 0, v214, s[12:13]
	v_cndmask_b32_e64 v136, 0, v162, s[20:21]
	v_cndmask_b32_e64 v166, v162, 0, s[20:21]
	v_cndmask_b32_e64 v163, v216, 0, s[14:15]
	v_cndmask_b32_e64 v165, 0, v216, s[14:15]
	v_cvt_pk_bf16_f32 v158, v136, v158
	v_cvt_pk_bf16_f32 v159, v159, v163
	v_cvt_pk_bf16_f32 v160, v166, v160
	v_cvt_pk_bf16_f32 v161, v161, v165
	s_setprio 1
	v_mfma_f32_16x16x32_bf16 v[60:63], v[182:185], v[158:161], v[60:63]
	v_mfma_f32_16x16x32_bf16 v[56:59], v[186:189], v[158:161], v[56:59]
	v_mfma_f32_16x16x32_bf16 v[52:55], v[190:193], v[158:161], v[52:55]
	v_mfma_f32_16x16x32_bf16 v[48:51], v[194:197], v[158:161], v[48:51]
	s_setprio 0
	ds_read_b64 v[158:159], v181 offset:1040
	ds_read_b64 v[160:161], v181 offset:1072
	ds_read_b64 v[166:167], v218 offset:1296
	ds_read_b64 v[168:169], v218 offset:1328
	ds_read_b64 v[170:171], v219 offset:1552
	ds_read_b64 v[172:173], v219 offset:1584
	ds_read_b64 v[174:175], v220 offset:1040
	ds_read_b64 v[176:177], v220 offset:1072
	ds_read_b128 v[182:185], v229 offset:21888
	ds_read_b128 v[186:189], v229 offset:21952
	ds_read_b128 v[190:193], v229 offset:24192
	ds_read_b128 v[194:197], v229 offset:24256
	v_add_u32_e32 v136, s70, v156
	v_add_u32_sdwa v165, s70, v140 dst_sel:DWORD dst_unused:UNUSED_PAD src0_sel:DWORD src1_sel:BYTE_2
	v_add_u32_sdwa v163, s70, v139 dst_sel:DWORD dst_unused:UNUSED_PAD src0_sel:DWORD src1_sel:BYTE_1
	v_add_u32_sdwa v215, s70, v140 dst_sel:DWORD dst_unused:UNUSED_PAD src0_sel:DWORD src1_sel:BYTE_3
	ds_read_b32 v136, v136 offset:41984
	ds_read_b32 v223, v163 offset:41984
	ds_read_b32 v165, v165 offset:41984
	ds_read_b32 v224, v215 offset:41984
	s_setprio 1
	s_waitcnt vmcnt(5)
	v_mfma_f32_16x16x32_bf16 v[198:201], v[198:201], v[88:91], 0
	s_waitcnt vmcnt(4)
	v_mfma_f32_16x16x32_bf16 v[198:201], v[202:205], v[92:95], v[198:201]
	v_mfma_f32_16x16x32_bf16 v[202:205], v[206:209], v[88:91], 0
	v_mfma_f32_16x16x32_bf16 v[202:205], v[210:213], v[92:95], v[202:205]
	s_setprio 0
	s_nop 6
	v_cndmask_b32_e64 v163, v198, v202, s[16:17]
	s_waitcnt lgkmcnt(15)
	v_add_f32_e32 v163, v217, v163
	v_cndmask_b32_e64 v198, v199, v203, s[18:19]
	v_cndmask_b32_e64 v200, v200, v204, s[6:7]
	v_exp_f32_e32 v163, v163
	v_add_f32_e32 v179, v179, v198
	s_waitcnt lgkmcnt(15)
	v_add_f32_e32 v200, v221, v200
	v_exp_f32_e32 v179, v179
	v_exp_f32_e32 v215, v200
	v_cndmask_b32_e64 v200, v201, v205, s[8:9]
	s_waitcnt lgkmcnt(15)
	v_add_f32_e32 v200, v222, v200
	v_exp_f32_e32 v217, v200
	v_cndmask_b32_e64 v198, v163, 0, s[16:17]
	v_cndmask_b32_e64 v202, 0, v163, s[16:17]
	v_pk_add_f32 v[162:163], v[162:163], 0 op_sel_hi:[1,0]
	v_cndmask_b32_e64 v199, v179, 0, s[18:19]
	v_pk_add_f32 v[162:163], v[178:179], v[162:163]
	v_cndmask_b32_e64 v200, 0, v179, s[18:19]
	v_pk_add_f32 v[162:163], v[214:215], v[162:163]
	v_cndmask_b32_e64 v201, v215, 0, s[6:7]
	v_pk_add_f32 v[162:163], v[216:217], v[162:163]
	v_cndmask_b32_e64 v203, 0, v215, s[6:7]
	v_pk_add_f32 v[130:131], v[130:131], v[162:163]
	v_cndmask_b32_e64 v204, v217, 0, s[8:9]
	v_cndmask_b32_e64 v205, 0, v217, s[8:9]
	v_cvt_pk_bf16_f32 v198, v198, v199
	v_cvt_pk_bf16_f32 v199, v201, v204
	v_cvt_pk_bf16_f32 v200, v202, v200
	v_cvt_pk_bf16_f32 v201, v203, v205
	s_setprio 1
	s_waitcnt lgkmcnt(14)
	v_mfma_f32_16x16x32_bf16 v[44:47], v[158:161], v[198:201], v[44:47]
	s_waitcnt lgkmcnt(12)
	v_mfma_f32_16x16x32_bf16 v[40:43], v[166:169], v[198:201], v[40:43]
	s_waitcnt lgkmcnt(10)
	v_mfma_f32_16x16x32_bf16 v[36:39], v[170:173], v[198:201], v[36:39]
	s_waitcnt lgkmcnt(8)
	v_mfma_f32_16x16x32_bf16 v[32:35], v[174:177], v[198:201], v[32:35]
	s_setprio 0
	ds_read_b64 v[158:159], v181 offset:1072
	ds_read_b64 v[160:161], v181 offset:1104
	ds_read_b64 v[166:167], v218 offset:1328
	ds_read_b64 v[168:169], v218 offset:1360
	ds_read_b64 v[170:171], v219 offset:1584
	ds_read_b64 v[172:173], v219 offset:1616
	ds_read_b64 v[174:175], v220 offset:1072
	ds_read_b64 v[176:177], v220 offset:1104
	ds_read_b128 v[198:201], v119 offset:23040
	ds_read_b128 v[202:205], v119 offset:23104
	v_add_u32_e32 v119, v148, v151
	ds_read_b128 v[206:209], v119 offset:18432
	ds_read_b128 v[210:213], v119 offset:18496
	v_add_u32_e32 v119, s70, v154
	v_add_u32_sdwa v162, s70, v144 dst_sel:DWORD dst_unused:UNUSED_PAD src0_sel:DWORD src1_sel:BYTE_1
	v_add_u32_sdwa v163, s70, v145 dst_sel:DWORD dst_unused:UNUSED_PAD src0_sel:DWORD src1_sel:BYTE_2
	v_add_u32_sdwa v178, s70, v145 dst_sel:DWORD dst_unused:UNUSED_PAD src0_sel:DWORD src1_sel:BYTE_3
	ds_read_b32 v119, v119 offset:41984
	ds_read_b32 v179, v162 offset:41984
	ds_read_b32 v214, v163 offset:41984
	ds_read_b32 v215, v178 offset:41984
	s_setprio 1
	s_waitcnt vmcnt(3) lgkmcnt(15)
	v_mfma_f32_16x16x32_bf16 v[182:185], v[182:185], v[96:99], 0
	s_waitcnt vmcnt(2)
	v_mfma_f32_16x16x32_bf16 v[182:185], v[186:189], v[100:103], v[182:185]
	v_mfma_f32_16x16x32_bf16 v[186:189], v[190:193], v[96:99], 0
	v_mfma_f32_16x16x32_bf16 v[186:189], v[194:197], v[100:103], v[186:189]
	s_setprio 0
	s_nop 6
	v_cndmask_b32_e64 v162, v186, v182, s[2:3]
	v_add_f32_e32 v136, v136, v162
	v_exp_f32_e32 v162, v136
	v_cndmask_b32_e64 v136, v187, v183, s[4:5]
	v_cndmask_b32_e64 v183, v184, v188, s[22:23]
	s_waitcnt lgkmcnt(15)
	v_add_f32_e32 v165, v165, v183
	v_exp_f32_e32 v190, v165
	v_cndmask_b32_e64 v165, v185, v189, s[24:25]
	v_add_f32_e32 v136, v223, v136
	s_waitcnt lgkmcnt(15)
	v_add_f32_e32 v165, v224, v165
	v_exp_f32_e32 v178, v136
	v_exp_f32_e32 v192, v165
	v_cndmask_b32_e64 v183, v190, 0, s[22:23]
	v_cndmask_b32_e64 v185, 0, v190, s[22:23]
	v_cndmask_b32_e64 v182, 0, v178, s[4:5]
	v_cndmask_b32_e64 v184, v192, 0, s[24:25]
	v_cndmask_b32_e64 v136, 0, v162, s[2:3]
	v_cndmask_b32_e64 v163, v162, 0, s[2:3]
	v_cndmask_b32_e64 v165, v178, 0, s[4:5]
	v_cndmask_b32_e64 v186, 0, v192, s[24:25]
	v_cvt_pk_bf16_f32 v182, v136, v182
	v_cvt_pk_bf16_f32 v183, v183, v184
	v_cvt_pk_bf16_f32 v184, v163, v165
	v_cvt_pk_bf16_f32 v185, v185, v186
	s_setprio 1
	s_waitcnt lgkmcnt(14)
	v_mfma_f32_16x16x32_bf16 v[28:31], v[158:161], v[182:185], v[28:31]
	s_waitcnt lgkmcnt(12)
	v_mfma_f32_16x16x32_bf16 v[24:27], v[166:169], v[182:185], v[24:27]
	s_waitcnt lgkmcnt(10)
	v_mfma_f32_16x16x32_bf16 v[20:23], v[170:173], v[182:185], v[20:23]
	s_waitcnt lgkmcnt(8)
	v_mfma_f32_16x16x32_bf16 v[16:19], v[174:177], v[182:185], v[16:19]
	s_setprio 0
	ds_read_b64 v[158:159], v220 offset:1088
	ds_read_b64 v[160:161], v220 offset:1120
	ds_read_b64 v[166:167], v219 offset:1600
	ds_read_b64 v[168:169], v219 offset:1632
	ds_read_b64 v[170:171], v218 offset:1344
	ds_read_b64 v[172:173], v218 offset:1376
	ds_read_b64 v[174:175], v181 offset:1088
	ds_read_b64 v[176:177], v181 offset:1120
	s_setprio 1
	s_waitcnt vmcnt(1) lgkmcnt(15)
	v_mfma_f32_16x16x32_bf16 v[182:185], v[198:201], v[104:107], 0
	s_waitcnt lgkmcnt(13)
	v_mfma_f32_16x16x32_bf16 v[186:189], v[206:209], v[104:107], 0
	s_waitcnt vmcnt(0)
	v_mfma_f32_16x16x32_bf16 v[182:185], v[202:205], v[108:111], v[182:185]
	s_waitcnt lgkmcnt(12)
	v_mfma_f32_16x16x32_bf16 v[186:189], v[210:213], v[108:111], v[186:189]
	s_setprio 0
	s_nop 6
	v_cndmask_b32_e64 v136, v182, v186, s[26:27]
	s_waitcnt lgkmcnt(11)
	v_add_f32_e32 v119, v119, v136
	v_exp_f32_e32 v163, v119
	v_cndmask_b32_e64 v119, v183, v187, s[28:29]
	v_cndmask_b32_e64 v181, v184, v188, s[30:31]
	s_waitcnt lgkmcnt(10)
	v_add_f32_e32 v119, v179, v119
	s_waitcnt lgkmcnt(9)
	v_add_f32_e32 v181, v214, v181
	v_exp_f32_e32 v179, v119
	v_exp_f32_e32 v191, v181
	v_cndmask_b32_e64 v181, v185, v189, s[34:35]
	s_waitcnt lgkmcnt(8)
	v_add_f32_e32 v181, v215, v181
	v_exp_f32_e32 v193, v181
	v_cndmask_b32_e64 v119, v163, 0, s[26:27]
	v_cndmask_b32_e64 v136, 0, v163, s[26:27]
	v_pk_add_f32 v[162:163], v[162:163], 0 op_sel_hi:[1,0]
	v_cndmask_b32_e64 v183, v191, 0, s[30:31]
	v_pk_add_f32 v[162:163], v[178:179], v[162:163]
	v_cndmask_b32_e64 v185, 0, v191, s[30:31]
	v_pk_add_f32 v[162:163], v[190:191], v[162:163]
	v_cndmask_b32_e64 v184, v193, 0, s[34:35]
	v_pk_add_f32 v[162:163], v[192:193], v[162:163]
	v_cndmask_b32_e64 v165, v179, 0, s[28:29]
	v_pk_add_f32 v[124:125], v[124:125], v[162:163]
	v_cndmask_b32_e64 v181, 0, v179, s[28:29]
	v_cndmask_b32_e64 v186, 0, v193, s[34:35]
	v_cvt_pk_bf16_f32 v182, v119, v165
	v_cvt_pk_bf16_f32 v183, v183, v184
	v_cvt_pk_bf16_f32 v184, v136, v181
	v_cvt_pk_bf16_f32 v185, v185, v186
	s_setprio 1
	s_waitcnt lgkmcnt(0)
	v_mfma_f32_16x16x32_bf16 v[12:15], v[174:177], v[182:185], v[12:15]
	v_mfma_f32_16x16x32_bf16 v[8:11], v[170:173], v[182:185], v[8:11]
	v_mfma_f32_16x16x32_bf16 v[4:7], v[166:169], v[182:185], v[4:7]
	v_mfma_f32_16x16x32_bf16 v[0:3], v[158:161], v[182:185], v[0:3]
	s_setprio 0
.LBB0_414:
	s_cmp_ge_u32 s68, s96
	s_cbranch_scc1 .LBB0_401
	s_waitcnt vmcnt(1)
	ds_write_b128 v225, v[64:67]
	s_waitcnt vmcnt(0)
	ds_write_b128 v157, v[68:71] offset:9216
	s_branch .LBB0_401

.LBB0_471:
	s_or_b64 exec, exec, s[2:3]
	s_abs_i32 s0, s84
	v_cvt_f32_u32_e32 v0, s0
	s_sub_i32 s3, 0, s0
	s_add_i32 s1, s84, 0x4ff
	s_xor_b32 s2, s1, s84
	v_rcp_iflag_f32_e32 v0, v0
	s_abs_i32 s1, s1
	s_ashr_i32 s2, s2, 31
	s_mov_b32 s49, 0
	v_mul_f32_e32 v0, 0x4f7ffffe, v0
	v_cvt_u32_f32_e32 v0, v0
	s_waitcnt lgkmcnt(0)
	s_barrier
	v_readfirstlane_b32 s4, v0
	s_mul_i32 s3, s3, s4
	s_mul_hi_u32 s3, s4, s3
	s_add_i32 s4, s4, s3
	s_mul_hi_u32 s3, s1, s4
	s_mul_i32 s4, s3, s0
	s_sub_i32 s1, s1, s4
	s_add_i32 s5, s3, 1
	s_sub_i32 s4, s1, s0
	s_cmp_ge_u32 s1, s0
	s_cselect_b32 s3, s5, s3
	s_cselect_b32 s1, s4, s1
	s_add_i32 s4, s3, 1
	s_cmp_ge_u32 s1, s0
	s_cselect_b32 s0, s4, s3
	s_xor_b32 s0, s0, s2
	s_sub_i32 s0, s0, s2
	s_mul_i32 s70, s0, s33
	s_min_i32 s0, s0, 3
	s_add_i32 s0, s70, s0
	s_min_i32 s71, s0, 0x500
	s_cmp_lt_i32 s70, s71
	s_cbranch_scc0 .LBB0_508
	v_lshrrev_b32_e32 v1, 2, v180
	v_and_b32_e32 v2, 12, v1
	v_add_u32_e32 v13, 26, v2
	v_add_u32_e32 v14, 24, v146
	v_sub_u32_e32 v15, v13, v14
	v_mov_b32_e32 v16, 0x400
	v_cmp_gt_u32_e32 vcc, 16, v15
	v_mov_b32_e32 v18, 0x800
	v_mov_b32_e32 v19, 0x200
	v_cndmask_b32_e32 v15, 0, v16, vcc
	v_add_u32_e32 v16, 27, v2
	v_sub_u32_e32 v17, v16, v14
	v_cmp_gt_u32_e64 s[0:1], 16, v17
	v_sub_u32_e64 v0, v146, 8 clamp
	v_or_b32_e32 v4, 1, v2
	v_cndmask_b32_e64 v17, 0, v18, s[0:1]
	v_add_u32_e32 v18, 25, v2
	v_sub_u32_e32 v14, v18, v14
	v_cmp_gt_u32_e64 s[4:5], 16, v14
	v_or_b32_e32 v6, 2, v2
	v_or_b32_e32 v8, 3, v1
	v_add_u32_e32 v9, 8, v146
	v_add_u32_e32 v11, 9, v2
	v_cndmask_b32_e64 v14, 0, v19, s[4:5]
	v_add_u32_e32 v19, 10, v2
	v_add_u32_e32 v21, 11, v2
	v_sub_u32_e32 v3, v2, v0
	v_sub_u32_e32 v5, v4, v0
	v_sub_u32_e32 v7, v6, v0
	v_sub_u32_e32 v0, v8, v0
	v_sub_u32_e32 v10, v2, v146
	v_sub_u32_e32 v12, v11, v9
	v_sub_u32_e32 v20, v19, v9
	v_sub_u32_e32 v9, v21, v9
	v_mov_b32_e32 v22, 0x80
	v_cmp_lt_u32_e64 s[8:9], 15, v9
	v_cmp_lt_u32_e64 s[14:15], 15, v0
	v_cmp_lt_u32_e64 s[16:17], 15, v10
	v_cmp_gt_u32_e64 s[2:3], 16, v10
	v_cmp_lt_u32_e64 s[6:7], 15, v20
	v_cndmask_b32_e64 v9, v22, 0, s[8:9]
	v_cmp_lt_u32_e64 s[10:11], 15, v5
	v_cndmask_b32_e64 v0, 8, 0, s[14:15]
	v_cndmask_b32_e64 v10, 16, 0, s[16:17]
	v_cndmask_b32_e64 v20, 64, 0, s[6:7]
	v_cndmask_b32_e64 v5, 2, 0, s[10:11]
	v_cmp_lt_u32_e64 s[12:13], 15, v7
	v_cmp_lt_u32_e64 s[18:19], 15, v12
	v_or3_b32 v0, v0, v10, v9
	v_or_b32_e32 v15, v15, v17
	v_mov_b32_e32 v17, 0x100
	v_cndmask_b32_e64 v7, 4, 0, s[12:13]
	v_cndmask_b32_e64 v12, 32, 0, s[18:19]
	v_or3_b32 v0, v5, v20, v0
	v_cndmask_b32_e64 v17, 0, v17, s[2:3]
	v_or3_b32 v0, v7, v12, v0
	v_or3_b32 v5, v17, v0, v14
	v_add_u32_e32 v0, 42, v2
	v_add_u32_e32 v12, 43, v2
	v_add_u32_e32 v17, 41, v2
	v_cndmask_b32_e32 v0, v0, v13, vcc
	v_or_b32_e32 v9, 32, v146
	v_cndmask_b32_e64 v12, v12, v16, s[0:1]
	v_cndmask_b32_e64 v17, v17, v18, s[4:5]
	v_sub_u32_e32 v0, v0, v9
	v_sub_u32_e32 v12, v12, v9
	v_sub_u32_e32 v17, v17, v9
	v_cndmask_b32_e64 v22, 40, 24, s[2:3]
	v_sub_u32_e32 v9, v2, v9
	v_mov_b32_e32 v20, 0x3c00
	v_add_u32_e32 v9, v9, v22
	v_mov_b32_e32 v10, 0x3c0000
	v_bfrev_b32_e32 v14, 60
	v_lshl_add_u32 v17, v17, 10, v20
	v_lshl_add_u32 v9, v9, 2, 60
	v_lshl_add_u32 v0, v0, 18, v10
	v_lshl_add_u32 v12, v12, 26, v14
	v_or_b32_e32 v139, v17, v9
	v_or3_b32 v140, v0, v12, v139
	v_cndmask_b32_e64 v0, v19, v13, s[6:7]
	v_or_b32_e32 v9, 16, v146
	v_cndmask_b32_e64 v12, v21, v16, s[8:9]
	v_cndmask_b32_e64 v11, v11, v18, s[18:19]
	v_sub_u32_e32 v0, v0, v9
	v_sub_u32_e32 v12, v12, v9
	v_sub_u32_e32 v11, v11, v9
	v_cndmask_b32_e64 v13, 8, 24, s[16:17]
	v_sub_u32_e32 v9, v2, v9
	v_add_u32_e32 v9, v9, v13
	v_lshl_add_u32 v11, v11, 10, v20
	v_lshl_add_u32 v9, v9, 2, 60
	v_lshl_add_u32 v0, v0, 18, v10
	v_lshl_add_u32 v12, v12, 26, v14
	v_or_b32_e32 v141, v11, v9
	v_or3_b32 v142, v0, v12, v141
	v_or_b32_e32 v0, 18, v2
	v_cndmask_b32_e64 v0, v6, v0, s[12:13]
	v_or_b32_e32 v6, 19, v1
	v_cndmask_b32_e64 v6, v8, v6, s[14:15]
	v_or_b32_e32 v8, 17, v2
	v_cndmask_b32_e64 v4, v4, v8, s[10:11]
	v_or_b32_e32 v8, 16, v2
	v_cmp_gt_u32_e64 s[20:21], 16, v3
	v_sub_u32_e32 v4, v4, v146
	v_sub_u32_e32 v0, v0, v146
	v_cndmask_b32_e64 v3, v8, v2, s[20:21]
	v_sub_u32_e32 v3, v3, v146
	v_sub_u32_e32 v6, v6, v146
	v_lshl_add_u32 v4, v4, 10, v20
	v_lshl_add_u32 v3, v3, 2, 60
	v_lshl_add_u32 v0, v0, 18, v10
	v_lshl_add_u32 v6, v6, 26, v14
	v_or_b32_e32 v4, v4, v3
	v_or3_b32 v143, v0, v6, v4
	v_or_b32_e32 v6, 48, v180
	v_add_u32_e32 v8, -8, v6
	v_or_b32_e32 v0, 35, v1
	v_min_u32_e32 v8, 48, v8
	v_sub_u32_e32 v9, v0, v8
	v_mov_b32_e32 v11, 0x8000
	v_cmp_gt_u32_e32 vcc, 16, v9
	v_mov_b32_e32 v16, 0x4000
	v_or_b32_e32 v1, 51, v1
	v_cndmask_b32_e32 v9, 0, v11, vcc
	v_or_b32_e32 v11, 34, v2
	v_sub_u32_e32 v12, v11, v8
	v_cmp_gt_u32_e64 s[0:1], 16, v12
	v_mov_b32_e32 v18, 0x2000
	v_cndmask_b32_e32 v0, v1, v0, vcc
	v_cndmask_b32_e64 v12, 0, v16, s[0:1]
	v_or_b32_e32 v16, 33, v2
	v_sub_u32_e32 v17, v16, v8
	v_cmp_gt_u32_e64 s[22:23], 16, v17
	v_or_b32_e32 v1, 50, v2
	v_cndmask_b32_e64 v1, v1, v11, s[0:1]
	v_cndmask_b32_e64 v17, 0, v18, s[22:23]
	v_or_b32_e32 v18, 32, v2
	v_sub_u32_e32 v8, v18, v8
	v_sub_u32_e32 v1, v1, v6
	v_cmp_gt_u32_e64 s[24:25], 16, v8
	v_lshl_add_u32 v1, v1, 18, v10
	v_or_b32_e32 v10, 49, v2
	v_or_b32_e32 v2, 48, v2
	v_cndmask_b32_e64 v10, v10, v16, s[22:23]
	v_cndmask_b32_e64 v2, v2, v18, s[24:25]
	v_sub_u32_e32 v10, v10, v6
	v_sub_u32_e32 v2, v2, v6
	v_sub_u32_e32 v0, v0, v6
	v_lshl_add_u32 v10, v10, 10, v20
	v_lshl_add_u32 v2, v2, 2, 60
	v_lshl_add_u32 v0, v0, 26, v14
	v_or_b32_e32 v144, v10, v2
	v_or3_b32 v145, v1, v0, v144
	v_and_b32_e32 v1, 7, v164
	v_mov_b32_e32 v19, 0x1000
	v_lshrrev_b32_e32 v147, 3, v164
	v_lshlrev_b32_e32 v114, 4, v1
	s_movk_i32 s0, 0x90
	s_movk_i32 s26, 0x400
	s_movk_i32 s27, 0x800
	v_cndmask_b32_e64 v8, 0, v19, s[24:25]
	v_lshlrev_b32_e32 v0, 3, v1
	v_lshrrev_b32_e32 v1, 4, v180
	v_mad_u32_u24 v10, v147, s0, v114
	s_add_u32 s0, s80, 0x11000000
	v_and_b32_e32 v112, 48, v180
	v_or_b32_e32 v7, v15, v5
	s_movk_i32 s29, 0x1000
	v_or_b32_e32 v8, v8, v17
	v_lshl_add_u32 v150, v1, 3, 0
	v_mul_u32_u24_e32 v151, 0x90, v6
	v_bitop3_b32 v6, v15, s26, v5 bitop3:0xc8
	v_bitop3_b32 v5, v15, s27, v5 bitop3:0xc8
	v_and_b32_e32 v152, 0xfc, v3
	v_and_b32_e32 v154, 0xfc, v2
	v_lshlrev_b32_e32 v2, 2, v1
	s_addc_u32 s1, s81, 0
	v_lshl_add_u32 v1, v13, 2, v112
	v_lshlrev_b32_e32 v3, 2, v146
	s_movk_i32 s28, 0x2000
	v_cmp_eq_u32_e64 s[24:25], 0, v5
	v_bitop3_b32 v5, v8, s29, v7 bitop3:0xc8
	s_add_u32 s50, s80, 0x50000
	v_sub_u32_e32 v1, v1, v3
	s_movk_i32 s30, 0x4000
	v_or_b32_e32 v17, v8, v7
	v_or_b32_e32 v9, v12, v9
	v_cmp_eq_u32_e64 s[26:27], 0, v5
	v_bitop3_b32 v5, v8, s28, v7 bitop3:0xc8
	s_addc_u32 s51, s81, 0
	v_add_u32_e32 v1, -4, v1
	s_mov_b32 s34, 0x8000
	v_cmp_eq_u32_e64 s[28:29], 0, v5
	v_bitop3_b32 v5, v9, s30, v17 bitop3:0xc8
	s_add_u32 s72, s80, 0x17000000
	v_and_b32_e32 v155, 0xfc, v1
	v_lshl_add_u32 v1, v22, 2, v112
	v_mov_b32_e32 v113, 0
	v_cmp_eq_u32_e64 s[30:31], 0, v5
	v_bitop3_b32 v5, v9, s34, v17 bitop3:0xc8
	s_addc_u32 s73, s81, 0
	v_sub_u32_e32 v1, v1, v3
	v_and_b32_e32 v11, 48, v164
	v_cmp_eq_u32_e64 s[34:35], 0, v5
	v_lshrrev_b32_e32 v153, 8, v4
	v_lshl_add_u64 v[4:5], s[80:81], 0, v[112:113]
	s_mov_b64 s[38:39], 0xc000000
	s_add_u32 s74, s80, 0x16000000
	v_add_u32_e32 v1, 0xffffffbc, v1
	v_add_u32_e32 v148, 0, v11
	v_mul_u32_u24_e32 v149, 0x90, v146
	v_cmp_eq_u32_e64 s[22:23], 0, v6
	v_cmp_gt_u32_e64 s[36:37], 16, v180
	v_lshl_add_u64 v[116:117], v[4:5], 0, s[38:39]
	s_addc_u32 s75, s81, 0
	v_mov_b32_e32 v115, v113
	v_and_b32_e32 v156, 0xfc, v1
	v_lshlrev_b32_e32 v112, 1, v0
	s_mov_b64 s[52:53], 0x20000
	s_mov_b64 s[60:61], 0x100
	v_lshlrev_b32_e32 v118, 1, v2
	s_mov_b64 s[62:63], 0x39000000
	s_mov_b32 s76, 0x500000
	v_add_u32_e32 v157, 0, v10
	v_add_u32_e32 v226, 4, v147
	v_bfe_u32 v226, v226, 3, 1
	v_and_b32_e32 v227, 1, v164
	v_lshlrev_b32_e32 v227, 5, v227
	v_sub_u32_e32 v227, 16, v227
	v_mad_i32_i24 v225, v226, v227, v157
	v_add_u32_e32 v226, 4, v146
	v_bfe_u32 v226, v226, 3, 1
	v_lshlrev_b32_e32 v226, 4, v226
	v_xor_b32_e32 v148, v148, v226
	v_xor_b32_e32 v228, 16, v148
	s_branch .LBB0_474

.LBB0_483:
	s_add_i32 s94, s38, s92
	s_lshl_b32 s38, s94, 6
	s_add_i32 s38, s38, s39
	v_add_u32_e32 v128, s38, v146
	s_lshl_b32 s38, s67, 1
	s_mov_b32 s39, s49
	v_ashrrev_i32_e32 v129, 31, v128
	v_lshl_add_u64 v[0:1], v[116:117], 0, s[38:39]
	v_lshlrev_b64 v[2:3], 10, v[128:129]
	v_add_u32_e32 v126, 16, v128
	v_lshl_add_u64 v[2:3], v[0:1], 0, v[2:3]
	v_ashrrev_i32_e32 v127, 31, v126
	global_load_dwordx4 v[80:83], v[2:3], off
	global_load_dwordx4 v[84:87], v[2:3], off offset:64
	v_lshlrev_b64 v[2:3], 10, v[126:127]
	v_add_u32_e32 v122, 32, v128
	v_lshl_add_u64 v[2:3], v[0:1], 0, v[2:3]
	v_ashrrev_i32_e32 v123, 31, v122
	global_load_dwordx4 v[88:91], v[2:3], off
	global_load_dwordx4 v[92:95], v[2:3], off offset:64
	v_lshlrev_b64 v[2:3], 10, v[122:123]
	v_add_u32_e32 v120, 48, v128
	v_lshl_add_u64 v[2:3], v[0:1], 0, v[2:3]
	v_ashrrev_i32_e32 v121, 31, v120
	global_load_dwordx4 v[96:99], v[2:3], off
	global_load_dwordx4 v[100:103], v[2:3], off offset:64
	v_lshlrev_b64 v[2:3], 10, v[120:121]
	v_lshl_add_u64 v[0:1], v[0:1], 0, v[2:3]
	global_load_dwordx4 v[104:107], v[0:1], off
	global_load_dwordx4 v[108:111], v[0:1], off offset:64
	v_mov_b32_e32 v131, 0
	s_andn2_b64 vcc, exec, s[68:69]
	v_mov_b32_e32 v130, 0
	v_mov_b32_e32 v125, 0
	v_mov_b32_e32 v124, 0
	v_mov_b32_e32 v63, 0
	v_mov_b32_e32 v62, 0
	v_mov_b32_e32 v61, 0
	v_mov_b32_e32 v60, 0
	v_mov_b32_e32 v59, 0
	v_mov_b32_e32 v58, 0
	v_mov_b32_e32 v57, 0
	v_mov_b32_e32 v56, 0
	v_mov_b32_e32 v55, 0
	v_mov_b32_e32 v54, 0
	v_mov_b32_e32 v53, 0
	v_mov_b32_e32 v52, 0
	v_mov_b32_e32 v51, 0
	v_mov_b32_e32 v50, 0
	v_mov_b32_e32 v49, 0
	v_mov_b32_e32 v48, 0
	v_mov_b32_e32 v47, 0
	v_mov_b32_e32 v46, 0
	v_mov_b32_e32 v45, 0
	v_mov_b32_e32 v44, 0
	v_mov_b32_e32 v43, 0
	v_mov_b32_e32 v42, 0
	v_mov_b32_e32 v41, 0
	v_mov_b32_e32 v40, 0
	v_mov_b32_e32 v39, 0
	v_mov_b32_e32 v38, 0
	v_mov_b32_e32 v37, 0
	v_mov_b32_e32 v36, 0
	v_mov_b32_e32 v35, 0
	v_mov_b32_e32 v34, 0
	v_mov_b32_e32 v33, 0
	v_mov_b32_e32 v32, 0
	v_mov_b32_e32 v31, 0
	v_mov_b32_e32 v30, 0
	v_mov_b32_e32 v29, 0
	v_mov_b32_e32 v28, 0
	v_mov_b32_e32 v27, 0
	v_mov_b32_e32 v26, 0
	v_mov_b32_e32 v25, 0
	v_mov_b32_e32 v24, 0
	v_mov_b32_e32 v23, 0
	v_mov_b32_e32 v22, 0
	v_mov_b32_e32 v21, 0
	v_mov_b32_e32 v20, 0
	v_mov_b32_e32 v19, 0
	v_mov_b32_e32 v18, 0
	v_mov_b32_e32 v17, 0
	v_mov_b32_e32 v16, 0
	v_mov_b32_e32 v15, 0
	v_mov_b32_e32 v14, 0
	v_mov_b32_e32 v13, 0
	v_mov_b32_e32 v12, 0
	v_mov_b32_e32 v11, 0
	v_mov_b32_e32 v10, 0
	v_mov_b32_e32 v9, 0
	v_mov_b32_e32 v8, 0
	v_mov_b32_e32 v7, 0
	v_mov_b32_e32 v6, 0
	v_mov_b32_e32 v5, 0
	v_mov_b32_e32 v4, 0
	v_mov_b32_e32 v3, 0
	v_mov_b32_e32 v2, 0
	v_mov_b32_e32 v1, 0
	v_mov_b32_e32 v0, 0
	s_waitcnt vmcnt(9)
	ds_write_b128 v225, v[64:67]
	s_waitcnt vmcnt(8)
	ds_write_b128 v157, v[68:71] offset:9216
	s_waitcnt lgkmcnt(0)
	s_barrier
	s_cbranch_vccnz .LBB0_500
	s_max_i32 s38, s94, 4
	s_add_i32 s38, s38, -4
	s_min_u32 s38, s38, s66
	s_mov_b32 s67, s49
	v_mov_b32_e32 v133, v113
	s_add_i32 s39, s38, 8
	v_mov_b32_e32 v0, s66
	v_cmp_lt_u64_e32 vcc, s[66:67], v[132:133]
	s_add_u32 s66, s80, s48
	v_mov_b32_e32 v1, v113
	v_cndmask_b32_e32 v2, v132, v0, vcc
	v_lshlrev_b32_e32 v0, 16, v2
	s_addc_u32 s67, s81, 0
	v_lshl_add_u64 v[0:1], s[66:67], 0, v[0:1]
	v_lshl_add_u64 v[132:133], v[0:1], 0, v[134:135]
	v_lshlrev_b32_e32 v0, 7, v2
	v_mov_b32_e32 v1, v113
	s_mul_i32 s68, s77, 0x780
	v_lshlrev_b32_e32 v2, 1, v136
	v_mov_b32_e32 v3, v113
	v_lshl_add_u64 v[0:1], s[64:65], 0, v[0:1]
	s_lshl_b32 s64, s89, 7
	v_lshl_add_u64 v[134:135], v[0:1], 0, v[2:3]
	s_add_i32 s68, s68, s64
	s_lshl_b32 s64, s94, 7
	v_mov_b32_e32 v2, v113
	s_sub_i32 s64, s68, s64
	v_mov_b32_e32 v124, v113
	v_mov_b32_e32 v125, v113
	v_mov_b32_e32 v0, v113
	v_mov_b32_e32 v1, v113
	v_mov_b64_e32 v[6:7], v[2:3]
	v_mov_b64_e32 v[10:11], v[2:3]
	v_mov_b64_e32 v[14:15], v[2:3]
	v_mov_b64_e32 v[18:19], v[2:3]
	v_mov_b64_e32 v[22:23], v[2:3]
	v_mov_b64_e32 v[26:27], v[2:3]
	v_mov_b64_e32 v[30:31], v[2:3]
	v_mov_b64_e32 v[34:35], v[2:3]
	v_mov_b64_e32 v[38:39], v[2:3]
	v_mov_b64_e32 v[42:43], v[2:3]
	v_mov_b64_e32 v[46:47], v[2:3]
	v_mov_b64_e32 v[50:51], v[2:3]
	v_mov_b64_e32 v[54:55], v[2:3]
	v_mov_b64_e32 v[58:59], v[2:3]
	v_mov_b64_e32 v[62:63], v[2:3]
	s_add_i32 s48, s89, 3
	s_add_i32 s66, s64, 0
	v_mov_b64_e32 v[4:5], v[0:1]
	v_mov_b64_e32 v[8:9], v[0:1]
	v_mov_b64_e32 v[12:13], v[0:1]
	v_mov_b64_e32 v[16:17], v[0:1]
	v_mov_b64_e32 v[20:21], v[0:1]
	v_mov_b64_e32 v[24:25], v[0:1]
	v_mov_b64_e32 v[28:29], v[0:1]
	v_mov_b64_e32 v[32:33], v[0:1]
	v_mov_b64_e32 v[36:37], v[0:1]
	v_mov_b64_e32 v[40:41], v[0:1]
	v_mov_b64_e32 v[44:45], v[0:1]
	v_mov_b64_e32 v[48:49], v[0:1]
	v_mov_b64_e32 v[52:53], v[0:1]
	v_mov_b64_e32 v[56:57], v[0:1]
	v_mov_b64_e32 v[60:61], v[0:1]
	v_mov_b64_e32 v[130:131], v[124:125]
	s_branch .LBB0_487

.LBB0_489:
	s_add_i32 s68, s48, -3
	s_cmp_ge_u32 s68, s38
	s_cselect_b64 s[64:65], -1, 0
	s_cmp_lt_u32 s68, s39
	s_cselect_b64 s[94:95], -1, 0
	s_and_b64 s[64:65], s[64:65], s[94:95]
	s_andn2_b64 vcc, exec, s[64:65]
	s_cbranch_vccnz .LBB0_491
	v_add_u32_e32 v178, v150, v149
	v_add_u32_e32 v181, 0x2000, v178
	v_add_u32_e32 v218, 0x2800, v178
	v_add_u32_e32 v219, 0x3000, v178
	v_add_u32_e32 v178, v150, v151
	v_add_u32_e32 v119, v148, v149
	v_add_u32_e32 v229, v228, v149
	v_add_u32_e32 v136, s66, v152
	v_add_u32_sdwa v163, s66, v143 dst_sel:DWORD dst_unused:UNUSED_PAD src0_sel:DWORD src1_sel:BYTE_2
	v_add_u32_sdwa v165, s66, v143 dst_sel:DWORD dst_unused:UNUSED_PAD src0_sel:DWORD src1_sel:BYTE_3
	v_add_u32_e32 v220, 0x2000, v178
	v_add_u32_sdwa v179, s66, v141 dst_sel:DWORD dst_unused:UNUSED_PAD src0_sel:DWORD src1_sel:BYTE_1
	ds_read_b128 v[158:161], v119
	ds_read_b128 v[166:169], v119 offset:64
	ds_read_b128 v[170:173], v119 offset:2304
	ds_read_b128 v[174:177], v119 offset:2368
	v_add_u32_e32 v162, s66, v153
	ds_read_b64 v[182:183], v181 offset:1024
	ds_read_b64 v[184:185], v181 offset:1056
	ds_read_b64 v[186:187], v218 offset:1280
	ds_read_b64 v[188:189], v218 offset:1312
	ds_read_b64 v[190:191], v219 offset:1536
	ds_read_b64 v[192:193], v219 offset:1568
	ds_read_b64 v[194:195], v220 offset:1024
	ds_read_b64 v[196:197], v220 offset:1056
	ds_read_b128 v[198:201], v229 offset:1152
	ds_read_b128 v[202:205], v229 offset:1216
	ds_read_b128 v[206:209], v229 offset:3456
	ds_read_b128 v[210:213], v229 offset:3520
	v_add_u32_e32 v178, s66, v155
	v_add_u32_sdwa v214, s66, v142 dst_sel:DWORD dst_unused:UNUSED_PAD src0_sel:DWORD src1_sel:BYTE_2
	v_add_u32_sdwa v215, s66, v142 dst_sel:DWORD dst_unused:UNUSED_PAD src0_sel:DWORD src1_sel:BYTE_3
	ds_read_b32 v136, v136 offset:41856
	ds_read_b32 v216, v162 offset:41856
	ds_read_b32 v163, v163 offset:41856
	ds_read_b32 v165, v165 offset:41856
	ds_read_b32 v217, v178 offset:41856
	ds_read_b32 v179, v179 offset:41856
	ds_read_b32 v221, v214 offset:41856
	ds_read_b32 v222, v215 offset:41856
	s_setprio 1
	s_waitcnt vmcnt(7) lgkmcnt(15)
	v_mfma_f32_16x16x32_bf16 v[158:161], v[158:161], v[80:83], 0
	s_waitcnt vmcnt(6)
	v_mfma_f32_16x16x32_bf16 v[158:161], v[166:169], v[84:87], v[158:161]
	v_mfma_f32_16x16x32_bf16 v[166:169], v[170:173], v[80:83], 0
	v_mfma_f32_16x16x32_bf16 v[166:169], v[174:177], v[84:87], v[166:169]
	s_setprio 0
	s_nop 6
	v_cndmask_b32_e64 v158, v166, v158, s[20:21]
	s_waitcnt lgkmcnt(7)
	v_add_f32_e32 v136, v136, v158
	v_exp_f32_e32 v162, v136
	v_cndmask_b32_e64 v136, v159, v167, s[10:11]
	v_cndmask_b32_e64 v159, v160, v168, s[12:13]
	s_waitcnt lgkmcnt(5)
	v_add_f32_e32 v159, v163, v159
	v_add_f32_e32 v136, v216, v136
	v_exp_f32_e32 v214, v159
	v_cndmask_b32_e64 v159, v161, v169, s[14:15]
	v_exp_f32_e32 v178, v136
	s_waitcnt lgkmcnt(4)
	v_add_f32_e32 v159, v165, v159
	v_exp_f32_e32 v216, v159
	v_cndmask_b32_e64 v159, v214, 0, s[12:13]
	v_cndmask_b32_e64 v158, v178, 0, s[10:11]
	v_cndmask_b32_e64 v160, 0, v178, s[10:11]
	v_cndmask_b32_e64 v161, 0, v214, s[12:13]
	v_cndmask_b32_e64 v136, 0, v162, s[20:21]
	v_cndmask_b32_e64 v166, v162, 0, s[20:21]
	v_cndmask_b32_e64 v163, v216, 0, s[14:15]
	v_cndmask_b32_e64 v165, 0, v216, s[14:15]
	v_cvt_pk_bf16_f32 v158, v136, v158
	v_cvt_pk_bf16_f32 v159, v159, v163
	v_cvt_pk_bf16_f32 v160, v166, v160
	v_cvt_pk_bf16_f32 v161, v161, v165
	s_setprio 1
	v_mfma_f32_16x16x32_bf16 v[60:63], v[182:185], v[158:161], v[60:63]
	v_mfma_f32_16x16x32_bf16 v[56:59], v[186:189], v[158:161], v[56:59]
	v_mfma_f32_16x16x32_bf16 v[52:55], v[190:193], v[158:161], v[52:55]
	v_mfma_f32_16x16x32_bf16 v[48:51], v[194:197], v[158:161], v[48:51]
	s_setprio 0
	ds_read_b64 v[158:159], v181 offset:1040
	ds_read_b64 v[160:161], v181 offset:1072
	ds_read_b64 v[166:167], v218 offset:1296
	ds_read_b64 v[168:169], v218 offset:1328
	ds_read_b64 v[170:171], v219 offset:1552
	ds_read_b64 v[172:173], v219 offset:1584
	ds_read_b64 v[174:175], v220 offset:1040
	ds_read_b64 v[176:177], v220 offset:1072
	ds_read_b128 v[182:185], v229 offset:3456
	ds_read_b128 v[186:189], v229 offset:3520
	ds_read_b128 v[190:193], v229 offset:5760
	ds_read_b128 v[194:197], v229 offset:5824
	v_add_u32_e32 v136, s66, v156
	v_add_u32_sdwa v165, s66, v140 dst_sel:DWORD dst_unused:UNUSED_PAD src0_sel:DWORD src1_sel:BYTE_2
	v_add_u32_sdwa v163, s66, v139 dst_sel:DWORD dst_unused:UNUSED_PAD src0_sel:DWORD src1_sel:BYTE_1
	v_add_u32_sdwa v215, s66, v140 dst_sel:DWORD dst_unused:UNUSED_PAD src0_sel:DWORD src1_sel:BYTE_3
	ds_read_b32 v136, v136 offset:41856
	ds_read_b32 v223, v163 offset:41856
	ds_read_b32 v165, v165 offset:41856
	ds_read_b32 v224, v215 offset:41856
	s_setprio 1
	s_waitcnt vmcnt(5)
	v_mfma_f32_16x16x32_bf16 v[198:201], v[198:201], v[88:91], 0
	s_waitcnt vmcnt(4)
	v_mfma_f32_16x16x32_bf16 v[198:201], v[202:205], v[92:95], v[198:201]
	v_mfma_f32_16x16x32_bf16 v[202:205], v[206:209], v[88:91], 0
	v_mfma_f32_16x16x32_bf16 v[202:205], v[210:213], v[92:95], v[202:205]
	s_setprio 0
	s_nop 6
	v_cndmask_b32_e64 v163, v198, v202, s[16:17]
	s_waitcnt lgkmcnt(15)
	v_add_f32_e32 v163, v217, v163
	v_cndmask_b32_e64 v198, v199, v203, s[18:19]
	v_cndmask_b32_e64 v200, v200, v204, s[6:7]
	v_exp_f32_e32 v163, v163
	v_add_f32_e32 v179, v179, v198
	s_waitcnt lgkmcnt(15)
	v_add_f32_e32 v200, v221, v200
	v_exp_f32_e32 v179, v179
	v_exp_f32_e32 v215, v200
	v_cndmask_b32_e64 v200, v201, v205, s[8:9]
	s_waitcnt lgkmcnt(15)
	v_add_f32_e32 v200, v222, v200
	v_exp_f32_e32 v217, v200
	v_cndmask_b32_e64 v198, v163, 0, s[16:17]
	v_cndmask_b32_e64 v202, 0, v163, s[16:17]
	v_pk_add_f32 v[162:163], v[162:163], 0 op_sel_hi:[1,0]
	v_cndmask_b32_e64 v199, v179, 0, s[18:19]
	v_pk_add_f32 v[162:163], v[178:179], v[162:163]
	v_cndmask_b32_e64 v200, 0, v179, s[18:19]
	v_pk_add_f32 v[162:163], v[214:215], v[162:163]
	v_cndmask_b32_e64 v201, v215, 0, s[6:7]
	v_pk_add_f32 v[162:163], v[216:217], v[162:163]
	v_cndmask_b32_e64 v203, 0, v215, s[6:7]
	v_pk_add_f32 v[130:131], v[130:131], v[162:163]
	v_cndmask_b32_e64 v204, v217, 0, s[8:9]
	v_cndmask_b32_e64 v205, 0, v217, s[8:9]
	v_cvt_pk_bf16_f32 v198, v198, v199
	v_cvt_pk_bf16_f32 v199, v201, v204
	v_cvt_pk_bf16_f32 v200, v202, v200
	v_cvt_pk_bf16_f32 v201, v203, v205
	s_setprio 1
	s_waitcnt lgkmcnt(14)
	v_mfma_f32_16x16x32_bf16 v[44:47], v[158:161], v[198:201], v[44:47]
	s_waitcnt lgkmcnt(12)
	v_mfma_f32_16x16x32_bf16 v[40:43], v[166:169], v[198:201], v[40:43]
	s_waitcnt lgkmcnt(10)
	v_mfma_f32_16x16x32_bf16 v[36:39], v[170:173], v[198:201], v[36:39]
	s_waitcnt lgkmcnt(8)
	v_mfma_f32_16x16x32_bf16 v[32:35], v[174:177], v[198:201], v[32:35]
	s_setprio 0
	ds_read_b64 v[158:159], v181 offset:1072
	ds_read_b64 v[160:161], v181 offset:1104
	ds_read_b64 v[166:167], v218 offset:1328
	ds_read_b64 v[168:169], v218 offset:1360
	ds_read_b64 v[170:171], v219 offset:1584
	ds_read_b64 v[172:173], v219 offset:1616
	ds_read_b64 v[174:175], v220 offset:1072
	ds_read_b64 v[176:177], v220 offset:1104
	ds_read_b128 v[198:201], v119 offset:4608
	ds_read_b128 v[202:205], v119 offset:4672
	v_add_u32_e32 v119, v148, v151
	ds_read_b128 v[206:209], v119
	ds_read_b128 v[210:213], v119 offset:64
	v_add_u32_e32 v119, s66, v154
	v_add_u32_sdwa v162, s66, v144 dst_sel:DWORD dst_unused:UNUSED_PAD src0_sel:DWORD src1_sel:BYTE_1
	v_add_u32_sdwa v163, s66, v145 dst_sel:DWORD dst_unused:UNUSED_PAD src0_sel:DWORD src1_sel:BYTE_2
	v_add_u32_sdwa v178, s66, v145 dst_sel:DWORD dst_unused:UNUSED_PAD src0_sel:DWORD src1_sel:BYTE_3
	ds_read_b32 v119, v119 offset:41856
	ds_read_b32 v179, v162 offset:41856
	ds_read_b32 v214, v163 offset:41856
	ds_read_b32 v215, v178 offset:41856
	s_setprio 1
	s_waitcnt vmcnt(3) lgkmcnt(15)
	v_mfma_f32_16x16x32_bf16 v[182:185], v[182:185], v[96:99], 0
	s_waitcnt vmcnt(2)
	v_mfma_f32_16x16x32_bf16 v[182:185], v[186:189], v[100:103], v[182:185]
	v_mfma_f32_16x16x32_bf16 v[186:189], v[190:193], v[96:99], 0
	v_mfma_f32_16x16x32_bf16 v[186:189], v[194:197], v[100:103], v[186:189]
	s_setprio 0
	s_nop 6
	v_cndmask_b32_e64 v162, v186, v182, s[2:3]
	v_add_f32_e32 v136, v136, v162
	v_exp_f32_e32 v162, v136
	v_cndmask_b32_e64 v136, v187, v183, s[4:5]
	v_cndmask_b32_e64 v183, v184, v188, s[22:23]
	s_waitcnt lgkmcnt(15)
	v_add_f32_e32 v165, v165, v183
	v_exp_f32_e32 v190, v165
	v_cndmask_b32_e64 v165, v185, v189, s[24:25]
	v_add_f32_e32 v136, v223, v136
	s_waitcnt lgkmcnt(15)
	v_add_f32_e32 v165, v224, v165
	v_exp_f32_e32 v178, v136
	v_exp_f32_e32 v192, v165
	v_cndmask_b32_e64 v183, v190, 0, s[22:23]
	v_cndmask_b32_e64 v185, 0, v190, s[22:23]
	v_cndmask_b32_e64 v182, 0, v178, s[4:5]
	v_cndmask_b32_e64 v184, v192, 0, s[24:25]
	v_cndmask_b32_e64 v136, 0, v162, s[2:3]
	v_cndmask_b32_e64 v163, v162, 0, s[2:3]
	v_cndmask_b32_e64 v165, v178, 0, s[4:5]
	v_cndmask_b32_e64 v186, 0, v192, s[24:25]
	v_cvt_pk_bf16_f32 v182, v136, v182
	v_cvt_pk_bf16_f32 v183, v183, v184
	v_cvt_pk_bf16_f32 v184, v163, v165
	v_cvt_pk_bf16_f32 v185, v185, v186
	s_setprio 1
	s_waitcnt lgkmcnt(14)
	v_mfma_f32_16x16x32_bf16 v[28:31], v[158:161], v[182:185], v[28:31]
	s_waitcnt lgkmcnt(12)
	v_mfma_f32_16x16x32_bf16 v[24:27], v[166:169], v[182:185], v[24:27]
	s_waitcnt lgkmcnt(10)
	v_mfma_f32_16x16x32_bf16 v[20:23], v[170:173], v[182:185], v[20:23]
	s_waitcnt lgkmcnt(8)
	v_mfma_f32_16x16x32_bf16 v[16:19], v[174:177], v[182:185], v[16:19]
	s_setprio 0
	ds_read_b64 v[158:159], v220 offset:1088
	ds_read_b64 v[160:161], v220 offset:1120
	ds_read_b64 v[166:167], v219 offset:1600
	ds_read_b64 v[168:169], v219 offset:1632
	ds_read_b64 v[170:171], v218 offset:1344
	ds_read_b64 v[172:173], v218 offset:1376
	ds_read_b64 v[174:175], v181 offset:1088
	ds_read_b64 v[176:177], v181 offset:1120
	s_setprio 1
	s_waitcnt vmcnt(1) lgkmcnt(15)
	v_mfma_f32_16x16x32_bf16 v[182:185], v[198:201], v[104:107], 0
	s_waitcnt lgkmcnt(13)
	v_mfma_f32_16x16x32_bf16 v[186:189], v[206:209], v[104:107], 0
	s_waitcnt vmcnt(0)
	v_mfma_f32_16x16x32_bf16 v[182:185], v[202:205], v[108:111], v[182:185]
	s_waitcnt lgkmcnt(12)
	v_mfma_f32_16x16x32_bf16 v[186:189], v[210:213], v[108:111], v[186:189]
	s_setprio 0
	s_nop 6
	v_cndmask_b32_e64 v136, v182, v186, s[26:27]
	s_waitcnt lgkmcnt(11)
	v_add_f32_e32 v119, v119, v136
	v_exp_f32_e32 v163, v119
	v_cndmask_b32_e64 v119, v183, v187, s[28:29]
	v_cndmask_b32_e64 v181, v184, v188, s[30:31]
	s_waitcnt lgkmcnt(10)
	v_add_f32_e32 v119, v179, v119
	s_waitcnt lgkmcnt(9)
	v_add_f32_e32 v181, v214, v181
	v_exp_f32_e32 v179, v119
	v_exp_f32_e32 v191, v181
	v_cndmask_b32_e64 v181, v185, v189, s[34:35]
	s_waitcnt lgkmcnt(8)
	v_add_f32_e32 v181, v215, v181
	v_exp_f32_e32 v193, v181
	v_cndmask_b32_e64 v119, v163, 0, s[26:27]
	v_cndmask_b32_e64 v136, 0, v163, s[26:27]
	v_pk_add_f32 v[162:163], v[162:163], 0 op_sel_hi:[1,0]
	v_cndmask_b32_e64 v183, v191, 0, s[30:31]
	v_pk_add_f32 v[162:163], v[178:179], v[162:163]
	v_cndmask_b32_e64 v185, 0, v191, s[30:31]
	v_pk_add_f32 v[162:163], v[190:191], v[162:163]
	v_cndmask_b32_e64 v184, v193, 0, s[34:35]
	v_pk_add_f32 v[162:163], v[192:193], v[162:163]
	v_cndmask_b32_e64 v165, v179, 0, s[28:29]
	v_pk_add_f32 v[124:125], v[124:125], v[162:163]
	v_cndmask_b32_e64 v181, 0, v179, s[28:29]
	v_cndmask_b32_e64 v186, 0, v193, s[34:35]
	v_cvt_pk_bf16_f32 v182, v119, v165
	v_cvt_pk_bf16_f32 v183, v183, v184
	v_cvt_pk_bf16_f32 v184, v136, v181
	v_cvt_pk_bf16_f32 v185, v185, v186
	s_setprio 1
	s_waitcnt lgkmcnt(0)
	v_mfma_f32_16x16x32_bf16 v[12:15], v[174:177], v[182:185], v[12:15]
	v_mfma_f32_16x16x32_bf16 v[8:11], v[170:173], v[182:185], v[8:11]
	v_mfma_f32_16x16x32_bf16 v[4:7], v[166:169], v[182:185], v[4:7]
	v_mfma_f32_16x16x32_bf16 v[0:3], v[158:161], v[182:185], v[0:3]
	s_setprio 0
.LBB0_491:
	s_cmp_lt_u32 s68, s93
	s_cselect_b64 s[64:65], -1, 0
	s_cmp_ge_u32 s68, s93
	s_cbranch_scc1 .LBB0_493
	s_waitcnt vmcnt(1)
	ds_write_b128 v225, v[72:75] offset:18432
	s_waitcnt vmcnt(0)
	ds_write_b128 v157, v[76:79] offset:27648

.LBB0_496:
	s_add_i32 s64, s48, -2
	s_cmp_ge_u32 s64, s38
	s_cselect_b64 s[68:69], -1, 0
	s_cmp_lt_u32 s64, s39
	s_cselect_b64 s[94:95], -1, 0
	s_and_b64 s[68:69], s[68:69], s[94:95]
	s_andn2_b64 vcc, exec, s[68:69]
	s_cbranch_vccnz .LBB0_498
	v_add_u32_e32 v178, v150, v149
	v_add_u32_e32 v181, 0x6800, v178
	v_add_u32_e32 v218, 0x7000, v178
	v_add_u32_e32 v219, 0x7800, v178
	v_add_u32_e32 v178, v150, v151
	v_add_u32_e32 v119, v148, v149
	v_add_u32_e32 v229, v228, v149
	v_add_u32_e32 v136, s66, v152
	v_add_u32_sdwa v163, s66, v143 dst_sel:DWORD dst_unused:UNUSED_PAD src0_sel:DWORD src1_sel:BYTE_2
	v_add_u32_sdwa v165, s66, v143 dst_sel:DWORD dst_unused:UNUSED_PAD src0_sel:DWORD src1_sel:BYTE_3
	v_add_u32_e32 v220, 0x6800, v178
	v_add_u32_sdwa v179, s66, v141 dst_sel:DWORD dst_unused:UNUSED_PAD src0_sel:DWORD src1_sel:BYTE_1
	ds_read_b128 v[158:161], v119 offset:18432
	ds_read_b128 v[166:169], v119 offset:18496
	ds_read_b128 v[170:173], v119 offset:20736
	ds_read_b128 v[174:177], v119 offset:20800
	v_add_u32_e32 v162, s66, v153
	ds_read_b64 v[182:183], v181 offset:1024
	ds_read_b64 v[184:185], v181 offset:1056
	ds_read_b64 v[186:187], v218 offset:1280
	ds_read_b64 v[188:189], v218 offset:1312
	ds_read_b64 v[190:191], v219 offset:1536
	ds_read_b64 v[192:193], v219 offset:1568
	ds_read_b64 v[194:195], v220 offset:1024
	ds_read_b64 v[196:197], v220 offset:1056
	ds_read_b128 v[198:201], v229 offset:19584
	ds_read_b128 v[202:205], v229 offset:19648
	ds_read_b128 v[206:209], v229 offset:21888
	ds_read_b128 v[210:213], v229 offset:21952
	v_add_u32_e32 v178, s66, v155
	v_add_u32_sdwa v214, s66, v142 dst_sel:DWORD dst_unused:UNUSED_PAD src0_sel:DWORD src1_sel:BYTE_2
	v_add_u32_sdwa v215, s66, v142 dst_sel:DWORD dst_unused:UNUSED_PAD src0_sel:DWORD src1_sel:BYTE_3
	ds_read_b32 v136, v136 offset:41984
	ds_read_b32 v216, v162 offset:41984
	ds_read_b32 v163, v163 offset:41984
	ds_read_b32 v165, v165 offset:41984
	ds_read_b32 v217, v178 offset:41984
	ds_read_b32 v179, v179 offset:41984
	ds_read_b32 v221, v214 offset:41984
	ds_read_b32 v222, v215 offset:41984
	s_setprio 1
	s_waitcnt vmcnt(7) lgkmcnt(15)
	v_mfma_f32_16x16x32_bf16 v[158:161], v[158:161], v[80:83], 0
	s_waitcnt vmcnt(6)
	v_mfma_f32_16x16x32_bf16 v[158:161], v[166:169], v[84:87], v[158:161]
	v_mfma_f32_16x16x32_bf16 v[166:169], v[170:173], v[80:83], 0
	v_mfma_f32_16x16x32_bf16 v[166:169], v[174:177], v[84:87], v[166:169]
	s_setprio 0
	s_nop 6
	v_cndmask_b32_e64 v158, v166, v158, s[20:21]
	s_waitcnt lgkmcnt(7)
	v_add_f32_e32 v136, v136, v158
	v_exp_f32_e32 v162, v136
	v_cndmask_b32_e64 v136, v159, v167, s[10:11]
	v_cndmask_b32_e64 v159, v160, v168, s[12:13]
	s_waitcnt lgkmcnt(5)
	v_add_f32_e32 v159, v163, v159
	v_add_f32_e32 v136, v216, v136
	v_exp_f32_e32 v214, v159
	v_cndmask_b32_e64 v159, v161, v169, s[14:15]
	v_exp_f32_e32 v178, v136
	s_waitcnt lgkmcnt(4)
	v_add_f32_e32 v159, v165, v159
	v_exp_f32_e32 v216, v159
	v_cndmask_b32_e64 v159, v214, 0, s[12:13]
	v_cndmask_b32_e64 v158, v178, 0, s[10:11]
	v_cndmask_b32_e64 v160, 0, v178, s[10:11]
	v_cndmask_b32_e64 v161, 0, v214, s[12:13]
	v_cndmask_b32_e64 v136, 0, v162, s[20:21]
	v_cndmask_b32_e64 v166, v162, 0, s[20:21]
	v_cndmask_b32_e64 v163, v216, 0, s[14:15]
	v_cndmask_b32_e64 v165, 0, v216, s[14:15]
	v_cvt_pk_bf16_f32 v158, v136, v158
	v_cvt_pk_bf16_f32 v159, v159, v163
	v_cvt_pk_bf16_f32 v160, v166, v160
	v_cvt_pk_bf16_f32 v161, v161, v165
	s_setprio 1
	v_mfma_f32_16x16x32_bf16 v[60:63], v[182:185], v[158:161], v[60:63]
	v_mfma_f32_16x16x32_bf16 v[56:59], v[186:189], v[158:161], v[56:59]
	v_mfma_f32_16x16x32_bf16 v[52:55], v[190:193], v[158:161], v[52:55]
	v_mfma_f32_16x16x32_bf16 v[48:51], v[194:197], v[158:161], v[48:51]
	s_setprio 0
	ds_read_b64 v[158:159], v181 offset:1040
	ds_read_b64 v[160:161], v181 offset:1072
	ds_read_b64 v[166:167], v218 offset:1296
	ds_read_b64 v[168:169], v218 offset:1328
	ds_read_b64 v[170:171], v219 offset:1552
	ds_read_b64 v[172:173], v219 offset:1584
	ds_read_b64 v[174:175], v220 offset:1040
	ds_read_b64 v[176:177], v220 offset:1072
	ds_read_b128 v[182:185], v229 offset:21888
	ds_read_b128 v[186:189], v229 offset:21952
	ds_read_b128 v[190:193], v229 offset:24192
	ds_read_b128 v[194:197], v229 offset:24256
	v_add_u32_e32 v136, s66, v156
	v_add_u32_sdwa v165, s66, v140 dst_sel:DWORD dst_unused:UNUSED_PAD src0_sel:DWORD src1_sel:BYTE_2
	v_add_u32_sdwa v163, s66, v139 dst_sel:DWORD dst_unused:UNUSED_PAD src0_sel:DWORD src1_sel:BYTE_1
	v_add_u32_sdwa v215, s66, v140 dst_sel:DWORD dst_unused:UNUSED_PAD src0_sel:DWORD src1_sel:BYTE_3
	ds_read_b32 v136, v136 offset:41984
	ds_read_b32 v223, v163 offset:41984
	ds_read_b32 v165, v165 offset:41984
	ds_read_b32 v224, v215 offset:41984
	s_setprio 1
	s_waitcnt vmcnt(5)
	v_mfma_f32_16x16x32_bf16 v[198:201], v[198:201], v[88:91], 0
	s_waitcnt vmcnt(4)
	v_mfma_f32_16x16x32_bf16 v[198:201], v[202:205], v[92:95], v[198:201]
	v_mfma_f32_16x16x32_bf16 v[202:205], v[206:209], v[88:91], 0
	v_mfma_f32_16x16x32_bf16 v[202:205], v[210:213], v[92:95], v[202:205]
	s_setprio 0
	s_nop 6
	v_cndmask_b32_e64 v163, v198, v202, s[16:17]
	s_waitcnt lgkmcnt(15)
	v_add_f32_e32 v163, v217, v163
	v_cndmask_b32_e64 v198, v199, v203, s[18:19]
	v_cndmask_b32_e64 v200, v200, v204, s[6:7]
	v_exp_f32_e32 v163, v163
	v_add_f32_e32 v179, v179, v198
	s_waitcnt lgkmcnt(15)
	v_add_f32_e32 v200, v221, v200
	v_exp_f32_e32 v179, v179
	v_exp_f32_e32 v215, v200
	v_cndmask_b32_e64 v200, v201, v205, s[8:9]
	s_waitcnt lgkmcnt(15)
	v_add_f32_e32 v200, v222, v200
	v_exp_f32_e32 v217, v200
	v_cndmask_b32_e64 v198, v163, 0, s[16:17]
	v_cndmask_b32_e64 v202, 0, v163, s[16:17]
	v_pk_add_f32 v[162:163], v[162:163], 0 op_sel_hi:[1,0]
	v_cndmask_b32_e64 v199, v179, 0, s[18:19]
	v_pk_add_f32 v[162:163], v[178:179], v[162:163]
	v_cndmask_b32_e64 v200, 0, v179, s[18:19]
	v_pk_add_f32 v[162:163], v[214:215], v[162:163]
	v_cndmask_b32_e64 v201, v215, 0, s[6:7]
	v_pk_add_f32 v[162:163], v[216:217], v[162:163]
	v_cndmask_b32_e64 v203, 0, v215, s[6:7]
	v_pk_add_f32 v[130:131], v[130:131], v[162:163]
	v_cndmask_b32_e64 v204, v217, 0, s[8:9]
	v_cndmask_b32_e64 v205, 0, v217, s[8:9]
	v_cvt_pk_bf16_f32 v198, v198, v199
	v_cvt_pk_bf16_f32 v199, v201, v204
	v_cvt_pk_bf16_f32 v200, v202, v200
	v_cvt_pk_bf16_f32 v201, v203, v205
	s_setprio 1
	s_waitcnt lgkmcnt(14)
	v_mfma_f32_16x16x32_bf16 v[44:47], v[158:161], v[198:201], v[44:47]
	s_waitcnt lgkmcnt(12)
	v_mfma_f32_16x16x32_bf16 v[40:43], v[166:169], v[198:201], v[40:43]
	s_waitcnt lgkmcnt(10)
	v_mfma_f32_16x16x32_bf16 v[36:39], v[170:173], v[198:201], v[36:39]
	s_waitcnt lgkmcnt(8)
	v_mfma_f32_16x16x32_bf16 v[32:35], v[174:177], v[198:201], v[32:35]
	s_setprio 0
	ds_read_b64 v[158:159], v181 offset:1072
	ds_read_b64 v[160:161], v181 offset:1104
	ds_read_b64 v[166:167], v218 offset:1328
	ds_read_b64 v[168:169], v218 offset:1360
	ds_read_b64 v[170:171], v219 offset:1584
	ds_read_b64 v[172:173], v219 offset:1616
	ds_read_b64 v[174:175], v220 offset:1072
	ds_read_b64 v[176:177], v220 offset:1104
	ds_read_b128 v[198:201], v119 offset:23040
	ds_read_b128 v[202:205], v119 offset:23104
	v_add_u32_e32 v119, v148, v151
	ds_read_b128 v[206:209], v119 offset:18432
	ds_read_b128 v[210:213], v119 offset:18496
	v_add_u32_e32 v119, s66, v154
	v_add_u32_sdwa v162, s66, v144 dst_sel:DWORD dst_unused:UNUSED_PAD src0_sel:DWORD src1_sel:BYTE_1
	v_add_u32_sdwa v163, s66, v145 dst_sel:DWORD dst_unused:UNUSED_PAD src0_sel:DWORD src1_sel:BYTE_2
	v_add_u32_sdwa v178, s66, v145 dst_sel:DWORD dst_unused:UNUSED_PAD src0_sel:DWORD src1_sel:BYTE_3
	ds_read_b32 v119, v119 offset:41984
	ds_read_b32 v179, v162 offset:41984
	ds_read_b32 v214, v163 offset:41984
	ds_read_b32 v215, v178 offset:41984
	s_setprio 1
	s_waitcnt vmcnt(3) lgkmcnt(15)
	v_mfma_f32_16x16x32_bf16 v[182:185], v[182:185], v[96:99], 0
	s_waitcnt vmcnt(2)
	v_mfma_f32_16x16x32_bf16 v[182:185], v[186:189], v[100:103], v[182:185]
	v_mfma_f32_16x16x32_bf16 v[186:189], v[190:193], v[96:99], 0
	v_mfma_f32_16x16x32_bf16 v[186:189], v[194:197], v[100:103], v[186:189]
	s_setprio 0
	s_nop 6
	v_cndmask_b32_e64 v162, v186, v182, s[2:3]
	v_add_f32_e32 v136, v136, v162
	v_exp_f32_e32 v162, v136
	v_cndmask_b32_e64 v136, v187, v183, s[4:5]
	v_cndmask_b32_e64 v183, v184, v188, s[22:23]
	s_waitcnt lgkmcnt(15)
	v_add_f32_e32 v165, v165, v183
	v_exp_f32_e32 v190, v165
	v_cndmask_b32_e64 v165, v185, v189, s[24:25]
	v_add_f32_e32 v136, v223, v136
	s_waitcnt lgkmcnt(15)
	v_add_f32_e32 v165, v224, v165
	v_exp_f32_e32 v178, v136
	v_exp_f32_e32 v192, v165
	v_cndmask_b32_e64 v183, v190, 0, s[22:23]
	v_cndmask_b32_e64 v185, 0, v190, s[22:23]
	v_cndmask_b32_e64 v182, 0, v178, s[4:5]
	v_cndmask_b32_e64 v184, v192, 0, s[24:25]
	v_cndmask_b32_e64 v136, 0, v162, s[2:3]
	v_cndmask_b32_e64 v163, v162, 0, s[2:3]
	v_cndmask_b32_e64 v165, v178, 0, s[4:5]
	v_cndmask_b32_e64 v186, 0, v192, s[24:25]
	v_cvt_pk_bf16_f32 v182, v136, v182
	v_cvt_pk_bf16_f32 v183, v183, v184
	v_cvt_pk_bf16_f32 v184, v163, v165
	v_cvt_pk_bf16_f32 v185, v185, v186
	s_setprio 1
	s_waitcnt lgkmcnt(14)
	v_mfma_f32_16x16x32_bf16 v[28:31], v[158:161], v[182:185], v[28:31]
	s_waitcnt lgkmcnt(12)
	v_mfma_f32_16x16x32_bf16 v[24:27], v[166:169], v[182:185], v[24:27]
	s_waitcnt lgkmcnt(10)
	v_mfma_f32_16x16x32_bf16 v[20:23], v[170:173], v[182:185], v[20:23]
	s_waitcnt lgkmcnt(8)
	v_mfma_f32_16x16x32_bf16 v[16:19], v[174:177], v[182:185], v[16:19]
	s_setprio 0
	ds_read_b64 v[158:159], v220 offset:1088
	ds_read_b64 v[160:161], v220 offset:1120
	ds_read_b64 v[166:167], v219 offset:1600
	ds_read_b64 v[168:169], v219 offset:1632
	ds_read_b64 v[170:171], v218 offset:1344
	ds_read_b64 v[172:173], v218 offset:1376
	ds_read_b64 v[174:175], v181 offset:1088
	ds_read_b64 v[176:177], v181 offset:1120
	s_setprio 1
	s_waitcnt vmcnt(1) lgkmcnt(15)
	v_mfma_f32_16x16x32_bf16 v[182:185], v[198:201], v[104:107], 0
	s_waitcnt lgkmcnt(13)
	v_mfma_f32_16x16x32_bf16 v[186:189], v[206:209], v[104:107], 0
	s_waitcnt vmcnt(0)
	v_mfma_f32_16x16x32_bf16 v[182:185], v[202:205], v[108:111], v[182:185]
	s_waitcnt lgkmcnt(12)
	v_mfma_f32_16x16x32_bf16 v[186:189], v[210:213], v[108:111], v[186:189]
	s_setprio 0
	s_nop 6
	v_cndmask_b32_e64 v136, v182, v186, s[26:27]
	s_waitcnt lgkmcnt(11)
	v_add_f32_e32 v119, v119, v136
	v_exp_f32_e32 v163, v119
	v_cndmask_b32_e64 v119, v183, v187, s[28:29]
	v_cndmask_b32_e64 v181, v184, v188, s[30:31]
	s_waitcnt lgkmcnt(10)
	v_add_f32_e32 v119, v179, v119
	s_waitcnt lgkmcnt(9)
	v_add_f32_e32 v181, v214, v181
	v_exp_f32_e32 v179, v119
	v_exp_f32_e32 v191, v181
	v_cndmask_b32_e64 v181, v185, v189, s[34:35]
	s_waitcnt lgkmcnt(8)
	v_add_f32_e32 v181, v215, v181
	v_exp_f32_e32 v193, v181
	v_cndmask_b32_e64 v119, v163, 0, s[26:27]
	v_cndmask_b32_e64 v136, 0, v163, s[26:27]
	v_pk_add_f32 v[162:163], v[162:163], 0 op_sel_hi:[1,0]
	v_cndmask_b32_e64 v183, v191, 0, s[30:31]
	v_pk_add_f32 v[162:163], v[178:179], v[162:163]
	v_cndmask_b32_e64 v185, 0, v191, s[30:31]
	v_pk_add_f32 v[162:163], v[190:191], v[162:163]
	v_cndmask_b32_e64 v184, v193, 0, s[34:35]
	v_pk_add_f32 v[162:163], v[192:193], v[162:163]
	v_cndmask_b32_e64 v165, v179, 0, s[28:29]
	v_pk_add_f32 v[124:125], v[124:125], v[162:163]
	v_cndmask_b32_e64 v181, 0, v179, s[28:29]
	v_cndmask_b32_e64 v186, 0, v193, s[34:35]
	v_cvt_pk_bf16_f32 v182, v119, v165
	v_cvt_pk_bf16_f32 v183, v183, v184
	v_cvt_pk_bf16_f32 v184, v136, v181
	v_cvt_pk_bf16_f32 v185, v185, v186
	s_setprio 1
	s_waitcnt lgkmcnt(0)
	v_mfma_f32_16x16x32_bf16 v[12:15], v[174:177], v[182:185], v[12:15]
	v_mfma_f32_16x16x32_bf16 v[8:11], v[170:173], v[182:185], v[8:11]
	v_mfma_f32_16x16x32_bf16 v[4:7], v[166:169], v[182:185], v[4:7]
	v_mfma_f32_16x16x32_bf16 v[0:3], v[158:161], v[182:185], v[0:3]
	s_setprio 0
.LBB0_498:
	s_cmp_ge_u32 s64, s93
	s_cbranch_scc1 .LBB0_485
	s_waitcnt vmcnt(1)
	ds_write_b128 v225, v[64:67]
	s_waitcnt vmcnt(0)
	ds_write_b128 v157, v[68:71] offset:9216
	s_branch .LBB0_485

.LBB0_572:
	s_or_b64 exec, exec, s[2:3]
	s_abs_i32 s0, s84
	v_cvt_f32_u32_e32 v0, s0
	s_sub_i32 s3, 0, s0
	s_add_i32 s1, s84, 0x4ff
	s_xor_b32 s2, s1, s84
	v_rcp_iflag_f32_e32 v0, v0
	s_abs_i32 s1, s1
	s_ashr_i32 s2, s2, 31
	v_and_b32_e32 v137, 15, v164
	v_mul_f32_e32 v0, 0x4f7ffffe, v0
	v_cvt_u32_f32_e32 v0, v0
	s_mov_b32 s53, 0
	s_waitcnt lgkmcnt(0)
	s_barrier
	v_readfirstlane_b32 s4, v0
	s_mul_i32 s3, s3, s4
	s_mul_hi_u32 s3, s4, s3
	s_add_i32 s4, s4, s3
	s_mul_hi_u32 s3, s1, s4
	s_mul_i32 s4, s3, s0
	s_sub_i32 s1, s1, s4
	s_add_i32 s4, s3, 1
	s_sub_i32 s5, s1, s0
	s_cmp_ge_u32 s1, s0
	s_cselect_b32 s3, s4, s3
	s_cselect_b32 s1, s5, s1
	s_add_i32 s4, s3, 1
	s_cmp_ge_u32 s1, s0
	s_cselect_b32 s0, s4, s3
	s_xor_b32 s0, s0, s2
	s_sub_i32 s0, s0, s2
	s_mul_i32 s1, s0, s33
	s_min_i32 s0, s0, 0x100000
	s_add_i32 s51, s1, 3
	s_add_i32 s1, s1, s0
	s_min_i32 s74, s1, 0x500
	s_cmp_lt_i32 s51, s74
	s_cbranch_scc0 .LBB0_609
	v_lshrrev_b32_e32 v1, 2, v180
	v_and_b32_e32 v2, 12, v1
	v_add_u32_e32 v13, 26, v2
	v_add_u32_e32 v14, 24, v137
	v_sub_u32_e32 v15, v13, v14
	v_mov_b32_e32 v16, 0x400
	v_cmp_gt_u32_e32 vcc, 16, v15
	v_mov_b32_e32 v18, 0x800
	v_mov_b32_e32 v19, 0x200
	v_cndmask_b32_e32 v15, 0, v16, vcc
	v_add_u32_e32 v16, 27, v2
	v_sub_u32_e32 v17, v16, v14
	v_cmp_gt_u32_e64 s[0:1], 16, v17
	v_sub_u32_e64 v0, v137, 8 clamp
	v_or_b32_e32 v4, 1, v2
	v_cndmask_b32_e64 v17, 0, v18, s[0:1]
	v_add_u32_e32 v18, 25, v2
	v_sub_u32_e32 v14, v18, v14
	v_cmp_gt_u32_e64 s[4:5], 16, v14
	v_or_b32_e32 v6, 2, v2
	v_or_b32_e32 v8, 3, v1
	v_add_u32_e32 v9, 8, v137
	v_add_u32_e32 v11, 9, v2
	v_cndmask_b32_e64 v14, 0, v19, s[4:5]
	v_add_u32_e32 v19, 10, v2
	v_add_u32_e32 v21, 11, v2
	v_sub_u32_e32 v3, v2, v0
	v_sub_u32_e32 v5, v4, v0
	v_sub_u32_e32 v7, v6, v0
	v_sub_u32_e32 v0, v8, v0
	v_sub_u32_e32 v10, v2, v137
	v_sub_u32_e32 v12, v11, v9
	v_sub_u32_e32 v20, v19, v9
	v_sub_u32_e32 v9, v21, v9
	v_mov_b32_e32 v22, 0x80
	v_cmp_lt_u32_e64 s[8:9], 15, v9
	v_cmp_lt_u32_e64 s[14:15], 15, v0
	v_cmp_lt_u32_e64 s[16:17], 15, v10
	v_cmp_gt_u32_e64 s[2:3], 16, v10
	v_cmp_lt_u32_e64 s[6:7], 15, v20
	v_cndmask_b32_e64 v9, v22, 0, s[8:9]
	v_cmp_lt_u32_e64 s[10:11], 15, v5
	v_cndmask_b32_e64 v0, 8, 0, s[14:15]
	v_cndmask_b32_e64 v10, 16, 0, s[16:17]
	v_cndmask_b32_e64 v20, 64, 0, s[6:7]
	v_cndmask_b32_e64 v5, 2, 0, s[10:11]
	v_cmp_lt_u32_e64 s[12:13], 15, v7
	v_cmp_lt_u32_e64 s[18:19], 15, v12
	v_or3_b32 v0, v0, v10, v9
	v_or_b32_e32 v15, v15, v17
	v_mov_b32_e32 v17, 0x100
	v_cndmask_b32_e64 v7, 4, 0, s[12:13]
	v_cndmask_b32_e64 v12, 32, 0, s[18:19]
	v_or3_b32 v0, v5, v20, v0
	v_cndmask_b32_e64 v17, 0, v17, s[2:3]
	v_or3_b32 v0, v7, v12, v0
	v_or3_b32 v5, v17, v0, v14
	v_add_u32_e32 v0, 42, v2
	v_add_u32_e32 v12, 43, v2
	v_add_u32_e32 v17, 41, v2
	v_cndmask_b32_e32 v0, v0, v13, vcc
	v_or_b32_e32 v9, 32, v137
	v_cndmask_b32_e64 v12, v12, v16, s[0:1]
	v_cndmask_b32_e64 v17, v17, v18, s[4:5]
	v_sub_u32_e32 v0, v0, v9
	v_sub_u32_e32 v12, v12, v9
	v_sub_u32_e32 v17, v17, v9
	v_cndmask_b32_e64 v22, 40, 24, s[2:3]
	v_sub_u32_e32 v9, v2, v9
	v_mov_b32_e32 v20, 0x3c00
	v_add_u32_e32 v9, v9, v22
	v_mov_b32_e32 v10, 0x3c0000
	v_bfrev_b32_e32 v14, 60
	v_lshl_add_u32 v17, v17, 10, v20
	v_lshl_add_u32 v9, v9, 2, 60
	v_lshl_add_u32 v0, v0, 18, v10
	v_lshl_add_u32 v12, v12, 26, v14
	v_or_b32_e32 v140, v17, v9
	v_or3_b32 v141, v0, v12, v140
	v_cndmask_b32_e64 v0, v19, v13, s[6:7]
	v_or_b32_e32 v9, 16, v137
	v_cndmask_b32_e64 v12, v21, v16, s[8:9]
	v_cndmask_b32_e64 v11, v11, v18, s[18:19]
	v_sub_u32_e32 v0, v0, v9
	v_sub_u32_e32 v12, v12, v9
	v_sub_u32_e32 v11, v11, v9
	v_cndmask_b32_e64 v13, 8, 24, s[16:17]
	v_sub_u32_e32 v9, v2, v9
	v_add_u32_e32 v9, v9, v13
	v_lshl_add_u32 v11, v11, 10, v20
	v_lshl_add_u32 v9, v9, 2, 60
	v_lshl_add_u32 v0, v0, 18, v10
	v_lshl_add_u32 v12, v12, 26, v14
	v_or_b32_e32 v142, v11, v9
	v_or3_b32 v143, v0, v12, v142
	v_or_b32_e32 v0, 18, v2
	v_cndmask_b32_e64 v0, v6, v0, s[12:13]
	v_or_b32_e32 v6, 19, v1
	v_cndmask_b32_e64 v6, v8, v6, s[14:15]
	v_or_b32_e32 v8, 17, v2
	v_cndmask_b32_e64 v4, v4, v8, s[10:11]
	v_or_b32_e32 v8, 16, v2
	v_cmp_gt_u32_e64 s[20:21], 16, v3
	v_sub_u32_e32 v4, v4, v137
	v_sub_u32_e32 v0, v0, v137
	v_cndmask_b32_e64 v3, v8, v2, s[20:21]
	v_sub_u32_e32 v3, v3, v137
	v_sub_u32_e32 v6, v6, v137
	v_lshl_add_u32 v4, v4, 10, v20
	v_lshl_add_u32 v3, v3, 2, 60
	v_lshl_add_u32 v0, v0, 18, v10
	v_lshl_add_u32 v6, v6, 26, v14
	v_or_b32_e32 v4, v4, v3
	v_or3_b32 v144, v0, v6, v4
	v_or_b32_e32 v6, 48, v180
	v_add_u32_e32 v8, -8, v6
	v_or_b32_e32 v0, 35, v1
	v_min_u32_e32 v8, 48, v8
	v_sub_u32_e32 v9, v0, v8
	v_mov_b32_e32 v11, 0x8000
	v_cmp_gt_u32_e32 vcc, 16, v9
	v_mov_b32_e32 v16, 0x4000
	v_or_b32_e32 v1, 51, v1
	v_cndmask_b32_e32 v9, 0, v11, vcc
	v_or_b32_e32 v11, 34, v2
	v_sub_u32_e32 v12, v11, v8
	v_cmp_gt_u32_e64 s[0:1], 16, v12
	v_mov_b32_e32 v18, 0x2000
	v_cndmask_b32_e32 v0, v1, v0, vcc
	v_cndmask_b32_e64 v12, 0, v16, s[0:1]
	v_or_b32_e32 v16, 33, v2
	v_sub_u32_e32 v17, v16, v8
	v_cmp_gt_u32_e64 s[22:23], 16, v17
	v_or_b32_e32 v1, 50, v2
	v_cndmask_b32_e64 v1, v1, v11, s[0:1]
	v_cndmask_b32_e64 v17, 0, v18, s[22:23]
	v_or_b32_e32 v18, 32, v2
	v_sub_u32_e32 v8, v18, v8
	v_sub_u32_e32 v1, v1, v6
	v_cmp_gt_u32_e64 s[24:25], 16, v8
	v_lshl_add_u32 v1, v1, 18, v10
	v_or_b32_e32 v10, 49, v2
	v_or_b32_e32 v2, 48, v2
	v_cndmask_b32_e64 v10, v10, v16, s[22:23]
	v_cndmask_b32_e64 v2, v2, v18, s[24:25]
	v_sub_u32_e32 v10, v10, v6
	v_sub_u32_e32 v2, v2, v6
	v_sub_u32_e32 v0, v0, v6
	v_lshl_add_u32 v10, v10, 10, v20
	v_lshl_add_u32 v2, v2, 2, 60
	v_lshl_add_u32 v0, v0, 26, v14
	v_or_b32_e32 v145, v10, v2
	v_or3_b32 v146, v1, v0, v145
	v_and_b32_e32 v1, 7, v164
	v_mov_b32_e32 v19, 0x1000
	v_lshrrev_b32_e32 v147, 3, v164
	v_lshlrev_b32_e32 v114, 4, v1
	s_movk_i32 s0, 0x90
	s_movk_i32 s26, 0x400
	s_movk_i32 s27, 0x800
	v_cndmask_b32_e64 v8, 0, v19, s[24:25]
	v_lshlrev_b32_e32 v0, 3, v1
	v_lshrrev_b32_e32 v1, 4, v180
	v_mad_u32_u24 v10, v147, s0, v114
	s_add_u32 s0, s80, 0x11000000
	v_and_b32_e32 v112, 48, v180
	v_or_b32_e32 v7, v15, v5
	s_movk_i32 s29, 0x1000
	v_or_b32_e32 v8, v8, v17
	v_lshl_add_u32 v150, v1, 3, 0
	v_mul_u32_u24_e32 v151, 0x90, v6
	v_bitop3_b32 v6, v15, s26, v5 bitop3:0xc8
	v_bitop3_b32 v5, v15, s27, v5 bitop3:0xc8
	v_and_b32_e32 v152, 0xfc, v3
	v_and_b32_e32 v154, 0xfc, v2
	v_lshlrev_b32_e32 v2, 2, v1
	s_addc_u32 s1, s81, 0
	v_lshl_add_u32 v1, v13, 2, v112
	v_lshlrev_b32_e32 v3, 2, v137
	s_movk_i32 s28, 0x2000
	v_cmp_eq_u32_e64 s[24:25], 0, v5
	v_bitop3_b32 v5, v8, s29, v7 bitop3:0xc8
	s_add_u32 s60, s80, 0x50000
	v_sub_u32_e32 v1, v1, v3
	s_movk_i32 s30, 0x4000
	v_or_b32_e32 v17, v8, v7
	v_or_b32_e32 v9, v12, v9
	v_cmp_eq_u32_e64 s[26:27], 0, v5
	v_bitop3_b32 v5, v8, s28, v7 bitop3:0xc8
	s_addc_u32 s61, s81, 0
	v_add_u32_e32 v1, -4, v1
	s_mov_b32 s34, 0x8000
	v_cmp_eq_u32_e64 s[28:29], 0, v5
	v_bitop3_b32 v5, v9, s30, v17 bitop3:0xc8
	s_add_u32 s75, s80, 0x17000000
	v_and_b32_e32 v155, 0xfc, v1
	v_lshl_add_u32 v1, v22, 2, v112
	v_mov_b32_e32 v113, 0
	v_cmp_eq_u32_e64 s[30:31], 0, v5
	v_bitop3_b32 v5, v9, s34, v17 bitop3:0xc8
	s_addc_u32 s76, s81, 0
	v_sub_u32_e32 v1, v1, v3
	v_and_b32_e32 v11, 48, v164
	v_cmp_eq_u32_e64 s[34:35], 0, v5
	v_lshrrev_b32_e32 v153, 8, v4
	v_lshl_add_u64 v[4:5], s[80:81], 0, v[112:113]
	s_mov_b64 s[38:39], 0xc000000
	s_add_u32 s77, s80, 0x16000000
	v_add_u32_e32 v1, 0xffffffbc, v1
	v_add_u32_e32 v148, 0, v11
	v_mul_u32_u24_e32 v149, 0x90, v137
	v_cmp_eq_u32_e64 s[22:23], 0, v6
	v_cmp_gt_u32_e64 s[36:37], 16, v180
	v_lshl_add_u64 v[116:117], v[4:5], 0, s[38:39]
	s_addc_u32 s93, s81, 0
	v_mov_b32_e32 v115, v113
	v_and_b32_e32 v156, 0xfc, v1
	v_lshlrev_b32_e32 v112, 1, v0
	s_mov_b64 s[62:63], 0x100
	v_lshlrev_b32_e32 v118, 1, v2
	s_mov_b64 s[64:65], 0x39000000
	s_mov_b32 s94, 0x500000
	v_add_u32_e32 v157, 0, v10
	v_add_u32_e32 v226, 4, v147
	v_bfe_u32 v226, v226, 3, 1
	v_and_b32_e32 v227, 1, v164
	v_lshlrev_b32_e32 v227, 5, v227
	v_sub_u32_e32 v227, 16, v227
	v_mad_i32_i24 v225, v226, v227, v157
	v_add_u32_e32 v226, 4, v137
	v_bfe_u32 v226, v226, 3, 1
	v_lshlrev_b32_e32 v226, 4, v226
	v_xor_b32_e32 v148, v148, v226
	v_xor_b32_e32 v228, 16, v148
	s_branch .LBB0_575

.LBB0_584:
	s_add_i32 s73, s38, s92
	s_lshl_b32 s38, s73, 6
	s_add_i32 s38, s38, s39
	v_add_u32_e32 v128, s38, v137
	s_lshl_b32 s38, s69, 1
	s_mov_b32 s39, s53
	v_ashrrev_i32_e32 v129, 31, v128
	v_lshl_add_u64 v[0:1], v[116:117], 0, s[38:39]
	v_lshlrev_b64 v[2:3], 10, v[128:129]
	v_add_u32_e32 v126, 16, v128
	v_lshl_add_u64 v[2:3], v[0:1], 0, v[2:3]
	v_ashrrev_i32_e32 v127, 31, v126
	global_load_dwordx4 v[80:83], v[2:3], off
	global_load_dwordx4 v[84:87], v[2:3], off offset:64
	v_lshlrev_b64 v[2:3], 10, v[126:127]
	v_add_u32_e32 v122, 32, v128
	v_lshl_add_u64 v[2:3], v[0:1], 0, v[2:3]
	v_ashrrev_i32_e32 v123, 31, v122
	global_load_dwordx4 v[88:91], v[2:3], off
	global_load_dwordx4 v[92:95], v[2:3], off offset:64
	v_lshlrev_b64 v[2:3], 10, v[122:123]
	v_add_u32_e32 v120, 48, v128
	v_lshl_add_u64 v[2:3], v[0:1], 0, v[2:3]
	v_ashrrev_i32_e32 v121, 31, v120
	global_load_dwordx4 v[96:99], v[2:3], off
	global_load_dwordx4 v[100:103], v[2:3], off offset:64
	v_lshlrev_b64 v[2:3], 10, v[120:121]
	v_lshl_add_u64 v[0:1], v[0:1], 0, v[2:3]
	global_load_dwordx4 v[104:107], v[0:1], off
	global_load_dwordx4 v[108:111], v[0:1], off offset:64
	v_mov_b32_e32 v131, 0
	s_andn2_b64 vcc, exec, s[70:71]
	v_mov_b32_e32 v130, 0
	v_mov_b32_e32 v125, 0
	v_mov_b32_e32 v124, 0
	v_mov_b32_e32 v63, 0
	v_mov_b32_e32 v62, 0
	v_mov_b32_e32 v61, 0
	v_mov_b32_e32 v60, 0
	v_mov_b32_e32 v59, 0
	v_mov_b32_e32 v58, 0
	v_mov_b32_e32 v57, 0
	v_mov_b32_e32 v56, 0
	v_mov_b32_e32 v55, 0
	v_mov_b32_e32 v54, 0
	v_mov_b32_e32 v53, 0
	v_mov_b32_e32 v52, 0
	v_mov_b32_e32 v51, 0
	v_mov_b32_e32 v50, 0
	v_mov_b32_e32 v49, 0
	v_mov_b32_e32 v48, 0
	v_mov_b32_e32 v47, 0
	v_mov_b32_e32 v46, 0
	v_mov_b32_e32 v45, 0
	v_mov_b32_e32 v44, 0
	v_mov_b32_e32 v43, 0
	v_mov_b32_e32 v42, 0
	v_mov_b32_e32 v41, 0
	v_mov_b32_e32 v40, 0
	v_mov_b32_e32 v39, 0
	v_mov_b32_e32 v38, 0
	v_mov_b32_e32 v37, 0
	v_mov_b32_e32 v36, 0
	v_mov_b32_e32 v35, 0
	v_mov_b32_e32 v34, 0
	v_mov_b32_e32 v33, 0
	v_mov_b32_e32 v32, 0
	v_mov_b32_e32 v31, 0
	v_mov_b32_e32 v30, 0
	v_mov_b32_e32 v29, 0
	v_mov_b32_e32 v28, 0
	v_mov_b32_e32 v27, 0
	v_mov_b32_e32 v26, 0
	v_mov_b32_e32 v25, 0
	v_mov_b32_e32 v24, 0
	v_mov_b32_e32 v23, 0
	v_mov_b32_e32 v22, 0
	v_mov_b32_e32 v21, 0
	v_mov_b32_e32 v20, 0
	v_mov_b32_e32 v19, 0
	v_mov_b32_e32 v18, 0
	v_mov_b32_e32 v17, 0
	v_mov_b32_e32 v16, 0
	v_mov_b32_e32 v15, 0
	v_mov_b32_e32 v14, 0
	v_mov_b32_e32 v13, 0
	v_mov_b32_e32 v12, 0
	v_mov_b32_e32 v11, 0
	v_mov_b32_e32 v10, 0
	v_mov_b32_e32 v9, 0
	v_mov_b32_e32 v8, 0
	v_mov_b32_e32 v7, 0
	v_mov_b32_e32 v6, 0
	v_mov_b32_e32 v5, 0
	v_mov_b32_e32 v4, 0
	v_mov_b32_e32 v3, 0
	v_mov_b32_e32 v2, 0
	v_mov_b32_e32 v1, 0
	v_mov_b32_e32 v0, 0
	s_waitcnt vmcnt(9)
	ds_write_b128 v225, v[64:67]
	s_waitcnt vmcnt(8)
	ds_write_b128 v157, v[68:71] offset:9216
	s_waitcnt lgkmcnt(0)
	s_barrier
	s_cbranch_vccnz .LBB0_601
	s_max_i32 s38, s73, 4
	s_add_i32 s38, s38, -4
	s_min_u32 s38, s38, s68
	s_mov_b32 s69, s53
	v_mov_b32_e32 v133, v113
	s_add_i32 s39, s38, 8
	v_mov_b32_e32 v0, s68
	v_cmp_lt_u64_e32 vcc, s[68:69], v[132:133]
	s_add_u32 s68, s80, s52
	v_mov_b32_e32 v1, v113
	v_cndmask_b32_e32 v2, v132, v0, vcc
	v_lshlrev_b32_e32 v0, 16, v2
	s_addc_u32 s69, s81, 0
	v_lshl_add_u64 v[0:1], s[68:69], 0, v[0:1]
	v_lshl_add_u64 v[132:133], v[0:1], 0, v[134:135]
	v_lshlrev_b32_e32 v0, 7, v2
	v_mov_b32_e32 v1, v113
	s_mul_i32 s70, s95, 0x780
	v_lshlrev_b32_e32 v2, 1, v136
	v_mov_b32_e32 v3, v113
	v_lshl_add_u64 v[0:1], s[66:67], 0, v[0:1]
	s_lshl_b32 s66, s72, 7
	v_lshl_add_u64 v[134:135], v[0:1], 0, v[2:3]
	s_add_i32 s70, s70, s66
	s_lshl_b32 s66, s73, 7
	v_mov_b32_e32 v2, v113
	s_sub_i32 s66, s70, s66
	v_mov_b32_e32 v124, v113
	v_mov_b32_e32 v125, v113
	v_mov_b32_e32 v0, v113
	v_mov_b32_e32 v1, v113
	v_mov_b64_e32 v[6:7], v[2:3]
	v_mov_b64_e32 v[10:11], v[2:3]
	v_mov_b64_e32 v[14:15], v[2:3]
	v_mov_b64_e32 v[18:19], v[2:3]
	v_mov_b64_e32 v[22:23], v[2:3]
	v_mov_b64_e32 v[26:27], v[2:3]
	v_mov_b64_e32 v[30:31], v[2:3]
	v_mov_b64_e32 v[34:35], v[2:3]
	v_mov_b64_e32 v[38:39], v[2:3]
	v_mov_b64_e32 v[42:43], v[2:3]
	v_mov_b64_e32 v[46:47], v[2:3]
	v_mov_b64_e32 v[50:51], v[2:3]
	v_mov_b64_e32 v[54:55], v[2:3]
	v_mov_b64_e32 v[58:59], v[2:3]
	v_mov_b64_e32 v[62:63], v[2:3]
	s_add_i32 s52, s72, 3
	s_add_i32 s68, s66, 0
	v_mov_b64_e32 v[4:5], v[0:1]
	v_mov_b64_e32 v[8:9], v[0:1]
	v_mov_b64_e32 v[12:13], v[0:1]
	v_mov_b64_e32 v[16:17], v[0:1]
	v_mov_b64_e32 v[20:21], v[0:1]
	v_mov_b64_e32 v[24:25], v[0:1]
	v_mov_b64_e32 v[28:29], v[0:1]
	v_mov_b64_e32 v[32:33], v[0:1]
	v_mov_b64_e32 v[36:37], v[0:1]
	v_mov_b64_e32 v[40:41], v[0:1]
	v_mov_b64_e32 v[44:45], v[0:1]
	v_mov_b64_e32 v[48:49], v[0:1]
	v_mov_b64_e32 v[52:53], v[0:1]
	v_mov_b64_e32 v[56:57], v[0:1]
	v_mov_b64_e32 v[60:61], v[0:1]
	v_mov_b64_e32 v[130:131], v[124:125]
	s_branch .LBB0_588

.LBB0_590:
	s_add_i32 s70, s52, -3
	s_cmp_ge_u32 s70, s38
	s_cselect_b64 s[66:67], -1, 0
	s_cmp_lt_u32 s70, s39
	s_cselect_b64 s[72:73], -1, 0
	s_and_b64 s[66:67], s[66:67], s[72:73]
	s_andn2_b64 vcc, exec, s[66:67]
	s_cbranch_vccnz .LBB0_592
	v_add_u32_e32 v178, v150, v149
	v_add_u32_e32 v181, 0x2000, v178
	v_add_u32_e32 v218, 0x2800, v178
	v_add_u32_e32 v219, 0x3000, v178
	v_add_u32_e32 v178, v150, v151
	v_add_u32_e32 v119, v148, v149
	v_add_u32_e32 v229, v228, v149
	v_add_u32_e32 v136, s68, v152
	v_add_u32_sdwa v163, s68, v144 dst_sel:DWORD dst_unused:UNUSED_PAD src0_sel:DWORD src1_sel:BYTE_2
	v_add_u32_sdwa v165, s68, v144 dst_sel:DWORD dst_unused:UNUSED_PAD src0_sel:DWORD src1_sel:BYTE_3
	v_add_u32_e32 v220, 0x2000, v178
	v_add_u32_sdwa v179, s68, v142 dst_sel:DWORD dst_unused:UNUSED_PAD src0_sel:DWORD src1_sel:BYTE_1
	ds_read_b128 v[158:161], v119
	ds_read_b128 v[166:169], v119 offset:64
	ds_read_b128 v[170:173], v119 offset:2304
	ds_read_b128 v[174:177], v119 offset:2368
	v_add_u32_e32 v162, s68, v153
	ds_read_b64 v[182:183], v181 offset:1024
	ds_read_b64 v[184:185], v181 offset:1056
	ds_read_b64 v[186:187], v218 offset:1280
	ds_read_b64 v[188:189], v218 offset:1312
	ds_read_b64 v[190:191], v219 offset:1536
	ds_read_b64 v[192:193], v219 offset:1568
	ds_read_b64 v[194:195], v220 offset:1024
	ds_read_b64 v[196:197], v220 offset:1056
	ds_read_b128 v[198:201], v229 offset:1152
	ds_read_b128 v[202:205], v229 offset:1216
	ds_read_b128 v[206:209], v229 offset:3456
	ds_read_b128 v[210:213], v229 offset:3520
	v_add_u32_e32 v178, s68, v155
	v_add_u32_sdwa v214, s68, v143 dst_sel:DWORD dst_unused:UNUSED_PAD src0_sel:DWORD src1_sel:BYTE_2
	v_add_u32_sdwa v215, s68, v143 dst_sel:DWORD dst_unused:UNUSED_PAD src0_sel:DWORD src1_sel:BYTE_3
	ds_read_b32 v136, v136 offset:41856
	ds_read_b32 v216, v162 offset:41856
	ds_read_b32 v163, v163 offset:41856
	ds_read_b32 v165, v165 offset:41856
	ds_read_b32 v217, v178 offset:41856
	ds_read_b32 v179, v179 offset:41856
	ds_read_b32 v221, v214 offset:41856
	ds_read_b32 v222, v215 offset:41856
	s_setprio 1
	s_waitcnt vmcnt(7) lgkmcnt(15)
	v_mfma_f32_16x16x32_bf16 v[158:161], v[158:161], v[80:83], 0
	s_waitcnt vmcnt(6)
	v_mfma_f32_16x16x32_bf16 v[158:161], v[166:169], v[84:87], v[158:161]
	v_mfma_f32_16x16x32_bf16 v[166:169], v[170:173], v[80:83], 0
	v_mfma_f32_16x16x32_bf16 v[166:169], v[174:177], v[84:87], v[166:169]
	s_setprio 0
	s_nop 6
	v_cndmask_b32_e64 v158, v166, v158, s[20:21]
	s_waitcnt lgkmcnt(7)
	v_add_f32_e32 v136, v136, v158
	v_exp_f32_e32 v162, v136
	v_cndmask_b32_e64 v136, v159, v167, s[10:11]
	v_cndmask_b32_e64 v159, v160, v168, s[12:13]
	s_waitcnt lgkmcnt(5)
	v_add_f32_e32 v159, v163, v159
	v_add_f32_e32 v136, v216, v136
	v_exp_f32_e32 v214, v159
	v_cndmask_b32_e64 v159, v161, v169, s[14:15]
	v_exp_f32_e32 v178, v136
	s_waitcnt lgkmcnt(4)
	v_add_f32_e32 v159, v165, v159
	v_exp_f32_e32 v216, v159
	v_cndmask_b32_e64 v159, v214, 0, s[12:13]
	v_cndmask_b32_e64 v158, v178, 0, s[10:11]
	v_cndmask_b32_e64 v160, 0, v178, s[10:11]
	v_cndmask_b32_e64 v161, 0, v214, s[12:13]
	v_cndmask_b32_e64 v136, 0, v162, s[20:21]
	v_cndmask_b32_e64 v166, v162, 0, s[20:21]
	v_cndmask_b32_e64 v163, v216, 0, s[14:15]
	v_cndmask_b32_e64 v165, 0, v216, s[14:15]
	v_cvt_pk_bf16_f32 v158, v136, v158
	v_cvt_pk_bf16_f32 v159, v159, v163
	v_cvt_pk_bf16_f32 v160, v166, v160
	v_cvt_pk_bf16_f32 v161, v161, v165
	s_setprio 1
	v_mfma_f32_16x16x32_bf16 v[60:63], v[182:185], v[158:161], v[60:63]
	v_mfma_f32_16x16x32_bf16 v[56:59], v[186:189], v[158:161], v[56:59]
	v_mfma_f32_16x16x32_bf16 v[52:55], v[190:193], v[158:161], v[52:55]
	v_mfma_f32_16x16x32_bf16 v[48:51], v[194:197], v[158:161], v[48:51]
	s_setprio 0
	ds_read_b64 v[158:159], v181 offset:1040
	ds_read_b64 v[160:161], v181 offset:1072
	ds_read_b64 v[166:167], v218 offset:1296
	ds_read_b64 v[168:169], v218 offset:1328
	ds_read_b64 v[170:171], v219 offset:1552
	ds_read_b64 v[172:173], v219 offset:1584
	ds_read_b64 v[174:175], v220 offset:1040
	ds_read_b64 v[176:177], v220 offset:1072
	ds_read_b128 v[182:185], v229 offset:3456
	ds_read_b128 v[186:189], v229 offset:3520
	ds_read_b128 v[190:193], v229 offset:5760
	ds_read_b128 v[194:197], v229 offset:5824
	v_add_u32_e32 v136, s68, v156
	v_add_u32_sdwa v165, s68, v141 dst_sel:DWORD dst_unused:UNUSED_PAD src0_sel:DWORD src1_sel:BYTE_2
	v_add_u32_sdwa v163, s68, v140 dst_sel:DWORD dst_unused:UNUSED_PAD src0_sel:DWORD src1_sel:BYTE_1
	v_add_u32_sdwa v215, s68, v141 dst_sel:DWORD dst_unused:UNUSED_PAD src0_sel:DWORD src1_sel:BYTE_3
	ds_read_b32 v136, v136 offset:41856
	ds_read_b32 v223, v163 offset:41856
	ds_read_b32 v165, v165 offset:41856
	ds_read_b32 v224, v215 offset:41856
	s_setprio 1
	s_waitcnt vmcnt(5)
	v_mfma_f32_16x16x32_bf16 v[198:201], v[198:201], v[88:91], 0
	s_waitcnt vmcnt(4)
	v_mfma_f32_16x16x32_bf16 v[198:201], v[202:205], v[92:95], v[198:201]
	v_mfma_f32_16x16x32_bf16 v[202:205], v[206:209], v[88:91], 0
	v_mfma_f32_16x16x32_bf16 v[202:205], v[210:213], v[92:95], v[202:205]
	s_setprio 0
	s_nop 6
	v_cndmask_b32_e64 v163, v198, v202, s[16:17]
	s_waitcnt lgkmcnt(15)
	v_add_f32_e32 v163, v217, v163
	v_cndmask_b32_e64 v198, v199, v203, s[18:19]
	v_cndmask_b32_e64 v200, v200, v204, s[6:7]
	v_exp_f32_e32 v163, v163
	v_add_f32_e32 v179, v179, v198
	s_waitcnt lgkmcnt(15)
	v_add_f32_e32 v200, v221, v200
	v_exp_f32_e32 v179, v179
	v_exp_f32_e32 v215, v200
	v_cndmask_b32_e64 v200, v201, v205, s[8:9]
	s_waitcnt lgkmcnt(15)
	v_add_f32_e32 v200, v222, v200
	v_exp_f32_e32 v217, v200
	v_cndmask_b32_e64 v198, v163, 0, s[16:17]
	v_cndmask_b32_e64 v202, 0, v163, s[16:17]
	v_pk_add_f32 v[162:163], v[162:163], 0 op_sel_hi:[1,0]
	v_cndmask_b32_e64 v199, v179, 0, s[18:19]
	v_pk_add_f32 v[162:163], v[178:179], v[162:163]
	v_cndmask_b32_e64 v200, 0, v179, s[18:19]
	v_pk_add_f32 v[162:163], v[214:215], v[162:163]
	v_cndmask_b32_e64 v201, v215, 0, s[6:7]
	v_pk_add_f32 v[162:163], v[216:217], v[162:163]
	v_cndmask_b32_e64 v203, 0, v215, s[6:7]
	v_pk_add_f32 v[130:131], v[130:131], v[162:163]
	v_cndmask_b32_e64 v204, v217, 0, s[8:9]
	v_cndmask_b32_e64 v205, 0, v217, s[8:9]
	v_cvt_pk_bf16_f32 v198, v198, v199
	v_cvt_pk_bf16_f32 v199, v201, v204
	v_cvt_pk_bf16_f32 v200, v202, v200
	v_cvt_pk_bf16_f32 v201, v203, v205
	s_setprio 1
	s_waitcnt lgkmcnt(14)
	v_mfma_f32_16x16x32_bf16 v[44:47], v[158:161], v[198:201], v[44:47]
	s_waitcnt lgkmcnt(12)
	v_mfma_f32_16x16x32_bf16 v[40:43], v[166:169], v[198:201], v[40:43]
	s_waitcnt lgkmcnt(10)
	v_mfma_f32_16x16x32_bf16 v[36:39], v[170:173], v[198:201], v[36:39]
	s_waitcnt lgkmcnt(8)
	v_mfma_f32_16x16x32_bf16 v[32:35], v[174:177], v[198:201], v[32:35]
	s_setprio 0
	ds_read_b64 v[158:159], v181 offset:1072
	ds_read_b64 v[160:161], v181 offset:1104
	ds_read_b64 v[166:167], v218 offset:1328
	ds_read_b64 v[168:169], v218 offset:1360
	ds_read_b64 v[170:171], v219 offset:1584
	ds_read_b64 v[172:173], v219 offset:1616
	ds_read_b64 v[174:175], v220 offset:1072
	ds_read_b64 v[176:177], v220 offset:1104
	ds_read_b128 v[198:201], v119 offset:4608
	ds_read_b128 v[202:205], v119 offset:4672
	v_add_u32_e32 v119, v148, v151
	ds_read_b128 v[206:209], v119
	ds_read_b128 v[210:213], v119 offset:64
	v_add_u32_e32 v119, s68, v154
	v_add_u32_sdwa v162, s68, v145 dst_sel:DWORD dst_unused:UNUSED_PAD src0_sel:DWORD src1_sel:BYTE_1
	v_add_u32_sdwa v163, s68, v146 dst_sel:DWORD dst_unused:UNUSED_PAD src0_sel:DWORD src1_sel:BYTE_2
	v_add_u32_sdwa v178, s68, v146 dst_sel:DWORD dst_unused:UNUSED_PAD src0_sel:DWORD src1_sel:BYTE_3
	ds_read_b32 v119, v119 offset:41856
	ds_read_b32 v179, v162 offset:41856
	ds_read_b32 v214, v163 offset:41856
	ds_read_b32 v215, v178 offset:41856
	s_setprio 1
	s_waitcnt vmcnt(3) lgkmcnt(15)
	v_mfma_f32_16x16x32_bf16 v[182:185], v[182:185], v[96:99], 0
	s_waitcnt vmcnt(2)
	v_mfma_f32_16x16x32_bf16 v[182:185], v[186:189], v[100:103], v[182:185]
	v_mfma_f32_16x16x32_bf16 v[186:189], v[190:193], v[96:99], 0
	v_mfma_f32_16x16x32_bf16 v[186:189], v[194:197], v[100:103], v[186:189]
	s_setprio 0
	s_nop 6
	v_cndmask_b32_e64 v162, v186, v182, s[2:3]
	v_add_f32_e32 v136, v136, v162
	v_exp_f32_e32 v162, v136
	v_cndmask_b32_e64 v136, v187, v183, s[4:5]
	v_cndmask_b32_e64 v183, v184, v188, s[22:23]
	s_waitcnt lgkmcnt(15)
	v_add_f32_e32 v165, v165, v183
	v_exp_f32_e32 v190, v165
	v_cndmask_b32_e64 v165, v185, v189, s[24:25]
	v_add_f32_e32 v136, v223, v136
	s_waitcnt lgkmcnt(15)
	v_add_f32_e32 v165, v224, v165
	v_exp_f32_e32 v178, v136
	v_exp_f32_e32 v192, v165
	v_cndmask_b32_e64 v183, v190, 0, s[22:23]
	v_cndmask_b32_e64 v185, 0, v190, s[22:23]
	v_cndmask_b32_e64 v182, 0, v178, s[4:5]
	v_cndmask_b32_e64 v184, v192, 0, s[24:25]
	v_cndmask_b32_e64 v136, 0, v162, s[2:3]
	v_cndmask_b32_e64 v163, v162, 0, s[2:3]
	v_cndmask_b32_e64 v165, v178, 0, s[4:5]
	v_cndmask_b32_e64 v186, 0, v192, s[24:25]
	v_cvt_pk_bf16_f32 v182, v136, v182
	v_cvt_pk_bf16_f32 v183, v183, v184
	v_cvt_pk_bf16_f32 v184, v163, v165
	v_cvt_pk_bf16_f32 v185, v185, v186
	s_setprio 1
	s_waitcnt lgkmcnt(14)
	v_mfma_f32_16x16x32_bf16 v[28:31], v[158:161], v[182:185], v[28:31]
	s_waitcnt lgkmcnt(12)
	v_mfma_f32_16x16x32_bf16 v[24:27], v[166:169], v[182:185], v[24:27]
	s_waitcnt lgkmcnt(10)
	v_mfma_f32_16x16x32_bf16 v[20:23], v[170:173], v[182:185], v[20:23]
	s_waitcnt lgkmcnt(8)
	v_mfma_f32_16x16x32_bf16 v[16:19], v[174:177], v[182:185], v[16:19]
	s_setprio 0
	ds_read_b64 v[158:159], v220 offset:1088
	ds_read_b64 v[160:161], v220 offset:1120
	ds_read_b64 v[166:167], v219 offset:1600
	ds_read_b64 v[168:169], v219 offset:1632
	ds_read_b64 v[170:171], v218 offset:1344
	ds_read_b64 v[172:173], v218 offset:1376
	ds_read_b64 v[174:175], v181 offset:1088
	ds_read_b64 v[176:177], v181 offset:1120
	s_setprio 1
	s_waitcnt vmcnt(1) lgkmcnt(15)
	v_mfma_f32_16x16x32_bf16 v[182:185], v[198:201], v[104:107], 0
	s_waitcnt lgkmcnt(13)
	v_mfma_f32_16x16x32_bf16 v[186:189], v[206:209], v[104:107], 0
	s_waitcnt vmcnt(0)
	v_mfma_f32_16x16x32_bf16 v[182:185], v[202:205], v[108:111], v[182:185]
	s_waitcnt lgkmcnt(12)
	v_mfma_f32_16x16x32_bf16 v[186:189], v[210:213], v[108:111], v[186:189]
	s_setprio 0
	s_nop 6
	v_cndmask_b32_e64 v136, v182, v186, s[26:27]
	s_waitcnt lgkmcnt(11)
	v_add_f32_e32 v119, v119, v136
	v_exp_f32_e32 v163, v119
	v_cndmask_b32_e64 v119, v183, v187, s[28:29]
	v_cndmask_b32_e64 v181, v184, v188, s[30:31]
	s_waitcnt lgkmcnt(10)
	v_add_f32_e32 v119, v179, v119
	s_waitcnt lgkmcnt(9)
	v_add_f32_e32 v181, v214, v181
	v_exp_f32_e32 v179, v119
	v_exp_f32_e32 v191, v181
	v_cndmask_b32_e64 v181, v185, v189, s[34:35]
	s_waitcnt lgkmcnt(8)
	v_add_f32_e32 v181, v215, v181
	v_exp_f32_e32 v193, v181
	v_cndmask_b32_e64 v119, v163, 0, s[26:27]
	v_cndmask_b32_e64 v136, 0, v163, s[26:27]
	v_pk_add_f32 v[162:163], v[162:163], 0 op_sel_hi:[1,0]
	v_cndmask_b32_e64 v183, v191, 0, s[30:31]
	v_pk_add_f32 v[162:163], v[178:179], v[162:163]
	v_cndmask_b32_e64 v185, 0, v191, s[30:31]
	v_pk_add_f32 v[162:163], v[190:191], v[162:163]
	v_cndmask_b32_e64 v184, v193, 0, s[34:35]
	v_pk_add_f32 v[162:163], v[192:193], v[162:163]
	v_cndmask_b32_e64 v165, v179, 0, s[28:29]
	v_pk_add_f32 v[124:125], v[124:125], v[162:163]
	v_cndmask_b32_e64 v181, 0, v179, s[28:29]
	v_cndmask_b32_e64 v186, 0, v193, s[34:35]
	v_cvt_pk_bf16_f32 v182, v119, v165
	v_cvt_pk_bf16_f32 v183, v183, v184
	v_cvt_pk_bf16_f32 v184, v136, v181
	v_cvt_pk_bf16_f32 v185, v185, v186
	s_setprio 1
	s_waitcnt lgkmcnt(0)
	v_mfma_f32_16x16x32_bf16 v[12:15], v[174:177], v[182:185], v[12:15]
	v_mfma_f32_16x16x32_bf16 v[8:11], v[170:173], v[182:185], v[8:11]
	v_mfma_f32_16x16x32_bf16 v[4:7], v[166:169], v[182:185], v[4:7]
	v_mfma_f32_16x16x32_bf16 v[0:3], v[158:161], v[182:185], v[0:3]
	s_setprio 0
.LBB0_592:
	s_cmp_lt_u32 s70, s96
	s_cselect_b64 s[66:67], -1, 0
	s_cmp_ge_u32 s70, s96
	s_cbranch_scc1 .LBB0_594
	s_waitcnt vmcnt(1)
	ds_write_b128 v225, v[72:75] offset:18432
	s_waitcnt vmcnt(0)
	ds_write_b128 v157, v[76:79] offset:27648

.LBB0_597:
	s_add_i32 s66, s52, -2
	s_cmp_ge_u32 s66, s38
	s_cselect_b64 s[70:71], -1, 0
	s_cmp_lt_u32 s66, s39
	s_cselect_b64 s[72:73], -1, 0
	s_and_b64 s[70:71], s[70:71], s[72:73]
	s_andn2_b64 vcc, exec, s[70:71]
	s_cbranch_vccnz .LBB0_599
	v_add_u32_e32 v178, v150, v149
	v_add_u32_e32 v181, 0x6800, v178
	v_add_u32_e32 v218, 0x7000, v178
	v_add_u32_e32 v219, 0x7800, v178
	v_add_u32_e32 v178, v150, v151
	v_add_u32_e32 v119, v148, v149
	v_add_u32_e32 v229, v228, v149
	v_add_u32_e32 v136, s68, v152
	v_add_u32_sdwa v163, s68, v144 dst_sel:DWORD dst_unused:UNUSED_PAD src0_sel:DWORD src1_sel:BYTE_2
	v_add_u32_sdwa v165, s68, v144 dst_sel:DWORD dst_unused:UNUSED_PAD src0_sel:DWORD src1_sel:BYTE_3
	v_add_u32_e32 v220, 0x6800, v178
	v_add_u32_sdwa v179, s68, v142 dst_sel:DWORD dst_unused:UNUSED_PAD src0_sel:DWORD src1_sel:BYTE_1
	ds_read_b128 v[158:161], v119 offset:18432
	ds_read_b128 v[166:169], v119 offset:18496
	ds_read_b128 v[170:173], v119 offset:20736
	ds_read_b128 v[174:177], v119 offset:20800
	v_add_u32_e32 v162, s68, v153
	ds_read_b64 v[182:183], v181 offset:1024
	ds_read_b64 v[184:185], v181 offset:1056
	ds_read_b64 v[186:187], v218 offset:1280
	ds_read_b64 v[188:189], v218 offset:1312
	ds_read_b64 v[190:191], v219 offset:1536
	ds_read_b64 v[192:193], v219 offset:1568
	ds_read_b64 v[194:195], v220 offset:1024
	ds_read_b64 v[196:197], v220 offset:1056
	ds_read_b128 v[198:201], v229 offset:19584
	ds_read_b128 v[202:205], v229 offset:19648
	ds_read_b128 v[206:209], v229 offset:21888
	ds_read_b128 v[210:213], v229 offset:21952
	v_add_u32_e32 v178, s68, v155
	v_add_u32_sdwa v214, s68, v143 dst_sel:DWORD dst_unused:UNUSED_PAD src0_sel:DWORD src1_sel:BYTE_2
	v_add_u32_sdwa v215, s68, v143 dst_sel:DWORD dst_unused:UNUSED_PAD src0_sel:DWORD src1_sel:BYTE_3
	ds_read_b32 v136, v136 offset:41984
	ds_read_b32 v216, v162 offset:41984
	ds_read_b32 v163, v163 offset:41984
	ds_read_b32 v165, v165 offset:41984
	ds_read_b32 v217, v178 offset:41984
	ds_read_b32 v179, v179 offset:41984
	ds_read_b32 v221, v214 offset:41984
	ds_read_b32 v222, v215 offset:41984
	s_setprio 1
	s_waitcnt vmcnt(7) lgkmcnt(15)
	v_mfma_f32_16x16x32_bf16 v[158:161], v[158:161], v[80:83], 0
	s_waitcnt vmcnt(6)
	v_mfma_f32_16x16x32_bf16 v[158:161], v[166:169], v[84:87], v[158:161]
	v_mfma_f32_16x16x32_bf16 v[166:169], v[170:173], v[80:83], 0
	v_mfma_f32_16x16x32_bf16 v[166:169], v[174:177], v[84:87], v[166:169]
	s_setprio 0
	s_nop 6
	v_cndmask_b32_e64 v158, v166, v158, s[20:21]
	s_waitcnt lgkmcnt(7)
	v_add_f32_e32 v136, v136, v158
	v_exp_f32_e32 v162, v136
	v_cndmask_b32_e64 v136, v159, v167, s[10:11]
	v_cndmask_b32_e64 v159, v160, v168, s[12:13]
	s_waitcnt lgkmcnt(5)
	v_add_f32_e32 v159, v163, v159
	v_add_f32_e32 v136, v216, v136
	v_exp_f32_e32 v214, v159
	v_cndmask_b32_e64 v159, v161, v169, s[14:15]
	v_exp_f32_e32 v178, v136
	s_waitcnt lgkmcnt(4)
	v_add_f32_e32 v159, v165, v159
	v_exp_f32_e32 v216, v159
	v_cndmask_b32_e64 v159, v214, 0, s[12:13]
	v_cndmask_b32_e64 v158, v178, 0, s[10:11]
	v_cndmask_b32_e64 v160, 0, v178, s[10:11]
	v_cndmask_b32_e64 v161, 0, v214, s[12:13]
	v_cndmask_b32_e64 v136, 0, v162, s[20:21]
	v_cndmask_b32_e64 v166, v162, 0, s[20:21]
	v_cndmask_b32_e64 v163, v216, 0, s[14:15]
	v_cndmask_b32_e64 v165, 0, v216, s[14:15]
	v_cvt_pk_bf16_f32 v158, v136, v158
	v_cvt_pk_bf16_f32 v159, v159, v163
	v_cvt_pk_bf16_f32 v160, v166, v160
	v_cvt_pk_bf16_f32 v161, v161, v165
	s_setprio 1
	v_mfma_f32_16x16x32_bf16 v[60:63], v[182:185], v[158:161], v[60:63]
	v_mfma_f32_16x16x32_bf16 v[56:59], v[186:189], v[158:161], v[56:59]
	v_mfma_f32_16x16x32_bf16 v[52:55], v[190:193], v[158:161], v[52:55]
	v_mfma_f32_16x16x32_bf16 v[48:51], v[194:197], v[158:161], v[48:51]
	s_setprio 0
	ds_read_b64 v[158:159], v181 offset:1040
	ds_read_b64 v[160:161], v181 offset:1072
	ds_read_b64 v[166:167], v218 offset:1296
	ds_read_b64 v[168:169], v218 offset:1328
	ds_read_b64 v[170:171], v219 offset:1552
	ds_read_b64 v[172:173], v219 offset:1584
	ds_read_b64 v[174:175], v220 offset:1040
	ds_read_b64 v[176:177], v220 offset:1072
	ds_read_b128 v[182:185], v229 offset:21888
	ds_read_b128 v[186:189], v229 offset:21952
	ds_read_b128 v[190:193], v229 offset:24192
	ds_read_b128 v[194:197], v229 offset:24256
	v_add_u32_e32 v136, s68, v156
	v_add_u32_sdwa v165, s68, v141 dst_sel:DWORD dst_unused:UNUSED_PAD src0_sel:DWORD src1_sel:BYTE_2
	v_add_u32_sdwa v163, s68, v140 dst_sel:DWORD dst_unused:UNUSED_PAD src0_sel:DWORD src1_sel:BYTE_1
	v_add_u32_sdwa v215, s68, v141 dst_sel:DWORD dst_unused:UNUSED_PAD src0_sel:DWORD src1_sel:BYTE_3
	ds_read_b32 v136, v136 offset:41984
	ds_read_b32 v223, v163 offset:41984
	ds_read_b32 v165, v165 offset:41984
	ds_read_b32 v224, v215 offset:41984
	s_setprio 1
	s_waitcnt vmcnt(5)
	v_mfma_f32_16x16x32_bf16 v[198:201], v[198:201], v[88:91], 0
	s_waitcnt vmcnt(4)
	v_mfma_f32_16x16x32_bf16 v[198:201], v[202:205], v[92:95], v[198:201]
	v_mfma_f32_16x16x32_bf16 v[202:205], v[206:209], v[88:91], 0
	v_mfma_f32_16x16x32_bf16 v[202:205], v[210:213], v[92:95], v[202:205]
	s_setprio 0
	s_nop 6
	v_cndmask_b32_e64 v163, v198, v202, s[16:17]
	s_waitcnt lgkmcnt(15)
	v_add_f32_e32 v163, v217, v163
	v_cndmask_b32_e64 v198, v199, v203, s[18:19]
	v_cndmask_b32_e64 v200, v200, v204, s[6:7]
	v_exp_f32_e32 v163, v163
	v_add_f32_e32 v179, v179, v198
	s_waitcnt lgkmcnt(15)
	v_add_f32_e32 v200, v221, v200
	v_exp_f32_e32 v179, v179
	v_exp_f32_e32 v215, v200
	v_cndmask_b32_e64 v200, v201, v205, s[8:9]
	s_waitcnt lgkmcnt(15)
	v_add_f32_e32 v200, v222, v200
	v_exp_f32_e32 v217, v200
	v_cndmask_b32_e64 v198, v163, 0, s[16:17]
	v_cndmask_b32_e64 v202, 0, v163, s[16:17]
	v_pk_add_f32 v[162:163], v[162:163], 0 op_sel_hi:[1,0]
	v_cndmask_b32_e64 v199, v179, 0, s[18:19]
	v_pk_add_f32 v[162:163], v[178:179], v[162:163]
	v_cndmask_b32_e64 v200, 0, v179, s[18:19]
	v_pk_add_f32 v[162:163], v[214:215], v[162:163]
	v_cndmask_b32_e64 v201, v215, 0, s[6:7]
	v_pk_add_f32 v[162:163], v[216:217], v[162:163]
	v_cndmask_b32_e64 v203, 0, v215, s[6:7]
	v_pk_add_f32 v[130:131], v[130:131], v[162:163]
	v_cndmask_b32_e64 v204, v217, 0, s[8:9]
	v_cndmask_b32_e64 v205, 0, v217, s[8:9]
	v_cvt_pk_bf16_f32 v198, v198, v199
	v_cvt_pk_bf16_f32 v199, v201, v204
	v_cvt_pk_bf16_f32 v200, v202, v200
	v_cvt_pk_bf16_f32 v201, v203, v205
	s_setprio 1
	s_waitcnt lgkmcnt(14)
	v_mfma_f32_16x16x32_bf16 v[44:47], v[158:161], v[198:201], v[44:47]
	s_waitcnt lgkmcnt(12)
	v_mfma_f32_16x16x32_bf16 v[40:43], v[166:169], v[198:201], v[40:43]
	s_waitcnt lgkmcnt(10)
	v_mfma_f32_16x16x32_bf16 v[36:39], v[170:173], v[198:201], v[36:39]
	s_waitcnt lgkmcnt(8)
	v_mfma_f32_16x16x32_bf16 v[32:35], v[174:177], v[198:201], v[32:35]
	s_setprio 0
	ds_read_b64 v[158:159], v181 offset:1072
	ds_read_b64 v[160:161], v181 offset:1104
	ds_read_b64 v[166:167], v218 offset:1328
	ds_read_b64 v[168:169], v218 offset:1360
	ds_read_b64 v[170:171], v219 offset:1584
	ds_read_b64 v[172:173], v219 offset:1616
	ds_read_b64 v[174:175], v220 offset:1072
	ds_read_b64 v[176:177], v220 offset:1104
	ds_read_b128 v[198:201], v119 offset:23040
	ds_read_b128 v[202:205], v119 offset:23104
	v_add_u32_e32 v119, v148, v151
	ds_read_b128 v[206:209], v119 offset:18432
	ds_read_b128 v[210:213], v119 offset:18496
	v_add_u32_e32 v119, s68, v154
	v_add_u32_sdwa v162, s68, v145 dst_sel:DWORD dst_unused:UNUSED_PAD src0_sel:DWORD src1_sel:BYTE_1
	v_add_u32_sdwa v163, s68, v146 dst_sel:DWORD dst_unused:UNUSED_PAD src0_sel:DWORD src1_sel:BYTE_2
	v_add_u32_sdwa v178, s68, v146 dst_sel:DWORD dst_unused:UNUSED_PAD src0_sel:DWORD src1_sel:BYTE_3
	ds_read_b32 v119, v119 offset:41984
	ds_read_b32 v179, v162 offset:41984
	ds_read_b32 v214, v163 offset:41984
	ds_read_b32 v215, v178 offset:41984
	s_setprio 1
	s_waitcnt vmcnt(3) lgkmcnt(15)
	v_mfma_f32_16x16x32_bf16 v[182:185], v[182:185], v[96:99], 0
	s_waitcnt vmcnt(2)
	v_mfma_f32_16x16x32_bf16 v[182:185], v[186:189], v[100:103], v[182:185]
	v_mfma_f32_16x16x32_bf16 v[186:189], v[190:193], v[96:99], 0
	v_mfma_f32_16x16x32_bf16 v[186:189], v[194:197], v[100:103], v[186:189]
	s_setprio 0
	s_nop 6
	v_cndmask_b32_e64 v162, v186, v182, s[2:3]
	v_add_f32_e32 v136, v136, v162
	v_exp_f32_e32 v162, v136
	v_cndmask_b32_e64 v136, v187, v183, s[4:5]
	v_cndmask_b32_e64 v183, v184, v188, s[22:23]
	s_waitcnt lgkmcnt(15)
	v_add_f32_e32 v165, v165, v183
	v_exp_f32_e32 v190, v165
	v_cndmask_b32_e64 v165, v185, v189, s[24:25]
	v_add_f32_e32 v136, v223, v136
	s_waitcnt lgkmcnt(15)
	v_add_f32_e32 v165, v224, v165
	v_exp_f32_e32 v178, v136
	v_exp_f32_e32 v192, v165
	v_cndmask_b32_e64 v183, v190, 0, s[22:23]
	v_cndmask_b32_e64 v185, 0, v190, s[22:23]
	v_cndmask_b32_e64 v182, 0, v178, s[4:5]
	v_cndmask_b32_e64 v184, v192, 0, s[24:25]
	v_cndmask_b32_e64 v136, 0, v162, s[2:3]
	v_cndmask_b32_e64 v163, v162, 0, s[2:3]
	v_cndmask_b32_e64 v165, v178, 0, s[4:5]
	v_cndmask_b32_e64 v186, 0, v192, s[24:25]
	v_cvt_pk_bf16_f32 v182, v136, v182
	v_cvt_pk_bf16_f32 v183, v183, v184
	v_cvt_pk_bf16_f32 v184, v163, v165
	v_cvt_pk_bf16_f32 v185, v185, v186
	s_setprio 1
	s_waitcnt lgkmcnt(14)
	v_mfma_f32_16x16x32_bf16 v[28:31], v[158:161], v[182:185], v[28:31]
	s_waitcnt lgkmcnt(12)
	v_mfma_f32_16x16x32_bf16 v[24:27], v[166:169], v[182:185], v[24:27]
	s_waitcnt lgkmcnt(10)
	v_mfma_f32_16x16x32_bf16 v[20:23], v[170:173], v[182:185], v[20:23]
	s_waitcnt lgkmcnt(8)
	v_mfma_f32_16x16x32_bf16 v[16:19], v[174:177], v[182:185], v[16:19]
	s_setprio 0
	ds_read_b64 v[158:159], v220 offset:1088
	ds_read_b64 v[160:161], v220 offset:1120
	ds_read_b64 v[166:167], v219 offset:1600
	ds_read_b64 v[168:169], v219 offset:1632
	ds_read_b64 v[170:171], v218 offset:1344
	ds_read_b64 v[172:173], v218 offset:1376
	ds_read_b64 v[174:175], v181 offset:1088
	ds_read_b64 v[176:177], v181 offset:1120
	s_setprio 1
	s_waitcnt vmcnt(1) lgkmcnt(15)
	v_mfma_f32_16x16x32_bf16 v[182:185], v[198:201], v[104:107], 0
	s_waitcnt lgkmcnt(13)
	v_mfma_f32_16x16x32_bf16 v[186:189], v[206:209], v[104:107], 0
	s_waitcnt vmcnt(0)
	v_mfma_f32_16x16x32_bf16 v[182:185], v[202:205], v[108:111], v[182:185]
	s_waitcnt lgkmcnt(12)
	v_mfma_f32_16x16x32_bf16 v[186:189], v[210:213], v[108:111], v[186:189]
	s_setprio 0
	s_nop 6
	v_cndmask_b32_e64 v136, v182, v186, s[26:27]
	s_waitcnt lgkmcnt(11)
	v_add_f32_e32 v119, v119, v136
	v_exp_f32_e32 v163, v119
	v_cndmask_b32_e64 v119, v183, v187, s[28:29]
	v_cndmask_b32_e64 v181, v184, v188, s[30:31]
	s_waitcnt lgkmcnt(10)
	v_add_f32_e32 v119, v179, v119
	s_waitcnt lgkmcnt(9)
	v_add_f32_e32 v181, v214, v181
	v_exp_f32_e32 v179, v119
	v_exp_f32_e32 v191, v181
	v_cndmask_b32_e64 v181, v185, v189, s[34:35]
	s_waitcnt lgkmcnt(8)
	v_add_f32_e32 v181, v215, v181
	v_exp_f32_e32 v193, v181
	v_cndmask_b32_e64 v119, v163, 0, s[26:27]
	v_cndmask_b32_e64 v136, 0, v163, s[26:27]
	v_pk_add_f32 v[162:163], v[162:163], 0 op_sel_hi:[1,0]
	v_cndmask_b32_e64 v183, v191, 0, s[30:31]
	v_pk_add_f32 v[162:163], v[178:179], v[162:163]
	v_cndmask_b32_e64 v185, 0, v191, s[30:31]
	v_pk_add_f32 v[162:163], v[190:191], v[162:163]
	v_cndmask_b32_e64 v184, v193, 0, s[34:35]
	v_pk_add_f32 v[162:163], v[192:193], v[162:163]
	v_cndmask_b32_e64 v165, v179, 0, s[28:29]
	v_pk_add_f32 v[124:125], v[124:125], v[162:163]
	v_cndmask_b32_e64 v181, 0, v179, s[28:29]
	v_cndmask_b32_e64 v186, 0, v193, s[34:35]
	v_cvt_pk_bf16_f32 v182, v119, v165
	v_cvt_pk_bf16_f32 v183, v183, v184
	v_cvt_pk_bf16_f32 v184, v136, v181
	v_cvt_pk_bf16_f32 v185, v185, v186
	s_setprio 1
	s_waitcnt lgkmcnt(0)
	v_mfma_f32_16x16x32_bf16 v[12:15], v[174:177], v[182:185], v[12:15]
	v_mfma_f32_16x16x32_bf16 v[8:11], v[170:173], v[182:185], v[8:11]
	v_mfma_f32_16x16x32_bf16 v[4:7], v[166:169], v[182:185], v[4:7]
	v_mfma_f32_16x16x32_bf16 v[0:3], v[158:161], v[182:185], v[0:3]
	s_setprio 0
.LBB0_599:
	s_cmp_ge_u32 s66, s96
	s_cbranch_scc1 .LBB0_586
	s_waitcnt vmcnt(1)
	ds_write_b128 v225, v[64:67]
	s_waitcnt vmcnt(0)
	ds_write_b128 v157, v[68:71] offset:9216
	s_branch .LBB0_586

.LBB0_672:
	s_or_b64 exec, exec, s[2:3]
	s_abs_i32 s0, s84
	v_cvt_f32_u32_e32 v0, s0
	s_sub_i32 s3, 0, s0
	s_add_i32 s1, s84, 0x4ff
	s_xor_b32 s2, s1, s84
	v_rcp_iflag_f32_e32 v0, v0
	s_abs_i32 s1, s1
	s_ashr_i32 s2, s2, 31
	s_mov_b32 s41, 0
	v_mul_f32_e32 v0, 0x4f7ffffe, v0
	v_cvt_u32_f32_e32 v0, v0
	s_waitcnt lgkmcnt(0)
	s_barrier
	v_readfirstlane_b32 s4, v0
	s_mul_i32 s3, s3, s4
	s_mul_hi_u32 s3, s4, s3
	s_add_i32 s4, s4, s3
	s_mul_hi_u32 s3, s1, s4
	s_mul_i32 s4, s3, s0
	s_sub_i32 s1, s1, s4
	s_add_i32 s5, s3, 1
	s_sub_i32 s4, s1, s0
	s_cmp_ge_u32 s1, s0
	s_cselect_b32 s3, s5, s3
	s_cselect_b32 s1, s4, s1
	s_add_i32 s4, s3, 1
	s_cmp_ge_u32 s1, s0
	s_cselect_b32 s0, s4, s3
	s_xor_b32 s0, s0, s2
	s_sub_i32 s0, s0, s2
	s_mul_i32 s1, s0, s33
	s_min_i32 s0, s0, 0x100000
	s_add_i32 s64, s1, 3
	s_add_i32 s1, s1, s0
	s_min_i32 s65, s1, 0x500
	s_cmp_lt_i32 s64, s65
	s_cbranch_scc0 .LBB0_709
	v_lshrrev_b32_e32 v1, 2, v180
	v_and_b32_e32 v2, 12, v1
	v_add_u32_e32 v13, 26, v2
	v_add_u32_e32 v14, 24, v137
	v_sub_u32_e32 v15, v13, v14
	v_mov_b32_e32 v16, 0x400
	v_cmp_gt_u32_e32 vcc, 16, v15
	v_mov_b32_e32 v18, 0x800
	v_mov_b32_e32 v19, 0x200
	v_cndmask_b32_e32 v15, 0, v16, vcc
	v_add_u32_e32 v16, 27, v2
	v_sub_u32_e32 v17, v16, v14
	v_cmp_gt_u32_e64 s[0:1], 16, v17
	v_sub_u32_e64 v0, v137, 8 clamp
	v_or_b32_e32 v4, 1, v2
	v_cndmask_b32_e64 v17, 0, v18, s[0:1]
	v_add_u32_e32 v18, 25, v2
	v_sub_u32_e32 v14, v18, v14
	v_cmp_gt_u32_e64 s[4:5], 16, v14
	v_or_b32_e32 v6, 2, v2
	v_or_b32_e32 v8, 3, v1
	v_add_u32_e32 v9, 8, v137
	v_add_u32_e32 v11, 9, v2
	v_cndmask_b32_e64 v14, 0, v19, s[4:5]
	v_add_u32_e32 v19, 10, v2
	v_add_u32_e32 v21, 11, v2
	v_sub_u32_e32 v3, v2, v0
	v_sub_u32_e32 v5, v4, v0
	v_sub_u32_e32 v7, v6, v0
	v_sub_u32_e32 v0, v8, v0
	v_sub_u32_e32 v10, v2, v137
	v_sub_u32_e32 v12, v11, v9
	v_sub_u32_e32 v20, v19, v9
	v_sub_u32_e32 v9, v21, v9
	v_mov_b32_e32 v22, 0x80
	v_cmp_lt_u32_e64 s[8:9], 15, v9
	v_cmp_lt_u32_e64 s[14:15], 15, v0
	v_cmp_lt_u32_e64 s[16:17], 15, v10
	v_cmp_gt_u32_e64 s[2:3], 16, v10
	v_cmp_lt_u32_e64 s[6:7], 15, v20
	v_cndmask_b32_e64 v9, v22, 0, s[8:9]
	v_cmp_lt_u32_e64 s[10:11], 15, v5
	v_cndmask_b32_e64 v0, 8, 0, s[14:15]
	v_cndmask_b32_e64 v10, 16, 0, s[16:17]
	v_cndmask_b32_e64 v20, 64, 0, s[6:7]
	v_cndmask_b32_e64 v5, 2, 0, s[10:11]
	v_cmp_lt_u32_e64 s[12:13], 15, v7
	v_cmp_lt_u32_e64 s[18:19], 15, v12
	v_or3_b32 v0, v0, v10, v9
	v_or_b32_e32 v15, v15, v17
	v_mov_b32_e32 v17, 0x100
	v_cndmask_b32_e64 v7, 4, 0, s[12:13]
	v_cndmask_b32_e64 v12, 32, 0, s[18:19]
	v_or3_b32 v0, v5, v20, v0
	v_cndmask_b32_e64 v17, 0, v17, s[2:3]
	v_or3_b32 v0, v7, v12, v0
	v_or3_b32 v5, v17, v0, v14
	v_add_u32_e32 v0, 42, v2
	v_add_u32_e32 v12, 43, v2
	v_add_u32_e32 v17, 41, v2
	v_cndmask_b32_e32 v0, v0, v13, vcc
	v_or_b32_e32 v9, 32, v137
	v_cndmask_b32_e64 v12, v12, v16, s[0:1]
	v_cndmask_b32_e64 v17, v17, v18, s[4:5]
	v_sub_u32_e32 v0, v0, v9
	v_sub_u32_e32 v12, v12, v9
	v_sub_u32_e32 v17, v17, v9
	v_cndmask_b32_e64 v22, 40, 24, s[2:3]
	v_sub_u32_e32 v9, v2, v9
	v_mov_b32_e32 v20, 0x3c00
	v_add_u32_e32 v9, v9, v22
	v_mov_b32_e32 v10, 0x3c0000
	v_bfrev_b32_e32 v14, 60
	v_lshl_add_u32 v17, v17, 10, v20
	v_lshl_add_u32 v9, v9, 2, 60
	v_lshl_add_u32 v0, v0, 18, v10
	v_lshl_add_u32 v12, v12, 26, v14
	v_or_b32_e32 v140, v17, v9
	v_or3_b32 v141, v0, v12, v140
	v_cndmask_b32_e64 v0, v19, v13, s[6:7]
	v_or_b32_e32 v9, 16, v137
	v_cndmask_b32_e64 v12, v21, v16, s[8:9]
	v_cndmask_b32_e64 v11, v11, v18, s[18:19]
	v_sub_u32_e32 v0, v0, v9
	v_sub_u32_e32 v12, v12, v9
	v_sub_u32_e32 v11, v11, v9
	v_cndmask_b32_e64 v13, 8, 24, s[16:17]
	v_sub_u32_e32 v9, v2, v9
	v_add_u32_e32 v9, v9, v13
	v_lshl_add_u32 v11, v11, 10, v20
	v_lshl_add_u32 v9, v9, 2, 60
	v_lshl_add_u32 v0, v0, 18, v10
	v_lshl_add_u32 v12, v12, 26, v14
	v_or_b32_e32 v142, v11, v9
	v_or3_b32 v143, v0, v12, v142
	v_or_b32_e32 v0, 18, v2
	v_cndmask_b32_e64 v0, v6, v0, s[12:13]
	v_or_b32_e32 v6, 19, v1
	v_cndmask_b32_e64 v6, v8, v6, s[14:15]
	v_or_b32_e32 v8, 17, v2
	v_cndmask_b32_e64 v4, v4, v8, s[10:11]
	v_or_b32_e32 v8, 16, v2
	v_cmp_gt_u32_e64 s[20:21], 16, v3
	v_sub_u32_e32 v4, v4, v137
	v_sub_u32_e32 v0, v0, v137
	v_cndmask_b32_e64 v3, v8, v2, s[20:21]
	v_sub_u32_e32 v3, v3, v137
	v_sub_u32_e32 v6, v6, v137
	v_lshl_add_u32 v4, v4, 10, v20
	v_lshl_add_u32 v3, v3, 2, 60
	v_lshl_add_u32 v0, v0, 18, v10
	v_lshl_add_u32 v6, v6, 26, v14
	v_or_b32_e32 v4, v4, v3
	v_or3_b32 v144, v0, v6, v4
	v_or_b32_e32 v6, 48, v180
	v_add_u32_e32 v8, -8, v6
	v_or_b32_e32 v0, 35, v1
	v_min_u32_e32 v8, 48, v8
	v_sub_u32_e32 v9, v0, v8
	v_mov_b32_e32 v11, 0x8000
	v_cmp_gt_u32_e32 vcc, 16, v9
	v_mov_b32_e32 v16, 0x4000
	v_or_b32_e32 v1, 51, v1
	v_cndmask_b32_e32 v9, 0, v11, vcc
	v_or_b32_e32 v11, 34, v2
	v_sub_u32_e32 v12, v11, v8
	v_cmp_gt_u32_e64 s[0:1], 16, v12
	v_mov_b32_e32 v18, 0x2000
	v_cndmask_b32_e32 v0, v1, v0, vcc
	v_cndmask_b32_e64 v12, 0, v16, s[0:1]
	v_or_b32_e32 v16, 33, v2
	v_sub_u32_e32 v17, v16, v8
	v_cmp_gt_u32_e64 s[22:23], 16, v17
	v_or_b32_e32 v1, 50, v2
	v_cndmask_b32_e64 v1, v1, v11, s[0:1]
	v_cndmask_b32_e64 v17, 0, v18, s[22:23]
	v_or_b32_e32 v18, 32, v2
	v_sub_u32_e32 v8, v18, v8
	v_sub_u32_e32 v1, v1, v6
	v_cmp_gt_u32_e64 s[24:25], 16, v8
	v_lshl_add_u32 v1, v1, 18, v10
	v_or_b32_e32 v10, 49, v2
	v_or_b32_e32 v2, 48, v2
	v_cndmask_b32_e64 v10, v10, v16, s[22:23]
	v_cndmask_b32_e64 v2, v2, v18, s[24:25]
	v_sub_u32_e32 v10, v10, v6
	v_sub_u32_e32 v2, v2, v6
	v_sub_u32_e32 v0, v0, v6
	v_lshl_add_u32 v10, v10, 10, v20
	v_lshl_add_u32 v2, v2, 2, 60
	v_lshl_add_u32 v0, v0, 26, v14
	v_or_b32_e32 v145, v10, v2
	v_or3_b32 v146, v1, v0, v145
	v_and_b32_e32 v1, 7, v164
	v_mov_b32_e32 v19, 0x1000
	v_lshrrev_b32_e32 v147, 3, v164
	v_lshlrev_b32_e32 v114, 4, v1
	s_movk_i32 s0, 0x90
	s_movk_i32 s26, 0x400
	s_movk_i32 s27, 0x800
	v_cndmask_b32_e64 v8, 0, v19, s[24:25]
	v_lshlrev_b32_e32 v0, 3, v1
	v_lshrrev_b32_e32 v1, 4, v180
	v_mad_u32_u24 v10, v147, s0, v114
	s_add_u32 s0, s80, 0x11000000
	v_and_b32_e32 v112, 48, v180
	v_or_b32_e32 v7, v15, v5
	s_movk_i32 s29, 0x1000
	v_or_b32_e32 v8, v8, v17
	v_lshl_add_u32 v150, v1, 3, 0
	v_mul_u32_u24_e32 v151, 0x90, v6
	v_bitop3_b32 v6, v15, s26, v5 bitop3:0xc8
	v_bitop3_b32 v5, v15, s27, v5 bitop3:0xc8
	v_and_b32_e32 v152, 0xfc, v3
	v_and_b32_e32 v154, 0xfc, v2
	v_lshlrev_b32_e32 v2, 2, v1
	s_addc_u32 s1, s81, 0
	v_lshl_add_u32 v1, v13, 2, v112
	v_lshlrev_b32_e32 v3, 2, v137
	s_movk_i32 s28, 0x2000
	v_cmp_eq_u32_e64 s[24:25], 0, v5
	v_bitop3_b32 v5, v8, s29, v7 bitop3:0xc8
	s_add_u32 s42, s80, 0x50000
	v_sub_u32_e32 v1, v1, v3
	s_movk_i32 s30, 0x4000
	v_or_b32_e32 v17, v8, v7
	v_or_b32_e32 v9, v12, v9
	v_cmp_eq_u32_e64 s[26:27], 0, v5
	v_bitop3_b32 v5, v8, s28, v7 bitop3:0xc8
	s_addc_u32 s43, s81, 0
	v_add_u32_e32 v1, -4, v1
	s_mov_b32 s34, 0x8000
	v_cmp_eq_u32_e64 s[28:29], 0, v5
	v_bitop3_b32 v5, v9, s30, v17 bitop3:0xc8
	s_add_u32 s66, s80, 0x17000000
	v_and_b32_e32 v155, 0xfc, v1
	v_lshl_add_u32 v1, v22, 2, v112
	v_mov_b32_e32 v113, 0
	v_cmp_eq_u32_e64 s[30:31], 0, v5
	v_bitop3_b32 v5, v9, s34, v17 bitop3:0xc8
	s_addc_u32 s67, s81, 0
	v_sub_u32_e32 v1, v1, v3
	v_and_b32_e32 v11, 48, v164
	v_cmp_eq_u32_e64 s[34:35], 0, v5
	v_lshrrev_b32_e32 v153, 8, v4
	v_lshl_add_u64 v[4:5], s[80:81], 0, v[112:113]
	s_mov_b64 s[38:39], 0xc000000
	s_add_u32 s68, s80, 0x16000000
	v_add_u32_e32 v1, 0xffffffbc, v1
	v_add_u32_e32 v148, 0, v11
	v_mul_u32_u24_e32 v149, 0x90, v137
	v_cmp_eq_u32_e64 s[22:23], 0, v6
	v_cmp_gt_u32_e64 s[36:37], 16, v180
	v_lshl_add_u64 v[116:117], v[4:5], 0, s[38:39]
	s_addc_u32 s69, s81, 0
	v_mov_b32_e32 v115, v113
	v_and_b32_e32 v156, 0xfc, v1
	v_lshlrev_b32_e32 v112, 1, v0
	s_mov_b64 s[46:47], 0x20000
	s_mov_b64 s[48:49], 0x100
	v_lshlrev_b32_e32 v118, 1, v2
	s_mov_b64 s[50:51], 0x39000000
	s_mov_b32 s70, 0x500000
	v_add_u32_e32 v157, 0, v10
	v_add_u32_e32 v226, 4, v147
	v_bfe_u32 v226, v226, 3, 1
	v_and_b32_e32 v227, 1, v164
	v_lshlrev_b32_e32 v227, 5, v227
	v_sub_u32_e32 v227, 16, v227
	v_mad_i32_i24 v225, v226, v227, v157
	v_add_u32_e32 v226, 4, v137
	v_bfe_u32 v226, v226, 3, 1
	v_lshlrev_b32_e32 v226, 4, v226
	v_xor_b32_e32 v148, v148, v226
	v_xor_b32_e32 v228, 16, v148
	s_branch .LBB0_675

.LBB0_684:
	s_add_i32 s74, s38, s92
	s_lshl_b32 s38, s74, 6
	s_add_i32 s38, s38, s39
	v_add_u32_e32 v128, s38, v137
	s_lshl_b32 s38, s61, 1
	s_mov_b32 s39, s41
	v_ashrrev_i32_e32 v129, 31, v128
	v_lshl_add_u64 v[0:1], v[116:117], 0, s[38:39]
	v_lshlrev_b64 v[2:3], 10, v[128:129]
	v_add_u32_e32 v126, 16, v128
	v_lshl_add_u64 v[2:3], v[0:1], 0, v[2:3]
	v_ashrrev_i32_e32 v127, 31, v126
	global_load_dwordx4 v[80:83], v[2:3], off
	global_load_dwordx4 v[84:87], v[2:3], off offset:64
	v_lshlrev_b64 v[2:3], 10, v[126:127]
	v_add_u32_e32 v122, 32, v128
	v_lshl_add_u64 v[2:3], v[0:1], 0, v[2:3]
	v_ashrrev_i32_e32 v123, 31, v122
	global_load_dwordx4 v[88:91], v[2:3], off
	global_load_dwordx4 v[92:95], v[2:3], off offset:64
	v_lshlrev_b64 v[2:3], 10, v[122:123]
	v_add_u32_e32 v120, 48, v128
	v_lshl_add_u64 v[2:3], v[0:1], 0, v[2:3]
	v_ashrrev_i32_e32 v121, 31, v120
	global_load_dwordx4 v[96:99], v[2:3], off
	global_load_dwordx4 v[100:103], v[2:3], off offset:64
	v_lshlrev_b64 v[2:3], 10, v[120:121]
	v_lshl_add_u64 v[0:1], v[0:1], 0, v[2:3]
	global_load_dwordx4 v[104:107], v[0:1], off
	global_load_dwordx4 v[108:111], v[0:1], off offset:64
	v_mov_b32_e32 v131, 0
	s_andn2_b64 vcc, exec, s[62:63]
	v_mov_b32_e32 v130, 0
	v_mov_b32_e32 v125, 0
	v_mov_b32_e32 v124, 0
	v_mov_b32_e32 v63, 0
	v_mov_b32_e32 v62, 0
	v_mov_b32_e32 v61, 0
	v_mov_b32_e32 v60, 0
	v_mov_b32_e32 v59, 0
	v_mov_b32_e32 v58, 0
	v_mov_b32_e32 v57, 0
	v_mov_b32_e32 v56, 0
	v_mov_b32_e32 v55, 0
	v_mov_b32_e32 v54, 0
	v_mov_b32_e32 v53, 0
	v_mov_b32_e32 v52, 0
	v_mov_b32_e32 v51, 0
	v_mov_b32_e32 v50, 0
	v_mov_b32_e32 v49, 0
	v_mov_b32_e32 v48, 0
	v_mov_b32_e32 v47, 0
	v_mov_b32_e32 v46, 0
	v_mov_b32_e32 v45, 0
	v_mov_b32_e32 v44, 0
	v_mov_b32_e32 v43, 0
	v_mov_b32_e32 v42, 0
	v_mov_b32_e32 v41, 0
	v_mov_b32_e32 v40, 0
	v_mov_b32_e32 v39, 0
	v_mov_b32_e32 v38, 0
	v_mov_b32_e32 v37, 0
	v_mov_b32_e32 v36, 0
	v_mov_b32_e32 v35, 0
	v_mov_b32_e32 v34, 0
	v_mov_b32_e32 v33, 0
	v_mov_b32_e32 v32, 0
	v_mov_b32_e32 v31, 0
	v_mov_b32_e32 v30, 0
	v_mov_b32_e32 v29, 0
	v_mov_b32_e32 v28, 0
	v_mov_b32_e32 v27, 0
	v_mov_b32_e32 v26, 0
	v_mov_b32_e32 v25, 0
	v_mov_b32_e32 v24, 0
	v_mov_b32_e32 v23, 0
	v_mov_b32_e32 v22, 0
	v_mov_b32_e32 v21, 0
	v_mov_b32_e32 v20, 0
	v_mov_b32_e32 v19, 0
	v_mov_b32_e32 v18, 0
	v_mov_b32_e32 v17, 0
	v_mov_b32_e32 v16, 0
	v_mov_b32_e32 v15, 0
	v_mov_b32_e32 v14, 0
	v_mov_b32_e32 v13, 0
	v_mov_b32_e32 v12, 0
	v_mov_b32_e32 v11, 0
	v_mov_b32_e32 v10, 0
	v_mov_b32_e32 v9, 0
	v_mov_b32_e32 v8, 0
	v_mov_b32_e32 v7, 0
	v_mov_b32_e32 v6, 0
	v_mov_b32_e32 v5, 0
	v_mov_b32_e32 v4, 0
	v_mov_b32_e32 v3, 0
	v_mov_b32_e32 v2, 0
	v_mov_b32_e32 v1, 0
	v_mov_b32_e32 v0, 0
	s_waitcnt vmcnt(9)
	ds_write_b128 v225, v[64:67]
	s_waitcnt vmcnt(8)
	ds_write_b128 v157, v[68:71] offset:9216
	s_waitcnt lgkmcnt(0)
	s_barrier
	s_cbranch_vccnz .LBB0_701
	s_max_i32 s38, s74, 4
	s_add_i32 s38, s38, -4
	s_min_u32 s38, s38, s60
	s_mov_b32 s61, s41
	v_mov_b32_e32 v133, v113
	s_add_i32 s39, s38, 8
	v_mov_b32_e32 v0, s60
	v_cmp_lt_u64_e32 vcc, s[60:61], v[132:133]
	s_add_u32 s60, s80, s40
	v_mov_b32_e32 v1, v113
	v_cndmask_b32_e32 v2, v132, v0, vcc
	v_lshlrev_b32_e32 v0, 16, v2
	s_addc_u32 s61, s81, 0
	v_lshl_add_u64 v[0:1], s[60:61], 0, v[0:1]
	v_lshl_add_u64 v[132:133], v[0:1], 0, v[134:135]
	v_lshlrev_b32_e32 v0, 7, v2
	v_mov_b32_e32 v1, v113
	s_mul_i32 s62, s71, 0x780
	v_lshlrev_b32_e32 v2, 1, v136
	v_mov_b32_e32 v3, v113
	v_lshl_add_u64 v[0:1], s[52:53], 0, v[0:1]
	s_lshl_b32 s52, s73, 7
	v_lshl_add_u64 v[134:135], v[0:1], 0, v[2:3]
	s_add_i32 s62, s62, s52
	s_lshl_b32 s52, s74, 7
	v_mov_b32_e32 v2, v113
	s_sub_i32 s52, s62, s52
	v_mov_b32_e32 v124, v113
	v_mov_b32_e32 v125, v113
	v_mov_b32_e32 v0, v113
	v_mov_b32_e32 v1, v113
	v_mov_b64_e32 v[6:7], v[2:3]
	v_mov_b64_e32 v[10:11], v[2:3]
	v_mov_b64_e32 v[14:15], v[2:3]
	v_mov_b64_e32 v[18:19], v[2:3]
	v_mov_b64_e32 v[22:23], v[2:3]
	v_mov_b64_e32 v[26:27], v[2:3]
	v_mov_b64_e32 v[30:31], v[2:3]
	v_mov_b64_e32 v[34:35], v[2:3]
	v_mov_b64_e32 v[38:39], v[2:3]
	v_mov_b64_e32 v[42:43], v[2:3]
	v_mov_b64_e32 v[46:47], v[2:3]
	v_mov_b64_e32 v[50:51], v[2:3]
	v_mov_b64_e32 v[54:55], v[2:3]
	v_mov_b64_e32 v[58:59], v[2:3]
	v_mov_b64_e32 v[62:63], v[2:3]
	s_add_i32 s40, s73, 3
	s_add_i32 s60, s52, 0
	v_mov_b64_e32 v[4:5], v[0:1]
	v_mov_b64_e32 v[8:9], v[0:1]
	v_mov_b64_e32 v[12:13], v[0:1]
	v_mov_b64_e32 v[16:17], v[0:1]
	v_mov_b64_e32 v[20:21], v[0:1]
	v_mov_b64_e32 v[24:25], v[0:1]
	v_mov_b64_e32 v[28:29], v[0:1]
	v_mov_b64_e32 v[32:33], v[0:1]
	v_mov_b64_e32 v[36:37], v[0:1]
	v_mov_b64_e32 v[40:41], v[0:1]
	v_mov_b64_e32 v[44:45], v[0:1]
	v_mov_b64_e32 v[48:49], v[0:1]
	v_mov_b64_e32 v[52:53], v[0:1]
	v_mov_b64_e32 v[56:57], v[0:1]
	v_mov_b64_e32 v[60:61], v[0:1]
	v_mov_b64_e32 v[130:131], v[124:125]
	s_branch .LBB0_688

.LBB0_690:
	s_add_i32 s62, s40, -3
	s_cmp_ge_u32 s62, s38
	s_cselect_b64 s[52:53], -1, 0
	s_cmp_lt_u32 s62, s39
	s_cselect_b64 s[74:75], -1, 0
	s_and_b64 s[52:53], s[52:53], s[74:75]
	s_andn2_b64 vcc, exec, s[52:53]
	s_cbranch_vccnz .LBB0_692
	v_add_u32_e32 v178, v150, v149
	v_add_u32_e32 v181, 0x2000, v178
	v_add_u32_e32 v218, 0x2800, v178
	v_add_u32_e32 v219, 0x3000, v178
	v_add_u32_e32 v178, v150, v151
	v_add_u32_e32 v119, v148, v149
	v_add_u32_e32 v229, v228, v149
	v_add_u32_e32 v136, s60, v152
	v_add_u32_sdwa v163, s60, v144 dst_sel:DWORD dst_unused:UNUSED_PAD src0_sel:DWORD src1_sel:BYTE_2
	v_add_u32_sdwa v165, s60, v144 dst_sel:DWORD dst_unused:UNUSED_PAD src0_sel:DWORD src1_sel:BYTE_3
	v_add_u32_e32 v220, 0x2000, v178
	v_add_u32_sdwa v179, s60, v142 dst_sel:DWORD dst_unused:UNUSED_PAD src0_sel:DWORD src1_sel:BYTE_1
	ds_read_b128 v[158:161], v119
	ds_read_b128 v[166:169], v119 offset:64
	ds_read_b128 v[170:173], v119 offset:2304
	ds_read_b128 v[174:177], v119 offset:2368
	v_add_u32_e32 v162, s60, v153
	ds_read_b64 v[182:183], v181 offset:1024
	ds_read_b64 v[184:185], v181 offset:1056
	ds_read_b64 v[186:187], v218 offset:1280
	ds_read_b64 v[188:189], v218 offset:1312
	ds_read_b64 v[190:191], v219 offset:1536
	ds_read_b64 v[192:193], v219 offset:1568
	ds_read_b64 v[194:195], v220 offset:1024
	ds_read_b64 v[196:197], v220 offset:1056
	ds_read_b128 v[198:201], v229 offset:1152
	ds_read_b128 v[202:205], v229 offset:1216
	ds_read_b128 v[206:209], v229 offset:3456
	ds_read_b128 v[210:213], v229 offset:3520
	v_add_u32_e32 v178, s60, v155
	v_add_u32_sdwa v214, s60, v143 dst_sel:DWORD dst_unused:UNUSED_PAD src0_sel:DWORD src1_sel:BYTE_2
	v_add_u32_sdwa v215, s60, v143 dst_sel:DWORD dst_unused:UNUSED_PAD src0_sel:DWORD src1_sel:BYTE_3
	ds_read_b32 v136, v136 offset:41856
	ds_read_b32 v216, v162 offset:41856
	ds_read_b32 v163, v163 offset:41856
	ds_read_b32 v165, v165 offset:41856
	ds_read_b32 v217, v178 offset:41856
	ds_read_b32 v179, v179 offset:41856
	ds_read_b32 v221, v214 offset:41856
	ds_read_b32 v222, v215 offset:41856
	s_setprio 1
	s_waitcnt vmcnt(7) lgkmcnt(15)
	v_mfma_f32_16x16x32_bf16 v[158:161], v[158:161], v[80:83], 0
	s_waitcnt vmcnt(6)
	v_mfma_f32_16x16x32_bf16 v[158:161], v[166:169], v[84:87], v[158:161]
	v_mfma_f32_16x16x32_bf16 v[166:169], v[170:173], v[80:83], 0
	v_mfma_f32_16x16x32_bf16 v[166:169], v[174:177], v[84:87], v[166:169]
	s_setprio 0
	s_nop 6
	v_cndmask_b32_e64 v158, v166, v158, s[20:21]
	s_waitcnt lgkmcnt(7)
	v_add_f32_e32 v136, v136, v158
	v_exp_f32_e32 v162, v136
	v_cndmask_b32_e64 v136, v159, v167, s[10:11]
	v_cndmask_b32_e64 v159, v160, v168, s[12:13]
	s_waitcnt lgkmcnt(5)
	v_add_f32_e32 v159, v163, v159
	v_add_f32_e32 v136, v216, v136
	v_exp_f32_e32 v214, v159
	v_cndmask_b32_e64 v159, v161, v169, s[14:15]
	v_exp_f32_e32 v178, v136
	s_waitcnt lgkmcnt(4)
	v_add_f32_e32 v159, v165, v159
	v_exp_f32_e32 v216, v159
	v_cndmask_b32_e64 v159, v214, 0, s[12:13]
	v_cndmask_b32_e64 v158, v178, 0, s[10:11]
	v_cndmask_b32_e64 v160, 0, v178, s[10:11]
	v_cndmask_b32_e64 v161, 0, v214, s[12:13]
	v_cndmask_b32_e64 v136, 0, v162, s[20:21]
	v_cndmask_b32_e64 v166, v162, 0, s[20:21]
	v_cndmask_b32_e64 v163, v216, 0, s[14:15]
	v_cndmask_b32_e64 v165, 0, v216, s[14:15]
	v_cvt_pk_bf16_f32 v158, v136, v158
	v_cvt_pk_bf16_f32 v159, v159, v163
	v_cvt_pk_bf16_f32 v160, v166, v160
	v_cvt_pk_bf16_f32 v161, v161, v165
	s_setprio 1
	v_mfma_f32_16x16x32_bf16 v[60:63], v[182:185], v[158:161], v[60:63]
	v_mfma_f32_16x16x32_bf16 v[56:59], v[186:189], v[158:161], v[56:59]
	v_mfma_f32_16x16x32_bf16 v[52:55], v[190:193], v[158:161], v[52:55]
	v_mfma_f32_16x16x32_bf16 v[48:51], v[194:197], v[158:161], v[48:51]
	s_setprio 0
	ds_read_b64 v[158:159], v181 offset:1040
	ds_read_b64 v[160:161], v181 offset:1072
	ds_read_b64 v[166:167], v218 offset:1296
	ds_read_b64 v[168:169], v218 offset:1328
	ds_read_b64 v[170:171], v219 offset:1552
	ds_read_b64 v[172:173], v219 offset:1584
	ds_read_b64 v[174:175], v220 offset:1040
	ds_read_b64 v[176:177], v220 offset:1072
	ds_read_b128 v[182:185], v229 offset:3456
	ds_read_b128 v[186:189], v229 offset:3520
	ds_read_b128 v[190:193], v229 offset:5760
	ds_read_b128 v[194:197], v229 offset:5824
	v_add_u32_e32 v136, s60, v156
	v_add_u32_sdwa v165, s60, v141 dst_sel:DWORD dst_unused:UNUSED_PAD src0_sel:DWORD src1_sel:BYTE_2
	v_add_u32_sdwa v163, s60, v140 dst_sel:DWORD dst_unused:UNUSED_PAD src0_sel:DWORD src1_sel:BYTE_1
	v_add_u32_sdwa v215, s60, v141 dst_sel:DWORD dst_unused:UNUSED_PAD src0_sel:DWORD src1_sel:BYTE_3
	ds_read_b32 v136, v136 offset:41856
	ds_read_b32 v223, v163 offset:41856
	ds_read_b32 v165, v165 offset:41856
	ds_read_b32 v224, v215 offset:41856
	s_setprio 1
	s_waitcnt vmcnt(5)
	v_mfma_f32_16x16x32_bf16 v[198:201], v[198:201], v[88:91], 0
	s_waitcnt vmcnt(4)
	v_mfma_f32_16x16x32_bf16 v[198:201], v[202:205], v[92:95], v[198:201]
	v_mfma_f32_16x16x32_bf16 v[202:205], v[206:209], v[88:91], 0
	v_mfma_f32_16x16x32_bf16 v[202:205], v[210:213], v[92:95], v[202:205]
	s_setprio 0
	s_nop 6
	v_cndmask_b32_e64 v163, v198, v202, s[16:17]
	s_waitcnt lgkmcnt(15)
	v_add_f32_e32 v163, v217, v163
	v_cndmask_b32_e64 v198, v199, v203, s[18:19]
	v_cndmask_b32_e64 v200, v200, v204, s[6:7]
	v_exp_f32_e32 v163, v163
	v_add_f32_e32 v179, v179, v198
	s_waitcnt lgkmcnt(15)
	v_add_f32_e32 v200, v221, v200
	v_exp_f32_e32 v179, v179
	v_exp_f32_e32 v215, v200
	v_cndmask_b32_e64 v200, v201, v205, s[8:9]
	s_waitcnt lgkmcnt(15)
	v_add_f32_e32 v200, v222, v200
	v_exp_f32_e32 v217, v200
	v_cndmask_b32_e64 v198, v163, 0, s[16:17]
	v_cndmask_b32_e64 v202, 0, v163, s[16:17]
	v_pk_add_f32 v[162:163], v[162:163], 0 op_sel_hi:[1,0]
	v_cndmask_b32_e64 v199, v179, 0, s[18:19]
	v_pk_add_f32 v[162:163], v[178:179], v[162:163]
	v_cndmask_b32_e64 v200, 0, v179, s[18:19]
	v_pk_add_f32 v[162:163], v[214:215], v[162:163]
	v_cndmask_b32_e64 v201, v215, 0, s[6:7]
	v_pk_add_f32 v[162:163], v[216:217], v[162:163]
	v_cndmask_b32_e64 v203, 0, v215, s[6:7]
	v_pk_add_f32 v[130:131], v[130:131], v[162:163]
	v_cndmask_b32_e64 v204, v217, 0, s[8:9]
	v_cndmask_b32_e64 v205, 0, v217, s[8:9]
	v_cvt_pk_bf16_f32 v198, v198, v199
	v_cvt_pk_bf16_f32 v199, v201, v204
	v_cvt_pk_bf16_f32 v200, v202, v200
	v_cvt_pk_bf16_f32 v201, v203, v205
	s_setprio 1
	s_waitcnt lgkmcnt(14)
	v_mfma_f32_16x16x32_bf16 v[44:47], v[158:161], v[198:201], v[44:47]
	s_waitcnt lgkmcnt(12)
	v_mfma_f32_16x16x32_bf16 v[40:43], v[166:169], v[198:201], v[40:43]
	s_waitcnt lgkmcnt(10)
	v_mfma_f32_16x16x32_bf16 v[36:39], v[170:173], v[198:201], v[36:39]
	s_waitcnt lgkmcnt(8)
	v_mfma_f32_16x16x32_bf16 v[32:35], v[174:177], v[198:201], v[32:35]
	s_setprio 0
	ds_read_b64 v[158:159], v181 offset:1072
	ds_read_b64 v[160:161], v181 offset:1104
	ds_read_b64 v[166:167], v218 offset:1328
	ds_read_b64 v[168:169], v218 offset:1360
	ds_read_b64 v[170:171], v219 offset:1584
	ds_read_b64 v[172:173], v219 offset:1616
	ds_read_b64 v[174:175], v220 offset:1072
	ds_read_b64 v[176:177], v220 offset:1104
	ds_read_b128 v[198:201], v119 offset:4608
	ds_read_b128 v[202:205], v119 offset:4672
	v_add_u32_e32 v119, v148, v151
	ds_read_b128 v[206:209], v119
	ds_read_b128 v[210:213], v119 offset:64
	v_add_u32_e32 v119, s60, v154
	v_add_u32_sdwa v162, s60, v145 dst_sel:DWORD dst_unused:UNUSED_PAD src0_sel:DWORD src1_sel:BYTE_1
	v_add_u32_sdwa v163, s60, v146 dst_sel:DWORD dst_unused:UNUSED_PAD src0_sel:DWORD src1_sel:BYTE_2
	v_add_u32_sdwa v178, s60, v146 dst_sel:DWORD dst_unused:UNUSED_PAD src0_sel:DWORD src1_sel:BYTE_3
	ds_read_b32 v119, v119 offset:41856
	ds_read_b32 v179, v162 offset:41856
	ds_read_b32 v214, v163 offset:41856
	ds_read_b32 v215, v178 offset:41856
	s_setprio 1
	s_waitcnt vmcnt(3) lgkmcnt(15)
	v_mfma_f32_16x16x32_bf16 v[182:185], v[182:185], v[96:99], 0
	s_waitcnt vmcnt(2)
	v_mfma_f32_16x16x32_bf16 v[182:185], v[186:189], v[100:103], v[182:185]
	v_mfma_f32_16x16x32_bf16 v[186:189], v[190:193], v[96:99], 0
	v_mfma_f32_16x16x32_bf16 v[186:189], v[194:197], v[100:103], v[186:189]
	s_setprio 0
	s_nop 6
	v_cndmask_b32_e64 v162, v186, v182, s[2:3]
	v_add_f32_e32 v136, v136, v162
	v_exp_f32_e32 v162, v136
	v_cndmask_b32_e64 v136, v187, v183, s[4:5]
	v_cndmask_b32_e64 v183, v184, v188, s[22:23]
	s_waitcnt lgkmcnt(15)
	v_add_f32_e32 v165, v165, v183
	v_exp_f32_e32 v190, v165
	v_cndmask_b32_e64 v165, v185, v189, s[24:25]
	v_add_f32_e32 v136, v223, v136
	s_waitcnt lgkmcnt(15)
	v_add_f32_e32 v165, v224, v165
	v_exp_f32_e32 v178, v136
	v_exp_f32_e32 v192, v165
	v_cndmask_b32_e64 v183, v190, 0, s[22:23]
	v_cndmask_b32_e64 v185, 0, v190, s[22:23]
	v_cndmask_b32_e64 v182, 0, v178, s[4:5]
	v_cndmask_b32_e64 v184, v192, 0, s[24:25]
	v_cndmask_b32_e64 v136, 0, v162, s[2:3]
	v_cndmask_b32_e64 v163, v162, 0, s[2:3]
	v_cndmask_b32_e64 v165, v178, 0, s[4:5]
	v_cndmask_b32_e64 v186, 0, v192, s[24:25]
	v_cvt_pk_bf16_f32 v182, v136, v182
	v_cvt_pk_bf16_f32 v183, v183, v184
	v_cvt_pk_bf16_f32 v184, v163, v165
	v_cvt_pk_bf16_f32 v185, v185, v186
	s_setprio 1
	s_waitcnt lgkmcnt(14)
	v_mfma_f32_16x16x32_bf16 v[28:31], v[158:161], v[182:185], v[28:31]
	s_waitcnt lgkmcnt(12)
	v_mfma_f32_16x16x32_bf16 v[24:27], v[166:169], v[182:185], v[24:27]
	s_waitcnt lgkmcnt(10)
	v_mfma_f32_16x16x32_bf16 v[20:23], v[170:173], v[182:185], v[20:23]
	s_waitcnt lgkmcnt(8)
	v_mfma_f32_16x16x32_bf16 v[16:19], v[174:177], v[182:185], v[16:19]
	s_setprio 0
	ds_read_b64 v[158:159], v220 offset:1088
	ds_read_b64 v[160:161], v220 offset:1120
	ds_read_b64 v[166:167], v219 offset:1600
	ds_read_b64 v[168:169], v219 offset:1632
	ds_read_b64 v[170:171], v218 offset:1344
	ds_read_b64 v[172:173], v218 offset:1376
	ds_read_b64 v[174:175], v181 offset:1088
	ds_read_b64 v[176:177], v181 offset:1120
	s_setprio 1
	s_waitcnt vmcnt(1) lgkmcnt(15)
	v_mfma_f32_16x16x32_bf16 v[182:185], v[198:201], v[104:107], 0
	s_waitcnt lgkmcnt(13)
	v_mfma_f32_16x16x32_bf16 v[186:189], v[206:209], v[104:107], 0
	s_waitcnt vmcnt(0)
	v_mfma_f32_16x16x32_bf16 v[182:185], v[202:205], v[108:111], v[182:185]
	s_waitcnt lgkmcnt(12)
	v_mfma_f32_16x16x32_bf16 v[186:189], v[210:213], v[108:111], v[186:189]
	s_setprio 0
	s_nop 6
	v_cndmask_b32_e64 v136, v182, v186, s[26:27]
	s_waitcnt lgkmcnt(11)
	v_add_f32_e32 v119, v119, v136
	v_exp_f32_e32 v163, v119
	v_cndmask_b32_e64 v119, v183, v187, s[28:29]
	v_cndmask_b32_e64 v181, v184, v188, s[30:31]
	s_waitcnt lgkmcnt(10)
	v_add_f32_e32 v119, v179, v119
	s_waitcnt lgkmcnt(9)
	v_add_f32_e32 v181, v214, v181
	v_exp_f32_e32 v179, v119
	v_exp_f32_e32 v191, v181
	v_cndmask_b32_e64 v181, v185, v189, s[34:35]
	s_waitcnt lgkmcnt(8)
	v_add_f32_e32 v181, v215, v181
	v_exp_f32_e32 v193, v181
	v_cndmask_b32_e64 v119, v163, 0, s[26:27]
	v_cndmask_b32_e64 v136, 0, v163, s[26:27]
	v_pk_add_f32 v[162:163], v[162:163], 0 op_sel_hi:[1,0]
	v_cndmask_b32_e64 v183, v191, 0, s[30:31]
	v_pk_add_f32 v[162:163], v[178:179], v[162:163]
	v_cndmask_b32_e64 v185, 0, v191, s[30:31]
	v_pk_add_f32 v[162:163], v[190:191], v[162:163]
	v_cndmask_b32_e64 v184, v193, 0, s[34:35]
	v_pk_add_f32 v[162:163], v[192:193], v[162:163]
	v_cndmask_b32_e64 v165, v179, 0, s[28:29]
	v_pk_add_f32 v[124:125], v[124:125], v[162:163]
	v_cndmask_b32_e64 v181, 0, v179, s[28:29]
	v_cndmask_b32_e64 v186, 0, v193, s[34:35]
	v_cvt_pk_bf16_f32 v182, v119, v165
	v_cvt_pk_bf16_f32 v183, v183, v184
	v_cvt_pk_bf16_f32 v184, v136, v181
	v_cvt_pk_bf16_f32 v185, v185, v186
	s_setprio 1
	s_waitcnt lgkmcnt(0)
	v_mfma_f32_16x16x32_bf16 v[12:15], v[174:177], v[182:185], v[12:15]
	v_mfma_f32_16x16x32_bf16 v[8:11], v[170:173], v[182:185], v[8:11]
	v_mfma_f32_16x16x32_bf16 v[4:7], v[166:169], v[182:185], v[4:7]
	v_mfma_f32_16x16x32_bf16 v[0:3], v[158:161], v[182:185], v[0:3]
	s_setprio 0
.LBB0_692:
	s_cmp_lt_u32 s62, s72
	s_cselect_b64 s[52:53], -1, 0
	s_cmp_ge_u32 s62, s72
	s_cbranch_scc1 .LBB0_694
	s_waitcnt vmcnt(1)
	ds_write_b128 v225, v[72:75] offset:18432
	s_waitcnt vmcnt(0)
	ds_write_b128 v157, v[76:79] offset:27648

.LBB0_697:
	s_add_i32 s52, s40, -2
	s_cmp_ge_u32 s52, s38
	s_cselect_b64 s[62:63], -1, 0
	s_cmp_lt_u32 s52, s39
	s_cselect_b64 s[74:75], -1, 0
	s_and_b64 s[62:63], s[62:63], s[74:75]
	s_andn2_b64 vcc, exec, s[62:63]
	s_cbranch_vccnz .LBB0_699
	v_add_u32_e32 v178, v150, v149
	v_add_u32_e32 v181, 0x6800, v178
	v_add_u32_e32 v218, 0x7000, v178
	v_add_u32_e32 v219, 0x7800, v178
	v_add_u32_e32 v178, v150, v151
	v_add_u32_e32 v119, v148, v149
	v_add_u32_e32 v229, v228, v149
	v_add_u32_e32 v136, s60, v152
	v_add_u32_sdwa v163, s60, v144 dst_sel:DWORD dst_unused:UNUSED_PAD src0_sel:DWORD src1_sel:BYTE_2
	v_add_u32_sdwa v165, s60, v144 dst_sel:DWORD dst_unused:UNUSED_PAD src0_sel:DWORD src1_sel:BYTE_3
	v_add_u32_e32 v220, 0x6800, v178
	v_add_u32_sdwa v179, s60, v142 dst_sel:DWORD dst_unused:UNUSED_PAD src0_sel:DWORD src1_sel:BYTE_1
	ds_read_b128 v[158:161], v119 offset:18432
	ds_read_b128 v[166:169], v119 offset:18496
	ds_read_b128 v[170:173], v119 offset:20736
	ds_read_b128 v[174:177], v119 offset:20800
	v_add_u32_e32 v162, s60, v153
	ds_read_b64 v[182:183], v181 offset:1024
	ds_read_b64 v[184:185], v181 offset:1056
	ds_read_b64 v[186:187], v218 offset:1280
	ds_read_b64 v[188:189], v218 offset:1312
	ds_read_b64 v[190:191], v219 offset:1536
	ds_read_b64 v[192:193], v219 offset:1568
	ds_read_b64 v[194:195], v220 offset:1024
	ds_read_b64 v[196:197], v220 offset:1056
	ds_read_b128 v[198:201], v229 offset:19584
	ds_read_b128 v[202:205], v229 offset:19648
	ds_read_b128 v[206:209], v229 offset:21888
	ds_read_b128 v[210:213], v229 offset:21952
	v_add_u32_e32 v178, s60, v155
	v_add_u32_sdwa v214, s60, v143 dst_sel:DWORD dst_unused:UNUSED_PAD src0_sel:DWORD src1_sel:BYTE_2
	v_add_u32_sdwa v215, s60, v143 dst_sel:DWORD dst_unused:UNUSED_PAD src0_sel:DWORD src1_sel:BYTE_3
	ds_read_b32 v136, v136 offset:41984
	ds_read_b32 v216, v162 offset:41984
	ds_read_b32 v163, v163 offset:41984
	ds_read_b32 v165, v165 offset:41984
	ds_read_b32 v217, v178 offset:41984
	ds_read_b32 v179, v179 offset:41984
	ds_read_b32 v221, v214 offset:41984
	ds_read_b32 v222, v215 offset:41984
	s_setprio 1
	s_waitcnt vmcnt(7) lgkmcnt(15)
	v_mfma_f32_16x16x32_bf16 v[158:161], v[158:161], v[80:83], 0
	s_waitcnt vmcnt(6)
	v_mfma_f32_16x16x32_bf16 v[158:161], v[166:169], v[84:87], v[158:161]
	v_mfma_f32_16x16x32_bf16 v[166:169], v[170:173], v[80:83], 0
	v_mfma_f32_16x16x32_bf16 v[166:169], v[174:177], v[84:87], v[166:169]
	s_setprio 0
	s_nop 6
	v_cndmask_b32_e64 v158, v166, v158, s[20:21]
	s_waitcnt lgkmcnt(7)
	v_add_f32_e32 v136, v136, v158
	v_exp_f32_e32 v162, v136
	v_cndmask_b32_e64 v136, v159, v167, s[10:11]
	v_cndmask_b32_e64 v159, v160, v168, s[12:13]
	s_waitcnt lgkmcnt(5)
	v_add_f32_e32 v159, v163, v159
	v_add_f32_e32 v136, v216, v136
	v_exp_f32_e32 v214, v159
	v_cndmask_b32_e64 v159, v161, v169, s[14:15]
	v_exp_f32_e32 v178, v136
	s_waitcnt lgkmcnt(4)
	v_add_f32_e32 v159, v165, v159
	v_exp_f32_e32 v216, v159
	v_cndmask_b32_e64 v159, v214, 0, s[12:13]
	v_cndmask_b32_e64 v158, v178, 0, s[10:11]
	v_cndmask_b32_e64 v160, 0, v178, s[10:11]
	v_cndmask_b32_e64 v161, 0, v214, s[12:13]
	v_cndmask_b32_e64 v136, 0, v162, s[20:21]
	v_cndmask_b32_e64 v166, v162, 0, s[20:21]
	v_cndmask_b32_e64 v163, v216, 0, s[14:15]
	v_cndmask_b32_e64 v165, 0, v216, s[14:15]
	v_cvt_pk_bf16_f32 v158, v136, v158
	v_cvt_pk_bf16_f32 v159, v159, v163
	v_cvt_pk_bf16_f32 v160, v166, v160
	v_cvt_pk_bf16_f32 v161, v161, v165
	s_setprio 1
	v_mfma_f32_16x16x32_bf16 v[60:63], v[182:185], v[158:161], v[60:63]
	v_mfma_f32_16x16x32_bf16 v[56:59], v[186:189], v[158:161], v[56:59]
	v_mfma_f32_16x16x32_bf16 v[52:55], v[190:193], v[158:161], v[52:55]
	v_mfma_f32_16x16x32_bf16 v[48:51], v[194:197], v[158:161], v[48:51]
	s_setprio 0
	ds_read_b64 v[158:159], v181 offset:1040
	ds_read_b64 v[160:161], v181 offset:1072
	ds_read_b64 v[166:167], v218 offset:1296
	ds_read_b64 v[168:169], v218 offset:1328
	ds_read_b64 v[170:171], v219 offset:1552
	ds_read_b64 v[172:173], v219 offset:1584
	ds_read_b64 v[174:175], v220 offset:1040
	ds_read_b64 v[176:177], v220 offset:1072
	ds_read_b128 v[182:185], v229 offset:21888
	ds_read_b128 v[186:189], v229 offset:21952
	ds_read_b128 v[190:193], v229 offset:24192
	ds_read_b128 v[194:197], v229 offset:24256
	v_add_u32_e32 v136, s60, v156
	v_add_u32_sdwa v165, s60, v141 dst_sel:DWORD dst_unused:UNUSED_PAD src0_sel:DWORD src1_sel:BYTE_2
	v_add_u32_sdwa v163, s60, v140 dst_sel:DWORD dst_unused:UNUSED_PAD src0_sel:DWORD src1_sel:BYTE_1
	v_add_u32_sdwa v215, s60, v141 dst_sel:DWORD dst_unused:UNUSED_PAD src0_sel:DWORD src1_sel:BYTE_3
	ds_read_b32 v136, v136 offset:41984
	ds_read_b32 v223, v163 offset:41984
	ds_read_b32 v165, v165 offset:41984
	ds_read_b32 v224, v215 offset:41984
	s_setprio 1
	s_waitcnt vmcnt(5)
	v_mfma_f32_16x16x32_bf16 v[198:201], v[198:201], v[88:91], 0
	s_waitcnt vmcnt(4)
	v_mfma_f32_16x16x32_bf16 v[198:201], v[202:205], v[92:95], v[198:201]
	v_mfma_f32_16x16x32_bf16 v[202:205], v[206:209], v[88:91], 0
	v_mfma_f32_16x16x32_bf16 v[202:205], v[210:213], v[92:95], v[202:205]
	s_setprio 0
	s_nop 6
	v_cndmask_b32_e64 v163, v198, v202, s[16:17]
	s_waitcnt lgkmcnt(15)
	v_add_f32_e32 v163, v217, v163
	v_cndmask_b32_e64 v198, v199, v203, s[18:19]
	v_cndmask_b32_e64 v200, v200, v204, s[6:7]
	v_exp_f32_e32 v163, v163
	v_add_f32_e32 v179, v179, v198
	s_waitcnt lgkmcnt(15)
	v_add_f32_e32 v200, v221, v200
	v_exp_f32_e32 v179, v179
	v_exp_f32_e32 v215, v200
	v_cndmask_b32_e64 v200, v201, v205, s[8:9]
	s_waitcnt lgkmcnt(15)
	v_add_f32_e32 v200, v222, v200
	v_exp_f32_e32 v217, v200
	v_cndmask_b32_e64 v198, v163, 0, s[16:17]
	v_cndmask_b32_e64 v202, 0, v163, s[16:17]
	v_pk_add_f32 v[162:163], v[162:163], 0 op_sel_hi:[1,0]
	v_cndmask_b32_e64 v199, v179, 0, s[18:19]
	v_pk_add_f32 v[162:163], v[178:179], v[162:163]
	v_cndmask_b32_e64 v200, 0, v179, s[18:19]
	v_pk_add_f32 v[162:163], v[214:215], v[162:163]
	v_cndmask_b32_e64 v201, v215, 0, s[6:7]
	v_pk_add_f32 v[162:163], v[216:217], v[162:163]
	v_cndmask_b32_e64 v203, 0, v215, s[6:7]
	v_pk_add_f32 v[130:131], v[130:131], v[162:163]
	v_cndmask_b32_e64 v204, v217, 0, s[8:9]
	v_cndmask_b32_e64 v205, 0, v217, s[8:9]
	v_cvt_pk_bf16_f32 v198, v198, v199
	v_cvt_pk_bf16_f32 v199, v201, v204
	v_cvt_pk_bf16_f32 v200, v202, v200
	v_cvt_pk_bf16_f32 v201, v203, v205
	s_setprio 1
	s_waitcnt lgkmcnt(14)
	v_mfma_f32_16x16x32_bf16 v[44:47], v[158:161], v[198:201], v[44:47]
	s_waitcnt lgkmcnt(12)
	v_mfma_f32_16x16x32_bf16 v[40:43], v[166:169], v[198:201], v[40:43]
	s_waitcnt lgkmcnt(10)
	v_mfma_f32_16x16x32_bf16 v[36:39], v[170:173], v[198:201], v[36:39]
	s_waitcnt lgkmcnt(8)
	v_mfma_f32_16x16x32_bf16 v[32:35], v[174:177], v[198:201], v[32:35]
	s_setprio 0
	ds_read_b64 v[158:159], v181 offset:1072
	ds_read_b64 v[160:161], v181 offset:1104
	ds_read_b64 v[166:167], v218 offset:1328
	ds_read_b64 v[168:169], v218 offset:1360
	ds_read_b64 v[170:171], v219 offset:1584
	ds_read_b64 v[172:173], v219 offset:1616
	ds_read_b64 v[174:175], v220 offset:1072
	ds_read_b64 v[176:177], v220 offset:1104
	ds_read_b128 v[198:201], v119 offset:23040
	ds_read_b128 v[202:205], v119 offset:23104
	v_add_u32_e32 v119, v148, v151
	ds_read_b128 v[206:209], v119 offset:18432
	ds_read_b128 v[210:213], v119 offset:18496
	v_add_u32_e32 v119, s60, v154
	v_add_u32_sdwa v162, s60, v145 dst_sel:DWORD dst_unused:UNUSED_PAD src0_sel:DWORD src1_sel:BYTE_1
	v_add_u32_sdwa v163, s60, v146 dst_sel:DWORD dst_unused:UNUSED_PAD src0_sel:DWORD src1_sel:BYTE_2
	v_add_u32_sdwa v178, s60, v146 dst_sel:DWORD dst_unused:UNUSED_PAD src0_sel:DWORD src1_sel:BYTE_3
	ds_read_b32 v119, v119 offset:41984
	ds_read_b32 v179, v162 offset:41984
	ds_read_b32 v214, v163 offset:41984
	ds_read_b32 v215, v178 offset:41984
	s_setprio 1
	s_waitcnt vmcnt(3) lgkmcnt(15)
	v_mfma_f32_16x16x32_bf16 v[182:185], v[182:185], v[96:99], 0
	s_waitcnt vmcnt(2)
	v_mfma_f32_16x16x32_bf16 v[182:185], v[186:189], v[100:103], v[182:185]
	v_mfma_f32_16x16x32_bf16 v[186:189], v[190:193], v[96:99], 0
	v_mfma_f32_16x16x32_bf16 v[186:189], v[194:197], v[100:103], v[186:189]
	s_setprio 0
	s_nop 6
	v_cndmask_b32_e64 v162, v186, v182, s[2:3]
	v_add_f32_e32 v136, v136, v162
	v_exp_f32_e32 v162, v136
	v_cndmask_b32_e64 v136, v187, v183, s[4:5]
	v_cndmask_b32_e64 v183, v184, v188, s[22:23]
	s_waitcnt lgkmcnt(15)
	v_add_f32_e32 v165, v165, v183
	v_exp_f32_e32 v190, v165
	v_cndmask_b32_e64 v165, v185, v189, s[24:25]
	v_add_f32_e32 v136, v223, v136
	s_waitcnt lgkmcnt(15)
	v_add_f32_e32 v165, v224, v165
	v_exp_f32_e32 v178, v136
	v_exp_f32_e32 v192, v165
	v_cndmask_b32_e64 v183, v190, 0, s[22:23]
	v_cndmask_b32_e64 v185, 0, v190, s[22:23]
	v_cndmask_b32_e64 v182, 0, v178, s[4:5]
	v_cndmask_b32_e64 v184, v192, 0, s[24:25]
	v_cndmask_b32_e64 v136, 0, v162, s[2:3]
	v_cndmask_b32_e64 v163, v162, 0, s[2:3]
	v_cndmask_b32_e64 v165, v178, 0, s[4:5]
	v_cndmask_b32_e64 v186, 0, v192, s[24:25]
	v_cvt_pk_bf16_f32 v182, v136, v182
	v_cvt_pk_bf16_f32 v183, v183, v184
	v_cvt_pk_bf16_f32 v184, v163, v165
	v_cvt_pk_bf16_f32 v185, v185, v186
	s_setprio 1
	s_waitcnt lgkmcnt(14)
	v_mfma_f32_16x16x32_bf16 v[28:31], v[158:161], v[182:185], v[28:31]
	s_waitcnt lgkmcnt(12)
	v_mfma_f32_16x16x32_bf16 v[24:27], v[166:169], v[182:185], v[24:27]
	s_waitcnt lgkmcnt(10)
	v_mfma_f32_16x16x32_bf16 v[20:23], v[170:173], v[182:185], v[20:23]
	s_waitcnt lgkmcnt(8)
	v_mfma_f32_16x16x32_bf16 v[16:19], v[174:177], v[182:185], v[16:19]
	s_setprio 0
	ds_read_b64 v[158:159], v220 offset:1088
	ds_read_b64 v[160:161], v220 offset:1120
	ds_read_b64 v[166:167], v219 offset:1600
	ds_read_b64 v[168:169], v219 offset:1632
	ds_read_b64 v[170:171], v218 offset:1344
	ds_read_b64 v[172:173], v218 offset:1376
	ds_read_b64 v[174:175], v181 offset:1088
	ds_read_b64 v[176:177], v181 offset:1120
	s_setprio 1
	s_waitcnt vmcnt(1) lgkmcnt(15)
	v_mfma_f32_16x16x32_bf16 v[182:185], v[198:201], v[104:107], 0
	s_waitcnt lgkmcnt(13)
	v_mfma_f32_16x16x32_bf16 v[186:189], v[206:209], v[104:107], 0
	s_waitcnt vmcnt(0)
	v_mfma_f32_16x16x32_bf16 v[182:185], v[202:205], v[108:111], v[182:185]
	s_waitcnt lgkmcnt(12)
	v_mfma_f32_16x16x32_bf16 v[186:189], v[210:213], v[108:111], v[186:189]
	s_setprio 0
	s_nop 6
	v_cndmask_b32_e64 v136, v182, v186, s[26:27]
	s_waitcnt lgkmcnt(11)
	v_add_f32_e32 v119, v119, v136
	v_exp_f32_e32 v163, v119
	v_cndmask_b32_e64 v119, v183, v187, s[28:29]
	v_cndmask_b32_e64 v181, v184, v188, s[30:31]
	s_waitcnt lgkmcnt(10)
	v_add_f32_e32 v119, v179, v119
	s_waitcnt lgkmcnt(9)
	v_add_f32_e32 v181, v214, v181
	v_exp_f32_e32 v179, v119
	v_exp_f32_e32 v191, v181
	v_cndmask_b32_e64 v181, v185, v189, s[34:35]
	s_waitcnt lgkmcnt(8)
	v_add_f32_e32 v181, v215, v181
	v_exp_f32_e32 v193, v181
	v_cndmask_b32_e64 v119, v163, 0, s[26:27]
	v_cndmask_b32_e64 v136, 0, v163, s[26:27]
	v_pk_add_f32 v[162:163], v[162:163], 0 op_sel_hi:[1,0]
	v_cndmask_b32_e64 v183, v191, 0, s[30:31]
	v_pk_add_f32 v[162:163], v[178:179], v[162:163]
	v_cndmask_b32_e64 v185, 0, v191, s[30:31]
	v_pk_add_f32 v[162:163], v[190:191], v[162:163]
	v_cndmask_b32_e64 v184, v193, 0, s[34:35]
	v_pk_add_f32 v[162:163], v[192:193], v[162:163]
	v_cndmask_b32_e64 v165, v179, 0, s[28:29]
	v_pk_add_f32 v[124:125], v[124:125], v[162:163]
	v_cndmask_b32_e64 v181, 0, v179, s[28:29]
	v_cndmask_b32_e64 v186, 0, v193, s[34:35]
	v_cvt_pk_bf16_f32 v182, v119, v165
	v_cvt_pk_bf16_f32 v183, v183, v184
	v_cvt_pk_bf16_f32 v184, v136, v181
	v_cvt_pk_bf16_f32 v185, v185, v186
	s_setprio 1
	s_waitcnt lgkmcnt(0)
	v_mfma_f32_16x16x32_bf16 v[12:15], v[174:177], v[182:185], v[12:15]
	v_mfma_f32_16x16x32_bf16 v[8:11], v[170:173], v[182:185], v[8:11]
	v_mfma_f32_16x16x32_bf16 v[4:7], v[166:169], v[182:185], v[4:7]
	v_mfma_f32_16x16x32_bf16 v[0:3], v[158:161], v[182:185], v[0:3]
	s_setprio 0
.LBB0_699:
	s_cmp_ge_u32 s52, s72
	s_cbranch_scc1 .LBB0_686
	s_waitcnt vmcnt(1)
	ds_write_b128 v225, v[64:67]
	s_waitcnt vmcnt(0)
	ds_write_b128 v157, v[68:71] offset:9216
	s_branch .LBB0_686
